# v23 + duplicate lgkmcnt(0) removed at MMA segment heads
# speedup vs baseline: 1.0220x; 1.0117x over previous
.LBB0_127:
	s_add_u32 s22, s20, 0xfff80080
	s_addc_u32 s23, s21, -1
	s_add_i32 s50, 0, 0x10000
	s_cmp_eq_u32 s49, 4
	s_cselect_b32 s23, s81, s23
	s_cselect_b32 s22, s80, s22
	s_cselect_b32 s39, s19, s48
	s_cselect_b32 s38, s31, s47
	v_lshl_add_u64 v[178:179], s[20:21], 0, v[138:139]
	s_add_i32 m0, s27, 0xc000
	ds_read_b128 v[162:165], v144
	ds_read_b128 v[166:169], v144 offset:1024
	ds_read_b128 v[170:173], v144 offset:2048
	ds_read_b128 v[174:177], v144 offset:3072
	ds_read_b128 v[192:195], v144 offset:4096
	ds_read_b128 v[196:199], v144 offset:5120
	ds_read_b128 v[200:203], v144 offset:6144
	ds_read_b128 v[204:207], v144 offset:7168
	global_load_lds_dwordx4 v[178:179], off
	v_lshl_add_u64 v[178:179], s[20:21], 0, v[140:141]
	s_add_i32 m0, s27, 0xe000
	s_nop 0
	global_load_lds_dwordx4 v[178:179], off
	s_waitcnt lgkmcnt(8)
	s_barrier
	s_waitcnt lgkmcnt(0)
	v_mfma_f32_16x16x32_bf16 v[126:129], v[146:149], v[162:165], v[126:129]
	v_mfma_f32_16x16x32_bf16 v[122:125], v[154:157], v[162:165], v[122:125]
	v_mfma_f32_16x16x32_bf16 v[118:121], v[146:149], v[170:173], v[118:121]
	v_mfma_f32_16x16x32_bf16 v[114:117], v[154:157], v[170:173], v[114:117]
	v_mfma_f32_16x16x32_bf16 v[102:105], v[146:149], v[192:195], v[102:105]
	v_mfma_f32_16x16x32_bf16 v[98:101], v[154:157], v[192:195], v[98:101]
	v_mfma_f32_16x16x32_bf16 v[86:89], v[146:149], v[200:203], v[86:89]
	v_mfma_f32_16x16x32_bf16 v[82:85], v[154:157], v[200:203], v[82:85]
	v_mfma_f32_16x16x32_bf16 v[126:129], v[150:153], v[166:169], v[126:129]
	v_mfma_f32_16x16x32_bf16 v[122:125], v[158:161], v[166:169], v[122:125]
	v_mfma_f32_16x16x32_bf16 v[118:121], v[150:153], v[174:177], v[118:121]
	v_mfma_f32_16x16x32_bf16 v[114:117], v[158:161], v[174:177], v[114:117]
	v_mfma_f32_16x16x32_bf16 v[102:105], v[150:153], v[196:199], v[102:105]
	v_mfma_f32_16x16x32_bf16 v[98:101], v[158:161], v[196:199], v[98:101]
	v_mfma_f32_16x16x32_bf16 v[86:89], v[150:153], v[204:207], v[86:89]
	v_mfma_f32_16x16x32_bf16 v[82:85], v[158:161], v[204:207], v[82:85]
	s_barrier
	s_add_i32 s52, 0, 0x14000
	s_add_i32 s50, s50, s26
	v_add_u32_e32 v145, s52, v142
	v_lshl_add_u64 v[178:179], s[38:39], 0, v[134:135]
	s_mov_b32 m0, s50
	ds_read_b128 v[208:211], v145
	ds_read_b128 v[224:227], v145 offset:1024
	ds_read_b128 v[228:231], v145 offset:2048
	ds_read_b128 v[232:235], v145 offset:3072
	global_load_lds_dwordx4 v[178:179], off
	v_lshl_add_u64 v[212:213], s[38:39], 0, v[130:131]
	s_add_i32 m0, s50, 0x2000
	s_nop 0
	global_load_lds_dwordx4 v[212:213], off
	s_barrier
	s_waitcnt lgkmcnt(0)
	v_mfma_f32_16x16x32_bf16 v[110:113], v[208:211], v[162:165], v[110:113]
	v_mfma_f32_16x16x32_bf16 v[106:109], v[228:231], v[162:165], v[106:109]
	v_mfma_f32_16x16x32_bf16 v[94:97], v[208:211], v[170:173], v[94:97]
	v_mfma_f32_16x16x32_bf16 v[90:93], v[228:231], v[170:173], v[90:93]
	v_mfma_f32_16x16x32_bf16 v[78:81], v[208:211], v[192:195], v[78:81]
	v_mfma_f32_16x16x32_bf16 v[74:77], v[228:231], v[192:195], v[74:77]
	v_mfma_f32_16x16x32_bf16 v[70:73], v[208:211], v[200:203], v[70:73]
	v_mfma_f32_16x16x32_bf16 v[66:69], v[228:231], v[200:203], v[66:69]
	v_mfma_f32_16x16x32_bf16 v[110:113], v[224:227], v[166:169], v[110:113]
	v_mfma_f32_16x16x32_bf16 v[106:109], v[232:235], v[166:169], v[106:109]
	v_mfma_f32_16x16x32_bf16 v[94:97], v[224:227], v[174:177], v[94:97]
	v_mfma_f32_16x16x32_bf16 v[90:93], v[232:235], v[174:177], v[90:93]
	v_mfma_f32_16x16x32_bf16 v[78:81], v[224:227], v[196:199], v[78:81]
	v_mfma_f32_16x16x32_bf16 v[74:77], v[232:235], v[196:199], v[74:77]
	v_mfma_f32_16x16x32_bf16 v[70:73], v[224:227], v[204:207], v[70:73]
	v_mfma_f32_16x16x32_bf16 v[66:69], v[232:235], v[204:207], v[66:69]
	s_mov_b32 m0, s27
	v_lshl_add_u64 v[236:237], s[22:23], 0, v[136:137]
	s_barrier
	ds_read_b128 v[162:165], v144 offset:16384
	ds_read_b128 v[166:169], v144 offset:17408
	ds_read_b128 v[170:173], v144 offset:18432
	ds_read_b128 v[174:177], v144 offset:19456
	ds_read_b128 v[192:195], v144 offset:20480
	ds_read_b128 v[196:199], v144 offset:21504
	ds_read_b128 v[200:203], v144 offset:22528
	ds_read_b128 v[204:207], v144 offset:23552
	global_load_lds_dwordx4 v[236:237], off
	v_lshl_add_u64 v[238:239], s[22:23], 0, v[132:133]
	s_mov_b32 m0, s28
	s_nop 0
	global_load_lds_dwordx4 v[238:239], off
	s_waitcnt vmcnt(10)
	s_barrier
	s_waitcnt lgkmcnt(0)
	v_mfma_f32_16x16x32_bf16 v[62:65], v[146:149], v[162:165], v[62:65]
	v_mfma_f32_16x16x32_bf16 v[58:61], v[154:157], v[162:165], v[58:61]
	v_mfma_f32_16x16x32_bf16 v[54:57], v[146:149], v[170:173], v[54:57]
	v_mfma_f32_16x16x32_bf16 v[50:53], v[154:157], v[170:173], v[50:53]
	v_mfma_f32_16x16x32_bf16 v[38:41], v[146:149], v[192:195], v[38:41]
	v_mfma_f32_16x16x32_bf16 v[34:37], v[154:157], v[192:195], v[34:37]
	v_mfma_f32_16x16x32_bf16 v[22:25], v[146:149], v[200:203], v[22:25]
	v_mfma_f32_16x16x32_bf16 v[18:21], v[154:157], v[200:203], v[18:21]
	v_mfma_f32_16x16x32_bf16 v[62:65], v[150:153], v[166:169], v[62:65]
	v_mfma_f32_16x16x32_bf16 v[58:61], v[158:161], v[166:169], v[58:61]
	v_mfma_f32_16x16x32_bf16 v[54:57], v[150:153], v[174:177], v[54:57]
	v_mfma_f32_16x16x32_bf16 v[50:53], v[158:161], v[174:177], v[50:53]
	v_mfma_f32_16x16x32_bf16 v[38:41], v[150:153], v[196:199], v[38:41]
	v_mfma_f32_16x16x32_bf16 v[34:37], v[158:161], v[196:199], v[34:37]
	v_mfma_f32_16x16x32_bf16 v[22:25], v[150:153], v[204:207], v[22:25]
	v_mfma_f32_16x16x32_bf16 v[18:21], v[158:161], v[204:207], v[18:21]
	s_barrier
	s_add_u32 s50, s38, 0x20000
	s_addc_u32 s51, s39, 0
	s_add_i32 s52, s52, s26
	v_lshl_add_u64 v[146:147], s[50:51], 0, v[134:135]
	s_mov_b32 m0, s52
	s_nop 0
	global_load_lds_dwordx4 v[146:147], off
	v_lshl_add_u64 v[146:147], s[50:51], 0, v[130:131]
	s_add_i32 m0, s52, 0x2000
	s_nop 0
	global_load_lds_dwordx4 v[146:147], off
	v_add_u32_e32 v145, 0x18000, v142
	ds_read_b128 v[146:149], v145
	ds_read_b128 v[150:153], v145 offset:1024
	ds_read_b128 v[154:157], v145 offset:2048
	ds_read_b128 v[158:161], v145 offset:3072
	s_waitcnt vmcnt(6)
	s_barrier
	v_mfma_f32_16x16x32_bf16 v[46:49], v[208:211], v[162:165], v[46:49]
	v_mfma_f32_16x16x32_bf16 v[42:45], v[228:231], v[162:165], v[42:45]
	v_mfma_f32_16x16x32_bf16 v[30:33], v[208:211], v[170:173], v[30:33]
	v_mfma_f32_16x16x32_bf16 v[26:29], v[228:231], v[170:173], v[26:29]
	v_mfma_f32_16x16x32_bf16 v[14:17], v[208:211], v[192:195], v[14:17]
	v_mfma_f32_16x16x32_bf16 v[10:13], v[228:231], v[192:195], v[10:13]
	v_mfma_f32_16x16x32_bf16 v[6:9], v[208:211], v[200:203], v[6:9]
	v_mfma_f32_16x16x32_bf16 v[2:5], v[228:231], v[200:203], v[2:5]
	v_mfma_f32_16x16x32_bf16 v[46:49], v[224:227], v[166:169], v[46:49]
	v_mfma_f32_16x16x32_bf16 v[42:45], v[232:235], v[166:169], v[42:45]
	v_mfma_f32_16x16x32_bf16 v[30:33], v[224:227], v[174:177], v[30:33]
	v_mfma_f32_16x16x32_bf16 v[26:29], v[232:235], v[174:177], v[26:29]
	v_mfma_f32_16x16x32_bf16 v[14:17], v[224:227], v[196:199], v[14:17]
	v_mfma_f32_16x16x32_bf16 v[10:13], v[232:235], v[196:199], v[10:13]
	v_mfma_f32_16x16x32_bf16 v[6:9], v[224:227], v[204:207], v[6:9]
	v_mfma_f32_16x16x32_bf16 v[2:5], v[232:235], v[204:207], v[2:5]
	s_add_i32 s50, 0, 0x18000
	s_barrier
	s_add_u32 s22, s22, 0x80000
	s_addc_u32 s23, s23, 0
	s_mov_b32 m0, s29
	v_lshl_add_u64 v[208:209], s[22:23], 0, v[136:137]
	ds_read_b128 v[162:165], v144 offset:32768
	ds_read_b128 v[166:169], v144 offset:33792
	ds_read_b128 v[170:173], v144 offset:34816
	ds_read_b128 v[174:177], v144 offset:35840
	ds_read_b128 v[192:195], v144 offset:36864
	ds_read_b128 v[196:199], v144 offset:37888
	ds_read_b128 v[200:203], v144 offset:38912
	ds_read_b128 v[204:207], v144 offset:39936
	global_load_lds_dwordx4 v[208:209], off
	v_lshl_add_u64 v[208:209], s[22:23], 0, v[132:133]
	s_mov_b32 m0, s36
	s_nop 0
	global_load_lds_dwordx4 v[208:209], off
	s_waitcnt lgkmcnt(8)
	s_barrier
	s_waitcnt lgkmcnt(0)
	v_mfma_f32_16x16x32_bf16 v[126:129], v[146:149], v[162:165], v[126:129]
	v_mfma_f32_16x16x32_bf16 v[122:125], v[154:157], v[162:165], v[122:125]
	v_mfma_f32_16x16x32_bf16 v[118:121], v[146:149], v[170:173], v[118:121]
	v_mfma_f32_16x16x32_bf16 v[114:117], v[154:157], v[170:173], v[114:117]
	v_mfma_f32_16x16x32_bf16 v[102:105], v[146:149], v[192:195], v[102:105]
	v_mfma_f32_16x16x32_bf16 v[98:101], v[154:157], v[192:195], v[98:101]
	v_mfma_f32_16x16x32_bf16 v[86:89], v[146:149], v[200:203], v[86:89]
	v_mfma_f32_16x16x32_bf16 v[82:85], v[154:157], v[200:203], v[82:85]
	v_mfma_f32_16x16x32_bf16 v[126:129], v[150:153], v[166:169], v[126:129]
	v_mfma_f32_16x16x32_bf16 v[122:125], v[158:161], v[166:169], v[122:125]
	v_mfma_f32_16x16x32_bf16 v[118:121], v[150:153], v[174:177], v[118:121]
	v_mfma_f32_16x16x32_bf16 v[114:117], v[158:161], v[174:177], v[114:117]
	v_mfma_f32_16x16x32_bf16 v[102:105], v[150:153], v[196:199], v[102:105]
	v_mfma_f32_16x16x32_bf16 v[98:101], v[158:161], v[196:199], v[98:101]
	v_mfma_f32_16x16x32_bf16 v[86:89], v[150:153], v[204:207], v[86:89]
	v_mfma_f32_16x16x32_bf16 v[82:85], v[158:161], v[204:207], v[82:85]
	s_barrier
	s_add_i32 s51, 0, 0x1c000
	s_add_i32 s22, s50, s26
	v_add_u32_e32 v145, s51, v142
	v_lshl_add_u64 v[178:179], v[178:179], 0, s[78:79]
	s_mov_b32 m0, s22
	ds_read_b128 v[208:211], v145
	ds_read_b128 v[224:227], v145 offset:1024
	ds_read_b128 v[228:231], v145 offset:2048
	ds_read_b128 v[232:235], v145 offset:3072
	global_load_lds_dwordx4 v[178:179], off
	v_lshl_add_u64 v[178:179], v[212:213], 0, s[78:79]
	s_add_i32 m0, s22, 0x2000
	s_nop 0
	global_load_lds_dwordx4 v[178:179], off
	s_barrier
	s_waitcnt lgkmcnt(0)
	v_mfma_f32_16x16x32_bf16 v[110:113], v[208:211], v[162:165], v[110:113]
	v_mfma_f32_16x16x32_bf16 v[106:109], v[228:231], v[162:165], v[106:109]
	v_mfma_f32_16x16x32_bf16 v[94:97], v[208:211], v[170:173], v[94:97]
	v_mfma_f32_16x16x32_bf16 v[90:93], v[228:231], v[170:173], v[90:93]
	v_mfma_f32_16x16x32_bf16 v[78:81], v[208:211], v[192:195], v[78:81]
	v_mfma_f32_16x16x32_bf16 v[74:77], v[228:231], v[192:195], v[74:77]
	v_mfma_f32_16x16x32_bf16 v[70:73], v[208:211], v[200:203], v[70:73]
	v_mfma_f32_16x16x32_bf16 v[66:69], v[228:231], v[200:203], v[66:69]
	v_mfma_f32_16x16x32_bf16 v[110:113], v[224:227], v[166:169], v[110:113]
	v_mfma_f32_16x16x32_bf16 v[106:109], v[232:235], v[166:169], v[106:109]
	v_mfma_f32_16x16x32_bf16 v[94:97], v[224:227], v[174:177], v[94:97]
	v_mfma_f32_16x16x32_bf16 v[90:93], v[232:235], v[174:177], v[90:93]
	v_mfma_f32_16x16x32_bf16 v[78:81], v[224:227], v[196:199], v[78:81]
	v_mfma_f32_16x16x32_bf16 v[74:77], v[232:235], v[196:199], v[74:77]
	v_mfma_f32_16x16x32_bf16 v[70:73], v[224:227], v[204:207], v[70:73]
	v_mfma_f32_16x16x32_bf16 v[66:69], v[232:235], v[204:207], v[66:69]
	s_mov_b32 m0, s42
	v_lshl_add_u64 v[178:179], v[236:237], 0, s[78:79]
	s_barrier
	ds_read_b128 v[162:165], v144 offset:49152
	ds_read_b128 v[166:169], v144 offset:50176
	ds_read_b128 v[170:173], v144 offset:51200
	ds_read_b128 v[174:177], v144 offset:52224
	ds_read_b128 v[192:195], v144 offset:53248
	ds_read_b128 v[196:199], v144 offset:54272
	ds_read_b128 v[200:203], v144 offset:55296
	ds_read_b128 v[204:207], v144 offset:56320
	global_load_lds_dwordx4 v[178:179], off
	v_lshl_add_u64 v[178:179], v[238:239], 0, s[78:79]
	s_mov_b32 m0, s43
	s_nop 0
	global_load_lds_dwordx4 v[178:179], off
	s_waitcnt vmcnt(10)
	s_barrier
	s_waitcnt lgkmcnt(0)
	v_mfma_f32_16x16x32_bf16 v[62:65], v[146:149], v[162:165], v[62:65]
	v_mfma_f32_16x16x32_bf16 v[58:61], v[154:157], v[162:165], v[58:61]
	v_mfma_f32_16x16x32_bf16 v[54:57], v[146:149], v[170:173], v[54:57]
	v_mfma_f32_16x16x32_bf16 v[50:53], v[154:157], v[170:173], v[50:53]
	v_mfma_f32_16x16x32_bf16 v[38:41], v[146:149], v[192:195], v[38:41]
	v_mfma_f32_16x16x32_bf16 v[34:37], v[154:157], v[192:195], v[34:37]
	v_mfma_f32_16x16x32_bf16 v[22:25], v[146:149], v[200:203], v[22:25]
	v_mfma_f32_16x16x32_bf16 v[18:21], v[154:157], v[200:203], v[18:21]
	v_mfma_f32_16x16x32_bf16 v[62:65], v[150:153], v[166:169], v[62:65]
	v_mfma_f32_16x16x32_bf16 v[58:61], v[158:161], v[166:169], v[58:61]
	v_mfma_f32_16x16x32_bf16 v[54:57], v[150:153], v[174:177], v[54:57]
	v_mfma_f32_16x16x32_bf16 v[50:53], v[158:161], v[174:177], v[50:53]
	v_mfma_f32_16x16x32_bf16 v[38:41], v[150:153], v[196:199], v[38:41]
	v_mfma_f32_16x16x32_bf16 v[34:37], v[158:161], v[196:199], v[34:37]
	v_mfma_f32_16x16x32_bf16 v[22:25], v[150:153], v[204:207], v[22:25]
	v_mfma_f32_16x16x32_bf16 v[18:21], v[158:161], v[204:207], v[18:21]
	s_barrier
	s_add_u32 s22, s38, 0x20080
	s_addc_u32 s23, s39, 0
	s_add_i32 s38, s51, s26
	v_lshl_add_u64 v[146:147], s[22:23], 0, v[134:135]
	s_mov_b32 m0, s38
	s_nop 0
	global_load_lds_dwordx4 v[146:147], off
	v_lshl_add_u64 v[146:147], s[22:23], 0, v[130:131]
	s_add_i32 m0, s38, 0x2000
	s_nop 0
	global_load_lds_dwordx4 v[146:147], off
	v_add_u32_e32 v145, 0x10000, v142
	ds_read_b128 v[146:149], v145
	ds_read_b128 v[150:153], v145 offset:1024
	ds_read_b128 v[154:157], v145 offset:2048
	ds_read_b128 v[158:161], v145 offset:3072
	s_waitcnt vmcnt(6)
	s_barrier
	v_mfma_f32_16x16x32_bf16 v[46:49], v[208:211], v[162:165], v[46:49]
	v_mfma_f32_16x16x32_bf16 v[42:45], v[228:231], v[162:165], v[42:45]
	v_mfma_f32_16x16x32_bf16 v[30:33], v[208:211], v[170:173], v[30:33]
	v_mfma_f32_16x16x32_bf16 v[26:29], v[228:231], v[170:173], v[26:29]
	v_mfma_f32_16x16x32_bf16 v[14:17], v[208:211], v[192:195], v[14:17]
	v_mfma_f32_16x16x32_bf16 v[10:13], v[228:231], v[192:195], v[10:13]
	v_mfma_f32_16x16x32_bf16 v[6:9], v[208:211], v[200:203], v[6:9]
	v_mfma_f32_16x16x32_bf16 v[2:5], v[228:231], v[200:203], v[2:5]
	v_mfma_f32_16x16x32_bf16 v[46:49], v[224:227], v[166:169], v[46:49]
	v_mfma_f32_16x16x32_bf16 v[42:45], v[232:235], v[166:169], v[42:45]
	v_mfma_f32_16x16x32_bf16 v[30:33], v[224:227], v[174:177], v[30:33]
	v_mfma_f32_16x16x32_bf16 v[26:29], v[232:235], v[174:177], v[26:29]
	v_mfma_f32_16x16x32_bf16 v[14:17], v[224:227], v[196:199], v[14:17]
	v_mfma_f32_16x16x32_bf16 v[10:13], v[232:235], v[196:199], v[10:13]
	v_mfma_f32_16x16x32_bf16 v[6:9], v[224:227], v[204:207], v[6:9]
	v_mfma_f32_16x16x32_bf16 v[2:5], v[232:235], v[204:207], v[2:5]
	s_add_i32 s49, s49, 2
	s_add_u32 s20, s20, 0x100
	s_addc_u32 s21, s21, 0
	s_add_u32 s47, s47, 0x100
	s_addc_u32 s48, s48, 0
	s_cmp_gt_u32 s49, 5
	s_barrier
	s_cbranch_scc0 .LBB0_127
	s_waitcnt lgkmcnt(0)
	v_lshl_add_u32 v146, s46, 8, v1
	v_lshl_or_b32 v148, s45, 8, v143
	v_ashrrev_i32_e32 v147, 31, v146
	v_readlane_b32 s48, v254, 40
	v_ashrrev_i32_e32 v149, 31, v148
	v_lshlrev_b64 v[150:151], 12, v[146:147]
	v_readlane_b32 s52, v254, 44
	v_readlane_b32 s53, v254, 45
	v_lshlrev_b64 v[148:149], 1, v[148:149]
	s_mov_b32 s19, 0x80000
	v_lshl_add_u64 v[150:151], s[52:53], 0, v[150:151]
	v_lshl_add_u64 v[150:151], v[150:151], 0, v[148:149]
	s_mov_b64 s[20:21], 0x80000
	v_cvt_pk_bf16_f32 v62, v62, v63
	v_cvt_pk_bf16_f32 v63, v64, v65
	v_cvt_pk_bf16_f32 v64, v58, v59
	v_add_co_u32_e32 v58, vcc, s19, v150
	v_cvt_pk_bf16_f32 v70, v70, v71
	v_cvt_pk_bf16_f32 v71, v72, v73
	v_cvt_pk_bf16_f32 v72, v66, v67
	v_lshl_add_u64 v[66:67], v[150:151], 0, s[20:21]
	v_addc_co_u32_e32 v59, vcc, 0, v151, vcc
	v_cvt_pk_bf16_f32 v46, v46, v47
	v_cvt_pk_bf16_f32 v47, v48, v49
	v_cvt_pk_bf16_f32 v48, v42, v43
	v_cvt_pk_bf16_f32 v49, v44, v45
	s_mov_b32 s19, 0x90000
	v_cvt_pk_bf16_f32 v110, v110, v111
	v_cvt_pk_bf16_f32 v111, v112, v113
	v_cvt_pk_bf16_f32 v112, v106, v107
	v_or_b32_e32 v106, 16, v146
	global_store_dwordx4 v[66:67], v[46:49], off offset:256
	s_mov_b64 s[20:21], 0x90000
	v_ashrrev_i32_e32 v107, 31, v106
	v_add_co_u32_e32 v48, vcc, s19, v150
	v_cvt_pk_bf16_f32 v94, v94, v95
	v_cvt_pk_bf16_f32 v95, v96, v97
	v_cvt_pk_bf16_f32 v96, v90, v91
	v_or_b32_e32 v90, 32, v146
	v_lshl_add_u64 v[46:47], v[150:151], 0, s[20:21]
	v_addc_co_u32_e32 v49, vcc, 0, v151, vcc
	v_cvt_pk_bf16_f32 v30, v30, v31
	v_cvt_pk_bf16_f32 v31, v32, v33
	v_cvt_pk_bf16_f32 v32, v26, v27
	v_cvt_pk_bf16_f32 v33, v28, v29
	s_mov_b32 s19, 0xa0000
	v_lshlrev_b64 v[106:107], 12, v[106:107]
	v_ashrrev_i32_e32 v91, 31, v90
	v_cvt_pk_bf16_f32 v78, v78, v79
	v_cvt_pk_bf16_f32 v79, v80, v81
	v_cvt_pk_bf16_f32 v80, v74, v75
	v_or_b32_e32 v74, 48, v146
	global_store_dwordx4 v[46:47], v[30:33], off offset:256
	s_mov_b64 s[20:21], 0xa0000
	v_cvt_pk_bf16_f32 v113, v108, v109
	v_add_co_u32_e32 v32, vcc, s19, v150
	v_lshl_add_u64 v[106:107], s[52:53], 0, v[106:107]
	v_lshlrev_b64 v[90:91], 12, v[90:91]
	v_ashrrev_i32_e32 v75, 31, v74
	v_lshl_add_u64 v[30:31], v[150:151], 0, s[20:21]
	v_addc_co_u32_e32 v33, vcc, 0, v151, vcc
	v_cvt_pk_bf16_f32 v14, v14, v15
	v_cvt_pk_bf16_f32 v15, v16, v17
	v_cvt_pk_bf16_f32 v16, v10, v11
	v_cvt_pk_bf16_f32 v17, v12, v13
	s_mov_b32 s19, 0xb0000
	global_store_dwordx4 v[150:151], v[110:113], off offset:256
	v_cvt_pk_bf16_f32 v97, v92, v93
	v_lshl_add_u64 v[90:91], s[52:53], 0, v[90:91]
	v_lshl_add_u64 v[110:111], v[106:107], 0, v[148:149]
	v_lshlrev_b64 v[74:75], 12, v[74:75]
	global_store_dwordx4 v[30:31], v[14:17], off offset:256
	global_store_dwordx4 v[110:111], v[94:97], off offset:256
	v_cvt_pk_bf16_f32 v81, v76, v77
	v_add_co_u32_e32 v16, vcc, s19, v150
	v_lshl_add_u64 v[94:95], v[90:91], 0, v[148:149]
	v_lshl_add_u64 v[74:75], s[52:53], 0, v[74:75]
	s_mov_b64 s[20:21], 0xb0000
	v_addc_co_u32_e32 v17, vcc, 0, v151, vcc
	v_cvt_pk_bf16_f32 v126, v126, v127
	v_cvt_pk_bf16_f32 v127, v128, v129
	v_cvt_pk_bf16_f32 v128, v122, v123
	v_cvt_pk_bf16_f32 v129, v124, v125
	v_cvt_pk_bf16_f32 v106, v118, v119
	v_cvt_pk_bf16_f32 v107, v120, v121
	v_cvt_pk_bf16_f32 v108, v114, v115
	v_cvt_pk_bf16_f32 v109, v116, v117
	v_cvt_pk_bf16_f32 v90, v102, v103
	v_cvt_pk_bf16_f32 v91, v104, v105
	v_cvt_pk_bf16_f32 v92, v98, v99
	v_cvt_pk_bf16_f32 v93, v100, v101
	global_store_dwordx4 v[94:95], v[78:81], off offset:256
	v_cvt_pk_bf16_f32 v76, v82, v83
	v_cvt_pk_bf16_f32 v77, v84, v85
	v_lshl_add_u64 v[78:79], v[74:75], 0, v[148:149]
	v_cvt_pk_bf16_f32 v74, v86, v87
	v_cvt_pk_bf16_f32 v75, v88, v89
	v_cvt_pk_bf16_f32 v73, v68, v69
	v_cvt_pk_bf16_f32 v65, v60, v61
	v_cvt_pk_bf16_f32 v42, v54, v55
	v_cvt_pk_bf16_f32 v43, v56, v57
	v_cvt_pk_bf16_f32 v44, v50, v51
	v_cvt_pk_bf16_f32 v45, v52, v53
	v_cvt_pk_bf16_f32 v26, v38, v39
	v_cvt_pk_bf16_f32 v27, v40, v41
	v_cvt_pk_bf16_f32 v28, v34, v35
	v_cvt_pk_bf16_f32 v29, v36, v37
	v_lshl_add_u64 v[14:15], v[150:151], 0, s[20:21]
	v_cvt_pk_bf16_f32 v10, v22, v23
	v_cvt_pk_bf16_f32 v11, v24, v25
	v_cvt_pk_bf16_f32 v12, v18, v19
	v_cvt_pk_bf16_f32 v13, v20, v21
	v_cvt_pk_bf16_f32 v6, v6, v7
	v_cvt_pk_bf16_f32 v7, v8, v9
	v_cvt_pk_bf16_f32 v8, v2, v3
	v_cvt_pk_bf16_f32 v9, v4, v5
	s_and_b64 vcc, exec, s[0:1]
	s_mov_b32 s45, s18
	s_mov_b32 s46, s30
	s_mov_b64 s[22:23], s[82:83]
	s_mov_b64 s[20:21], s[80:81]
	s_mov_b32 s64, 0x800000
	s_movk_i32 s65, 0x1fff
	v_readlane_b32 s49, v254, 41
	v_readlane_b32 s50, v254, 42
	v_readlane_b32 s51, v254, 43
	v_readlane_b32 s54, v254, 46
	v_readlane_b32 s55, v254, 47
	v_readlane_b32 s56, v254, 48
	v_readlane_b32 s57, v254, 49
	v_readlane_b32 s58, v254, 50
	v_readlane_b32 s59, v254, 51
	v_readlane_b32 s60, v254, 52
	v_readlane_b32 s61, v254, 53
	v_readlane_b32 s62, v254, 54
	v_readlane_b32 s63, v254, 55
	global_store_dwordx4 v[150:151], v[126:129], off
	global_store_dwordx4 v[110:111], v[106:109], off
	global_store_dwordx4 v[94:95], v[90:93], off
	global_store_dwordx4 v[78:79], v[74:77], off
	global_store_dwordx4 v[78:79], v[70:73], off offset:256
	global_store_dwordx4 v[58:59], v[62:65], off
	global_store_dwordx4 v[48:49], v[42:45], off
	global_store_dwordx4 v[32:33], v[26:29], off
	global_store_dwordx4 v[16:17], v[10:13], off
	global_store_dwordx4 v[14:15], v[6:9], off offset:256
	s_cbranch_vccz .LBB0_118
	s_waitcnt vmcnt(0)
	v_readlane_b32 s44, v255, 30
	s_mov_b32 s66, s90
	s_cmpk_gt_u32 s25, 0xff
	v_readlane_b32 s45, v255, 31
	v_readlane_b32 s42, v255, 32
	s_cbranch_scc1 .LBB0_131
	s_barrier

.LBB0_240:
	s_add_u32 s22, s80, 0xfff80080
	s_addc_u32 s23, s81, -1
	s_add_i32 s52, 0, 0x10000
	s_cmp_eq_u32 s51, 28
	s_cselect_b32 s23, s21, s23
	s_cselect_b32 s22, s47, s22
	s_cselect_b32 s83, s19, s50
	s_cselect_b32 s82, s48, s49
	v_lshl_add_u64 v[178:179], s[80:81], 0, v[134:135]
	s_add_i32 m0, s27, 0xc000
	ds_read_b128 v[158:161], v140
	ds_read_b128 v[162:165], v140 offset:1024
	ds_read_b128 v[166:169], v140 offset:2048
	ds_read_b128 v[170:173], v140 offset:3072
	ds_read_b128 v[174:177], v140 offset:4096
	ds_read_b128 v[192:195], v140 offset:5120
	ds_read_b128 v[196:199], v140 offset:6144
	ds_read_b128 v[200:203], v140 offset:7168
	global_load_lds_dwordx4 v[178:179], off
	v_lshl_add_u64 v[178:179], s[80:81], 0, v[136:137]
	s_add_i32 m0, s27, 0xe000
	s_nop 0
	global_load_lds_dwordx4 v[178:179], off
	s_waitcnt lgkmcnt(8)
	s_barrier
	s_waitcnt lgkmcnt(0)
	v_mfma_f32_16x16x32_bf16 v[126:129], v[142:145], v[158:161], v[126:129]
	v_mfma_f32_16x16x32_bf16 v[122:125], v[150:153], v[158:161], v[122:125]
	v_mfma_f32_16x16x32_bf16 v[118:121], v[142:145], v[166:169], v[118:121]
	v_mfma_f32_16x16x32_bf16 v[114:117], v[150:153], v[166:169], v[114:117]
	v_mfma_f32_16x16x32_bf16 v[110:113], v[142:145], v[174:177], v[110:113]
	v_mfma_f32_16x16x32_bf16 v[102:105], v[150:153], v[174:177], v[102:105]
	v_mfma_f32_16x16x32_bf16 v[94:97], v[142:145], v[196:199], v[94:97]
	v_mfma_f32_16x16x32_bf16 v[86:89], v[150:153], v[196:199], v[86:89]
	v_mfma_f32_16x16x32_bf16 v[126:129], v[146:149], v[162:165], v[126:129]
	v_mfma_f32_16x16x32_bf16 v[122:125], v[154:157], v[162:165], v[122:125]
	v_mfma_f32_16x16x32_bf16 v[118:121], v[146:149], v[170:173], v[118:121]
	v_mfma_f32_16x16x32_bf16 v[114:117], v[154:157], v[170:173], v[114:117]
	v_mfma_f32_16x16x32_bf16 v[110:113], v[146:149], v[192:195], v[110:113]
	v_mfma_f32_16x16x32_bf16 v[102:105], v[154:157], v[192:195], v[102:105]
	v_mfma_f32_16x16x32_bf16 v[94:97], v[146:149], v[200:203], v[94:97]
	v_mfma_f32_16x16x32_bf16 v[86:89], v[154:157], v[200:203], v[86:89]
	s_barrier
	s_add_i32 s54, 0, 0x14000
	s_add_i32 s52, s52, s26
	v_add_u32_e32 v141, s54, v138
	v_lshl_add_u64 v[178:179], s[82:83], 0, v[132:133]
	s_mov_b32 m0, s52
	ds_read_b128 v[204:207], v141
	ds_read_b128 v[208:211], v141 offset:1024
	ds_read_b128 v[224:227], v141 offset:2048
	ds_read_b128 v[228:231], v141 offset:3072
	global_load_lds_dwordx4 v[178:179], off
	v_lshl_add_u64 v[212:213], s[82:83], 0, v[130:131]
	s_add_i32 m0, s52, 0x2000
	s_nop 0
	global_load_lds_dwordx4 v[212:213], off
	s_barrier
	s_waitcnt lgkmcnt(0)
	v_mfma_f32_16x16x32_bf16 v[106:109], v[204:207], v[158:161], v[106:109]
	v_mfma_f32_16x16x32_bf16 v[98:101], v[224:227], v[158:161], v[98:101]
	v_mfma_f32_16x16x32_bf16 v[90:93], v[204:207], v[166:169], v[90:93]
	v_mfma_f32_16x16x32_bf16 v[82:85], v[224:227], v[166:169], v[82:85]
	v_mfma_f32_16x16x32_bf16 v[78:81], v[204:207], v[174:177], v[78:81]
	v_mfma_f32_16x16x32_bf16 v[74:77], v[224:227], v[174:177], v[74:77]
	v_mfma_f32_16x16x32_bf16 v[70:73], v[204:207], v[196:199], v[70:73]
	v_mfma_f32_16x16x32_bf16 v[66:69], v[224:227], v[196:199], v[66:69]
	v_mfma_f32_16x16x32_bf16 v[106:109], v[208:211], v[162:165], v[106:109]
	v_mfma_f32_16x16x32_bf16 v[98:101], v[228:231], v[162:165], v[98:101]
	v_mfma_f32_16x16x32_bf16 v[90:93], v[208:211], v[170:173], v[90:93]
	v_mfma_f32_16x16x32_bf16 v[82:85], v[228:231], v[170:173], v[82:85]
	v_mfma_f32_16x16x32_bf16 v[78:81], v[208:211], v[192:195], v[78:81]
	v_mfma_f32_16x16x32_bf16 v[74:77], v[228:231], v[192:195], v[74:77]
	v_mfma_f32_16x16x32_bf16 v[70:73], v[208:211], v[200:203], v[70:73]
	v_mfma_f32_16x16x32_bf16 v[66:69], v[228:231], v[200:203], v[66:69]
	s_mov_b32 m0, s27
	v_lshl_add_u64 v[232:233], s[22:23], 0, v[132:133]
	s_barrier
	ds_read_b128 v[158:161], v140 offset:16384
	ds_read_b128 v[162:165], v140 offset:17408
	ds_read_b128 v[166:169], v140 offset:18432
	ds_read_b128 v[170:173], v140 offset:19456
	ds_read_b128 v[174:177], v140 offset:20480
	ds_read_b128 v[192:195], v140 offset:21504
	ds_read_b128 v[196:199], v140 offset:22528
	ds_read_b128 v[200:203], v140 offset:23552
	global_load_lds_dwordx4 v[232:233], off
	v_lshl_add_u64 v[234:235], s[22:23], 0, v[130:131]
	s_mov_b32 m0, s28
	s_nop 0
	global_load_lds_dwordx4 v[234:235], off
	s_waitcnt vmcnt(10)
	s_barrier
	s_waitcnt lgkmcnt(0)
	v_mfma_f32_16x16x32_bf16 v[62:65], v[142:145], v[158:161], v[62:65]
	v_mfma_f32_16x16x32_bf16 v[58:61], v[150:153], v[158:161], v[58:61]
	v_mfma_f32_16x16x32_bf16 v[54:57], v[142:145], v[166:169], v[54:57]
	v_mfma_f32_16x16x32_bf16 v[50:53], v[150:153], v[166:169], v[50:53]
	v_mfma_f32_16x16x32_bf16 v[46:49], v[142:145], v[174:177], v[46:49]
	v_mfma_f32_16x16x32_bf16 v[38:41], v[150:153], v[174:177], v[38:41]
	v_mfma_f32_16x16x32_bf16 v[30:33], v[142:145], v[196:199], v[30:33]
	v_mfma_f32_16x16x32_bf16 v[22:25], v[150:153], v[196:199], v[22:25]
	v_mfma_f32_16x16x32_bf16 v[62:65], v[146:149], v[162:165], v[62:65]
	v_mfma_f32_16x16x32_bf16 v[58:61], v[154:157], v[162:165], v[58:61]
	v_mfma_f32_16x16x32_bf16 v[54:57], v[146:149], v[170:173], v[54:57]
	v_mfma_f32_16x16x32_bf16 v[50:53], v[154:157], v[170:173], v[50:53]
	v_mfma_f32_16x16x32_bf16 v[46:49], v[146:149], v[192:195], v[46:49]
	v_mfma_f32_16x16x32_bf16 v[38:41], v[154:157], v[192:195], v[38:41]
	v_mfma_f32_16x16x32_bf16 v[30:33], v[146:149], v[200:203], v[30:33]
	v_mfma_f32_16x16x32_bf16 v[22:25], v[154:157], v[200:203], v[22:25]
	s_barrier
	s_add_u32 s52, s82, 0x80000
	s_addc_u32 s53, s83, 0
	s_add_i32 s54, s54, s26
	v_lshl_add_u64 v[142:143], s[52:53], 0, v[132:133]
	s_mov_b32 m0, s54
	s_nop 0
	global_load_lds_dwordx4 v[142:143], off
	v_lshl_add_u64 v[142:143], s[52:53], 0, v[130:131]
	s_add_i32 m0, s54, 0x2000
	s_nop 0
	global_load_lds_dwordx4 v[142:143], off
	v_add_u32_e32 v141, 0x18000, v138
	ds_read_b128 v[142:145], v141
	ds_read_b128 v[146:149], v141 offset:1024
	ds_read_b128 v[150:153], v141 offset:2048
	ds_read_b128 v[154:157], v141 offset:3072
	s_waitcnt vmcnt(6)
	s_barrier
	v_mfma_f32_16x16x32_bf16 v[42:45], v[204:207], v[158:161], v[42:45]
	v_mfma_f32_16x16x32_bf16 v[34:37], v[224:227], v[158:161], v[34:37]
	v_mfma_f32_16x16x32_bf16 v[26:29], v[204:207], v[166:169], v[26:29]
	v_mfma_f32_16x16x32_bf16 v[18:21], v[224:227], v[166:169], v[18:21]
	v_mfma_f32_16x16x32_bf16 v[14:17], v[204:207], v[174:177], v[14:17]
	v_mfma_f32_16x16x32_bf16 v[10:13], v[224:227], v[174:177], v[10:13]
	v_mfma_f32_16x16x32_bf16 v[6:9], v[204:207], v[196:199], v[6:9]
	v_mfma_f32_16x16x32_bf16 v[2:5], v[224:227], v[196:199], v[2:5]
	v_mfma_f32_16x16x32_bf16 v[42:45], v[208:211], v[162:165], v[42:45]
	v_mfma_f32_16x16x32_bf16 v[34:37], v[228:231], v[162:165], v[34:37]
	v_mfma_f32_16x16x32_bf16 v[26:29], v[208:211], v[170:173], v[26:29]
	v_mfma_f32_16x16x32_bf16 v[18:21], v[228:231], v[170:173], v[18:21]
	v_mfma_f32_16x16x32_bf16 v[14:17], v[208:211], v[192:195], v[14:17]
	v_mfma_f32_16x16x32_bf16 v[10:13], v[228:231], v[192:195], v[10:13]
	v_mfma_f32_16x16x32_bf16 v[6:9], v[208:211], v[200:203], v[6:9]
	v_mfma_f32_16x16x32_bf16 v[2:5], v[228:231], v[200:203], v[2:5]
	s_add_i32 s52, 0, 0x18000
	s_barrier
	s_add_u32 s22, s22, 0x80000
	s_addc_u32 s23, s23, 0
	s_mov_b32 m0, s29
	v_lshl_add_u64 v[204:205], s[22:23], 0, v[132:133]
	ds_read_b128 v[158:161], v140 offset:32768
	ds_read_b128 v[162:165], v140 offset:33792
	ds_read_b128 v[166:169], v140 offset:34816
	ds_read_b128 v[170:173], v140 offset:35840
	ds_read_b128 v[174:177], v140 offset:36864
	ds_read_b128 v[192:195], v140 offset:37888
	ds_read_b128 v[196:199], v140 offset:38912
	ds_read_b128 v[200:203], v140 offset:39936
	global_load_lds_dwordx4 v[204:205], off
	v_lshl_add_u64 v[204:205], s[22:23], 0, v[130:131]
	s_mov_b32 m0, s36
	s_nop 0
	global_load_lds_dwordx4 v[204:205], off
	s_waitcnt lgkmcnt(8)
	s_barrier
	s_waitcnt lgkmcnt(0)
	v_mfma_f32_16x16x32_bf16 v[126:129], v[142:145], v[158:161], v[126:129]
	v_mfma_f32_16x16x32_bf16 v[122:125], v[150:153], v[158:161], v[122:125]
	v_mfma_f32_16x16x32_bf16 v[118:121], v[142:145], v[166:169], v[118:121]
	v_mfma_f32_16x16x32_bf16 v[114:117], v[150:153], v[166:169], v[114:117]
	v_mfma_f32_16x16x32_bf16 v[110:113], v[142:145], v[174:177], v[110:113]
	v_mfma_f32_16x16x32_bf16 v[102:105], v[150:153], v[174:177], v[102:105]
	v_mfma_f32_16x16x32_bf16 v[94:97], v[142:145], v[196:199], v[94:97]
	v_mfma_f32_16x16x32_bf16 v[86:89], v[150:153], v[196:199], v[86:89]
	v_mfma_f32_16x16x32_bf16 v[126:129], v[146:149], v[162:165], v[126:129]
	v_mfma_f32_16x16x32_bf16 v[122:125], v[154:157], v[162:165], v[122:125]
	v_mfma_f32_16x16x32_bf16 v[118:121], v[146:149], v[170:173], v[118:121]
	v_mfma_f32_16x16x32_bf16 v[114:117], v[154:157], v[170:173], v[114:117]
	v_mfma_f32_16x16x32_bf16 v[110:113], v[146:149], v[192:195], v[110:113]
	v_mfma_f32_16x16x32_bf16 v[102:105], v[154:157], v[192:195], v[102:105]
	v_mfma_f32_16x16x32_bf16 v[94:97], v[146:149], v[200:203], v[94:97]
	v_mfma_f32_16x16x32_bf16 v[86:89], v[154:157], v[200:203], v[86:89]
	s_barrier
	s_add_i32 s53, 0, 0x1c000
	s_add_i32 s22, s52, s26
	v_add_u32_e32 v141, s53, v138
	v_lshl_add_u64 v[178:179], v[178:179], 0, s[78:79]
	s_mov_b32 m0, s22
	ds_read_b128 v[204:207], v141
	ds_read_b128 v[208:211], v141 offset:1024
	ds_read_b128 v[224:227], v141 offset:2048
	ds_read_b128 v[228:231], v141 offset:3072
	global_load_lds_dwordx4 v[178:179], off
	v_lshl_add_u64 v[178:179], v[212:213], 0, s[78:79]
	s_add_i32 m0, s22, 0x2000
	s_nop 0
	global_load_lds_dwordx4 v[178:179], off
	s_barrier
	s_waitcnt lgkmcnt(0)
	v_mfma_f32_16x16x32_bf16 v[106:109], v[204:207], v[158:161], v[106:109]
	v_mfma_f32_16x16x32_bf16 v[98:101], v[224:227], v[158:161], v[98:101]
	v_mfma_f32_16x16x32_bf16 v[90:93], v[204:207], v[166:169], v[90:93]
	v_mfma_f32_16x16x32_bf16 v[82:85], v[224:227], v[166:169], v[82:85]
	v_mfma_f32_16x16x32_bf16 v[78:81], v[204:207], v[174:177], v[78:81]
	v_mfma_f32_16x16x32_bf16 v[74:77], v[224:227], v[174:177], v[74:77]
	v_mfma_f32_16x16x32_bf16 v[70:73], v[204:207], v[196:199], v[70:73]
	v_mfma_f32_16x16x32_bf16 v[66:69], v[224:227], v[196:199], v[66:69]
	v_mfma_f32_16x16x32_bf16 v[106:109], v[208:211], v[162:165], v[106:109]
	v_mfma_f32_16x16x32_bf16 v[98:101], v[228:231], v[162:165], v[98:101]
	v_mfma_f32_16x16x32_bf16 v[90:93], v[208:211], v[170:173], v[90:93]
	v_mfma_f32_16x16x32_bf16 v[82:85], v[228:231], v[170:173], v[82:85]
	v_mfma_f32_16x16x32_bf16 v[78:81], v[208:211], v[192:195], v[78:81]
	v_mfma_f32_16x16x32_bf16 v[74:77], v[228:231], v[192:195], v[74:77]
	v_mfma_f32_16x16x32_bf16 v[70:73], v[208:211], v[200:203], v[70:73]
	v_mfma_f32_16x16x32_bf16 v[66:69], v[228:231], v[200:203], v[66:69]
	s_mov_b32 m0, s42
	v_lshl_add_u64 v[178:179], v[232:233], 0, s[78:79]
	s_barrier
	ds_read_b128 v[158:161], v140 offset:49152
	ds_read_b128 v[162:165], v140 offset:50176
	ds_read_b128 v[166:169], v140 offset:51200
	ds_read_b128 v[170:173], v140 offset:52224
	ds_read_b128 v[174:177], v140 offset:53248
	ds_read_b128 v[192:195], v140 offset:54272
	ds_read_b128 v[196:199], v140 offset:55296
	ds_read_b128 v[200:203], v140 offset:56320
	global_load_lds_dwordx4 v[178:179], off
	v_lshl_add_u64 v[178:179], v[234:235], 0, s[78:79]
	s_mov_b32 m0, s43
	s_nop 0
	global_load_lds_dwordx4 v[178:179], off
	s_waitcnt vmcnt(10)
	s_barrier
	s_waitcnt lgkmcnt(0)
	v_mfma_f32_16x16x32_bf16 v[62:65], v[142:145], v[158:161], v[62:65]
	v_mfma_f32_16x16x32_bf16 v[58:61], v[150:153], v[158:161], v[58:61]
	v_mfma_f32_16x16x32_bf16 v[54:57], v[142:145], v[166:169], v[54:57]
	v_mfma_f32_16x16x32_bf16 v[50:53], v[150:153], v[166:169], v[50:53]
	v_mfma_f32_16x16x32_bf16 v[46:49], v[142:145], v[174:177], v[46:49]
	v_mfma_f32_16x16x32_bf16 v[38:41], v[150:153], v[174:177], v[38:41]
	v_mfma_f32_16x16x32_bf16 v[30:33], v[142:145], v[196:199], v[30:33]
	v_mfma_f32_16x16x32_bf16 v[22:25], v[150:153], v[196:199], v[22:25]
	v_mfma_f32_16x16x32_bf16 v[62:65], v[146:149], v[162:165], v[62:65]
	v_mfma_f32_16x16x32_bf16 v[58:61], v[154:157], v[162:165], v[58:61]
	v_mfma_f32_16x16x32_bf16 v[54:57], v[146:149], v[170:173], v[54:57]
	v_mfma_f32_16x16x32_bf16 v[50:53], v[154:157], v[170:173], v[50:53]
	v_mfma_f32_16x16x32_bf16 v[46:49], v[146:149], v[192:195], v[46:49]
	v_mfma_f32_16x16x32_bf16 v[38:41], v[154:157], v[192:195], v[38:41]
	v_mfma_f32_16x16x32_bf16 v[30:33], v[146:149], v[200:203], v[30:33]
	v_mfma_f32_16x16x32_bf16 v[22:25], v[154:157], v[200:203], v[22:25]
	s_barrier
	s_add_u32 s22, s82, 0x80080
	s_addc_u32 s23, s83, 0
	s_add_i32 s52, s53, s26
	v_lshl_add_u64 v[142:143], s[22:23], 0, v[132:133]
	s_mov_b32 m0, s52
	s_nop 0
	global_load_lds_dwordx4 v[142:143], off
	v_lshl_add_u64 v[142:143], s[22:23], 0, v[130:131]
	s_add_i32 m0, s52, 0x2000
	s_nop 0
	global_load_lds_dwordx4 v[142:143], off
	v_add_u32_e32 v141, 0x10000, v138
	ds_read_b128 v[142:145], v141
	ds_read_b128 v[146:149], v141 offset:1024
	ds_read_b128 v[150:153], v141 offset:2048
	ds_read_b128 v[154:157], v141 offset:3072
	s_waitcnt vmcnt(6)
	s_barrier
	v_mfma_f32_16x16x32_bf16 v[42:45], v[204:207], v[158:161], v[42:45]
	v_mfma_f32_16x16x32_bf16 v[34:37], v[224:227], v[158:161], v[34:37]
	v_mfma_f32_16x16x32_bf16 v[26:29], v[204:207], v[166:169], v[26:29]
	v_mfma_f32_16x16x32_bf16 v[18:21], v[224:227], v[166:169], v[18:21]
	v_mfma_f32_16x16x32_bf16 v[14:17], v[204:207], v[174:177], v[14:17]
	v_mfma_f32_16x16x32_bf16 v[10:13], v[224:227], v[174:177], v[10:13]
	v_mfma_f32_16x16x32_bf16 v[6:9], v[204:207], v[196:199], v[6:9]
	v_mfma_f32_16x16x32_bf16 v[2:5], v[224:227], v[196:199], v[2:5]
	v_mfma_f32_16x16x32_bf16 v[42:45], v[208:211], v[162:165], v[42:45]
	v_mfma_f32_16x16x32_bf16 v[34:37], v[228:231], v[162:165], v[34:37]
	v_mfma_f32_16x16x32_bf16 v[26:29], v[208:211], v[170:173], v[26:29]
	v_mfma_f32_16x16x32_bf16 v[18:21], v[228:231], v[170:173], v[18:21]
	v_mfma_f32_16x16x32_bf16 v[14:17], v[208:211], v[192:195], v[14:17]
	v_mfma_f32_16x16x32_bf16 v[10:13], v[228:231], v[192:195], v[10:13]
	v_mfma_f32_16x16x32_bf16 v[6:9], v[208:211], v[200:203], v[6:9]
	v_mfma_f32_16x16x32_bf16 v[2:5], v[228:231], v[200:203], v[2:5]
	s_add_i32 s51, s51, 2
	s_add_u32 s80, s80, 0x100
	s_addc_u32 s81, s81, 0
	s_add_u32 s49, s49, 0x100
	s_addc_u32 s50, s50, 0
	s_cmp_gt_u32 s51, 29
	s_barrier
	s_cbranch_scc0 .LBB0_240
	s_waitcnt lgkmcnt(0)
	v_readlane_b32 s48, v254, 40
	v_lshl_or_b32 v142, s45, 8, v139
	v_readlane_b32 s52, v254, 44
	v_readlane_b32 s53, v254, 45
	v_lshl_add_u32 v141, s46, 8, v1
	v_ashrrev_i32_e32 v143, 31, v142
	v_mov_b64_e32 v[144:145], s[52:53]
	s_movk_i32 s19, 0x1400
	v_mad_i64_i32 v[146:147], s[22:23], v141, s19, v[144:145]
	v_lshlrev_b64 v[142:143], 2, v[142:143]
	v_lshl_add_u64 v[146:147], v[146:147], 0, v[142:143]
	global_store_dwordx4 v[146:147], v[126:129], off
	global_store_dwordx4 v[146:147], v[122:125], off offset:64
	global_store_dwordx4 v[146:147], v[106:109], off offset:512
	global_store_dwordx4 v[146:147], v[98:101], off offset:576
	s_movk_i32 s94, 0x1400
	s_and_b64 vcc, exec, s[0:1]
	v_or_b32_e32 v98, 16, v141
	v_mad_i64_i32 v[98:99], s[22:23], v98, s19, v[144:145]
	v_lshl_add_u64 v[98:99], v[98:99], 0, v[142:143]
	global_store_dwordx4 v[98:99], v[118:121], off
	global_store_dwordx4 v[98:99], v[114:117], off offset:64
	global_store_dwordx4 v[98:99], v[90:93], off offset:512
	global_store_dwordx4 v[98:99], v[82:85], off offset:576
	s_mov_b32 s45, s18
	s_mov_b32 s46, s20
	v_or_b32_e32 v82, 32, v141
	v_mad_i64_i32 v[82:83], s[22:23], v82, s19, v[144:145]
	v_lshl_add_u64 v[82:83], v[82:83], 0, v[142:143]
	global_store_dwordx4 v[82:83], v[110:113], off
	global_store_dwordx4 v[82:83], v[102:105], off offset:64
	global_store_dwordx4 v[82:83], v[78:81], off offset:512
	global_store_dwordx4 v[82:83], v[74:77], off offset:576
	s_mov_b64 s[80:81], s[30:31]
	v_readlane_b32 s49, v254, 41
	v_or_b32_e32 v74, 48, v141
	v_mad_i64_i32 v[74:75], s[22:23], v74, s19, v[144:145]
	v_lshl_add_u64 v[74:75], v[74:75], 0, v[142:143]
	global_store_dwordx4 v[74:75], v[94:97], off
	global_store_dwordx4 v[74:75], v[86:89], off offset:64
	global_store_dwordx4 v[74:75], v[70:73], off offset:512
	global_store_dwordx4 v[74:75], v[66:69], off offset:576
	v_readlane_b32 s50, v254, 42
	v_readlane_b32 s51, v254, 43
	v_add_u32_e32 v66, 0x80, v141
	v_mad_i64_i32 v[66:67], s[22:23], v66, s19, v[144:145]
	v_lshl_add_u64 v[66:67], v[66:67], 0, v[142:143]
	global_store_dwordx4 v[66:67], v[62:65], off
	global_store_dwordx4 v[66:67], v[58:61], off offset:64
	global_store_dwordx4 v[66:67], v[42:45], off offset:512
	global_store_dwordx4 v[66:67], v[34:37], off offset:576
	v_readlane_b32 s54, v254, 46
	v_readlane_b32 s55, v254, 47
	v_add_u32_e32 v34, 0x90, v141
	v_mad_i64_i32 v[34:35], s[22:23], v34, s19, v[144:145]
	v_lshl_add_u64 v[34:35], v[34:35], 0, v[142:143]
	global_store_dwordx4 v[34:35], v[54:57], off
	global_store_dwordx4 v[34:35], v[50:53], off offset:64
	global_store_dwordx4 v[34:35], v[26:29], off offset:512
	global_store_dwordx4 v[34:35], v[18:21], off offset:576
	v_readlane_b32 s56, v254, 48
	v_readlane_b32 s57, v254, 49
	v_add_u32_e32 v18, 0xa0, v141
	v_mad_i64_i32 v[18:19], s[22:23], v18, s19, v[144:145]
	v_lshl_add_u64 v[18:19], v[18:19], 0, v[142:143]
	global_store_dwordx4 v[18:19], v[46:49], off
	global_store_dwordx4 v[18:19], v[38:41], off offset:64
	global_store_dwordx4 v[18:19], v[14:17], off offset:512
	global_store_dwordx4 v[18:19], v[10:13], off offset:576
	v_readlane_b32 s58, v254, 50
	v_readlane_b32 s59, v254, 51
	v_add_u32_e32 v10, 0xb0, v141
	v_mad_i64_i32 v[10:11], s[22:23], v10, s19, v[144:145]
	v_lshl_add_u64 v[10:11], v[10:11], 0, v[142:143]
	s_mov_b64 s[22:23], s[38:39]
	v_readlane_b32 s60, v254, 52
	v_readlane_b32 s61, v254, 53
	v_readlane_b32 s62, v254, 54
	v_readlane_b32 s63, v254, 55
	global_store_dwordx4 v[10:11], v[30:33], off
	global_store_dwordx4 v[10:11], v[22:25], off offset:64
	global_store_dwordx4 v[10:11], v[6:9], off offset:512
	global_store_dwordx4 v[10:11], v[2:5], off offset:576
	s_cbranch_vccz .LBB0_237
	s_waitcnt vmcnt(0)
	v_readlane_b32 s44, v255, 30
	s_cmpk_gt_u32 s25, 0xff
	v_readlane_b32 s45, v255, 31
	v_readlane_b32 s42, v255, 32
	s_cbranch_scc1 .LBB0_244
	s_barrier

.LBB0_357:
	s_add_u32 s22, s20, 0xfffe0080
	s_addc_u32 s23, s21, -1
	s_add_i32 s52, 0, 0x10000
	s_cmp_eq_u32 s51, 4
	s_cselect_b32 s23, s31, s23
	s_cselect_b32 s22, s47, s22
	s_cselect_b32 s85, s19, s50
	s_cselect_b32 s84, s48, s49
	v_lshl_add_u64 v[178:179], s[20:21], 0, v[138:139]
	s_add_i32 m0, s27, 0xc000
	ds_read_b128 v[162:165], v144
	ds_read_b128 v[166:169], v144 offset:1024
	ds_read_b128 v[170:173], v144 offset:2048
	ds_read_b128 v[174:177], v144 offset:3072
	ds_read_b128 v[192:195], v144 offset:4096
	ds_read_b128 v[196:199], v144 offset:5120
	ds_read_b128 v[200:203], v144 offset:6144
	ds_read_b128 v[204:207], v144 offset:7168
	global_load_lds_dwordx4 v[178:179], off
	v_lshl_add_u64 v[178:179], s[20:21], 0, v[140:141]
	s_add_i32 m0, s27, 0xe000
	s_nop 0
	global_load_lds_dwordx4 v[178:179], off
	s_waitcnt lgkmcnt(8)
	s_barrier
	s_waitcnt lgkmcnt(0)
	v_mfma_f32_16x16x32_bf16 v[126:129], v[146:149], v[162:165], v[126:129]
	v_mfma_f32_16x16x32_bf16 v[122:125], v[154:157], v[162:165], v[122:125]
	v_mfma_f32_16x16x32_bf16 v[118:121], v[146:149], v[170:173], v[118:121]
	v_mfma_f32_16x16x32_bf16 v[114:117], v[154:157], v[170:173], v[114:117]
	v_mfma_f32_16x16x32_bf16 v[102:105], v[146:149], v[192:195], v[102:105]
	v_mfma_f32_16x16x32_bf16 v[98:101], v[154:157], v[192:195], v[98:101]
	v_mfma_f32_16x16x32_bf16 v[86:89], v[146:149], v[200:203], v[86:89]
	v_mfma_f32_16x16x32_bf16 v[82:85], v[154:157], v[200:203], v[82:85]
	v_mfma_f32_16x16x32_bf16 v[126:129], v[150:153], v[166:169], v[126:129]
	v_mfma_f32_16x16x32_bf16 v[122:125], v[158:161], v[166:169], v[122:125]
	v_mfma_f32_16x16x32_bf16 v[118:121], v[150:153], v[174:177], v[118:121]
	v_mfma_f32_16x16x32_bf16 v[114:117], v[158:161], v[174:177], v[114:117]
	v_mfma_f32_16x16x32_bf16 v[102:105], v[150:153], v[196:199], v[102:105]
	v_mfma_f32_16x16x32_bf16 v[98:101], v[158:161], v[196:199], v[98:101]
	v_mfma_f32_16x16x32_bf16 v[86:89], v[150:153], v[204:207], v[86:89]
	v_mfma_f32_16x16x32_bf16 v[82:85], v[158:161], v[204:207], v[82:85]
	s_barrier
	s_add_i32 s54, 0, 0x14000
	s_add_i32 s52, s52, s26
	v_add_u32_e32 v145, s54, v142
	v_lshl_add_u64 v[178:179], s[84:85], 0, v[134:135]
	s_mov_b32 m0, s52
	ds_read_b128 v[208:211], v145
	ds_read_b128 v[224:227], v145 offset:1024
	ds_read_b128 v[228:231], v145 offset:2048
	ds_read_b128 v[232:235], v145 offset:3072
	global_load_lds_dwordx4 v[178:179], off
	v_lshl_add_u64 v[212:213], s[84:85], 0, v[130:131]
	s_add_i32 m0, s52, 0x2000
	s_nop 0
	global_load_lds_dwordx4 v[212:213], off
	s_barrier
	s_waitcnt lgkmcnt(0)
	v_mfma_f32_16x16x32_bf16 v[110:113], v[208:211], v[162:165], v[110:113]
	v_mfma_f32_16x16x32_bf16 v[106:109], v[228:231], v[162:165], v[106:109]
	v_mfma_f32_16x16x32_bf16 v[94:97], v[208:211], v[170:173], v[94:97]
	v_mfma_f32_16x16x32_bf16 v[90:93], v[228:231], v[170:173], v[90:93]
	v_mfma_f32_16x16x32_bf16 v[78:81], v[208:211], v[192:195], v[78:81]
	v_mfma_f32_16x16x32_bf16 v[74:77], v[228:231], v[192:195], v[74:77]
	v_mfma_f32_16x16x32_bf16 v[70:73], v[208:211], v[200:203], v[70:73]
	v_mfma_f32_16x16x32_bf16 v[66:69], v[228:231], v[200:203], v[66:69]
	v_mfma_f32_16x16x32_bf16 v[110:113], v[224:227], v[166:169], v[110:113]
	v_mfma_f32_16x16x32_bf16 v[106:109], v[232:235], v[166:169], v[106:109]
	v_mfma_f32_16x16x32_bf16 v[94:97], v[224:227], v[174:177], v[94:97]
	v_mfma_f32_16x16x32_bf16 v[90:93], v[232:235], v[174:177], v[90:93]
	v_mfma_f32_16x16x32_bf16 v[78:81], v[224:227], v[196:199], v[78:81]
	v_mfma_f32_16x16x32_bf16 v[74:77], v[232:235], v[196:199], v[74:77]
	v_mfma_f32_16x16x32_bf16 v[70:73], v[224:227], v[204:207], v[70:73]
	v_mfma_f32_16x16x32_bf16 v[66:69], v[232:235], v[204:207], v[66:69]
	s_mov_b32 m0, s27
	v_lshl_add_u64 v[236:237], s[22:23], 0, v[136:137]
	s_barrier
	ds_read_b128 v[162:165], v144 offset:16384
	ds_read_b128 v[166:169], v144 offset:17408
	ds_read_b128 v[170:173], v144 offset:18432
	ds_read_b128 v[174:177], v144 offset:19456
	ds_read_b128 v[192:195], v144 offset:20480
	ds_read_b128 v[196:199], v144 offset:21504
	ds_read_b128 v[200:203], v144 offset:22528
	ds_read_b128 v[204:207], v144 offset:23552
	global_load_lds_dwordx4 v[236:237], off
	v_lshl_add_u64 v[238:239], s[22:23], 0, v[132:133]
	s_mov_b32 m0, s28
	s_nop 0
	global_load_lds_dwordx4 v[238:239], off
	s_waitcnt vmcnt(10)
	s_barrier
	s_waitcnt lgkmcnt(0)
	v_mfma_f32_16x16x32_bf16 v[62:65], v[146:149], v[162:165], v[62:65]
	v_mfma_f32_16x16x32_bf16 v[58:61], v[154:157], v[162:165], v[58:61]
	v_mfma_f32_16x16x32_bf16 v[54:57], v[146:149], v[170:173], v[54:57]
	v_mfma_f32_16x16x32_bf16 v[50:53], v[154:157], v[170:173], v[50:53]
	v_mfma_f32_16x16x32_bf16 v[38:41], v[146:149], v[192:195], v[38:41]
	v_mfma_f32_16x16x32_bf16 v[34:37], v[154:157], v[192:195], v[34:37]
	v_mfma_f32_16x16x32_bf16 v[22:25], v[146:149], v[200:203], v[22:25]
	v_mfma_f32_16x16x32_bf16 v[18:21], v[154:157], v[200:203], v[18:21]
	v_mfma_f32_16x16x32_bf16 v[62:65], v[150:153], v[166:169], v[62:65]
	v_mfma_f32_16x16x32_bf16 v[58:61], v[158:161], v[166:169], v[58:61]
	v_mfma_f32_16x16x32_bf16 v[54:57], v[150:153], v[174:177], v[54:57]
	v_mfma_f32_16x16x32_bf16 v[50:53], v[158:161], v[174:177], v[50:53]
	v_mfma_f32_16x16x32_bf16 v[38:41], v[150:153], v[196:199], v[38:41]
	v_mfma_f32_16x16x32_bf16 v[34:37], v[158:161], v[196:199], v[34:37]
	v_mfma_f32_16x16x32_bf16 v[22:25], v[150:153], v[204:207], v[22:25]
	v_mfma_f32_16x16x32_bf16 v[18:21], v[158:161], v[204:207], v[18:21]
	s_barrier
	s_add_u32 s52, s84, 0x20000
	s_addc_u32 s53, s85, 0
	s_add_i32 s54, s54, s26
	v_lshl_add_u64 v[146:147], s[52:53], 0, v[134:135]
	s_mov_b32 m0, s54
	s_nop 0
	global_load_lds_dwordx4 v[146:147], off
	v_lshl_add_u64 v[146:147], s[52:53], 0, v[130:131]
	s_add_i32 m0, s54, 0x2000
	s_nop 0
	global_load_lds_dwordx4 v[146:147], off
	v_add_u32_e32 v145, 0x18000, v142
	ds_read_b128 v[146:149], v145
	ds_read_b128 v[150:153], v145 offset:1024
	ds_read_b128 v[154:157], v145 offset:2048
	ds_read_b128 v[158:161], v145 offset:3072
	s_waitcnt vmcnt(6)
	s_barrier
	v_mfma_f32_16x16x32_bf16 v[46:49], v[208:211], v[162:165], v[46:49]
	v_mfma_f32_16x16x32_bf16 v[42:45], v[228:231], v[162:165], v[42:45]
	v_mfma_f32_16x16x32_bf16 v[30:33], v[208:211], v[170:173], v[30:33]
	v_mfma_f32_16x16x32_bf16 v[26:29], v[228:231], v[170:173], v[26:29]
	v_mfma_f32_16x16x32_bf16 v[14:17], v[208:211], v[192:195], v[14:17]
	v_mfma_f32_16x16x32_bf16 v[10:13], v[228:231], v[192:195], v[10:13]
	v_mfma_f32_16x16x32_bf16 v[6:9], v[208:211], v[200:203], v[6:9]
	v_mfma_f32_16x16x32_bf16 v[2:5], v[228:231], v[200:203], v[2:5]
	v_mfma_f32_16x16x32_bf16 v[46:49], v[224:227], v[166:169], v[46:49]
	v_mfma_f32_16x16x32_bf16 v[42:45], v[232:235], v[166:169], v[42:45]
	v_mfma_f32_16x16x32_bf16 v[30:33], v[224:227], v[174:177], v[30:33]
	v_mfma_f32_16x16x32_bf16 v[26:29], v[232:235], v[174:177], v[26:29]
	v_mfma_f32_16x16x32_bf16 v[14:17], v[224:227], v[196:199], v[14:17]
	v_mfma_f32_16x16x32_bf16 v[10:13], v[232:235], v[196:199], v[10:13]
	v_mfma_f32_16x16x32_bf16 v[6:9], v[224:227], v[204:207], v[6:9]
	v_mfma_f32_16x16x32_bf16 v[2:5], v[232:235], v[204:207], v[2:5]
	s_add_i32 s52, 0, 0x18000
	s_barrier
	s_add_u32 s22, s22, 0x20000
	s_addc_u32 s23, s23, 0
	s_mov_b32 m0, s29
	v_lshl_add_u64 v[208:209], s[22:23], 0, v[136:137]
	ds_read_b128 v[162:165], v144 offset:32768
	ds_read_b128 v[166:169], v144 offset:33792
	ds_read_b128 v[170:173], v144 offset:34816
	ds_read_b128 v[174:177], v144 offset:35840
	ds_read_b128 v[192:195], v144 offset:36864
	ds_read_b128 v[196:199], v144 offset:37888
	ds_read_b128 v[200:203], v144 offset:38912
	ds_read_b128 v[204:207], v144 offset:39936
	global_load_lds_dwordx4 v[208:209], off
	v_lshl_add_u64 v[208:209], s[22:23], 0, v[132:133]
	s_mov_b32 m0, s36
	s_nop 0
	global_load_lds_dwordx4 v[208:209], off
	s_waitcnt lgkmcnt(8)
	s_barrier
	s_waitcnt lgkmcnt(0)
	v_mfma_f32_16x16x32_bf16 v[126:129], v[146:149], v[162:165], v[126:129]
	v_mfma_f32_16x16x32_bf16 v[122:125], v[154:157], v[162:165], v[122:125]
	v_mfma_f32_16x16x32_bf16 v[118:121], v[146:149], v[170:173], v[118:121]
	v_mfma_f32_16x16x32_bf16 v[114:117], v[154:157], v[170:173], v[114:117]
	v_mfma_f32_16x16x32_bf16 v[102:105], v[146:149], v[192:195], v[102:105]
	v_mfma_f32_16x16x32_bf16 v[98:101], v[154:157], v[192:195], v[98:101]
	v_mfma_f32_16x16x32_bf16 v[86:89], v[146:149], v[200:203], v[86:89]
	v_mfma_f32_16x16x32_bf16 v[82:85], v[154:157], v[200:203], v[82:85]
	v_mfma_f32_16x16x32_bf16 v[126:129], v[150:153], v[166:169], v[126:129]
	v_mfma_f32_16x16x32_bf16 v[122:125], v[158:161], v[166:169], v[122:125]
	v_mfma_f32_16x16x32_bf16 v[118:121], v[150:153], v[174:177], v[118:121]
	v_mfma_f32_16x16x32_bf16 v[114:117], v[158:161], v[174:177], v[114:117]
	v_mfma_f32_16x16x32_bf16 v[102:105], v[150:153], v[196:199], v[102:105]
	v_mfma_f32_16x16x32_bf16 v[98:101], v[158:161], v[196:199], v[98:101]
	v_mfma_f32_16x16x32_bf16 v[86:89], v[150:153], v[204:207], v[86:89]
	v_mfma_f32_16x16x32_bf16 v[82:85], v[158:161], v[204:207], v[82:85]
	s_barrier
	s_add_i32 s53, 0, 0x1c000
	s_add_i32 s22, s52, s26
	v_add_u32_e32 v145, s53, v142
	v_lshl_add_u64 v[178:179], v[178:179], 0, s[78:79]
	s_mov_b32 m0, s22
	ds_read_b128 v[208:211], v145
	ds_read_b128 v[224:227], v145 offset:1024
	ds_read_b128 v[228:231], v145 offset:2048
	ds_read_b128 v[232:235], v145 offset:3072
	global_load_lds_dwordx4 v[178:179], off
	v_lshl_add_u64 v[178:179], v[212:213], 0, s[78:79]
	s_add_i32 m0, s22, 0x2000
	s_nop 0
	global_load_lds_dwordx4 v[178:179], off
	s_barrier
	s_waitcnt lgkmcnt(0)
	v_mfma_f32_16x16x32_bf16 v[110:113], v[208:211], v[162:165], v[110:113]
	v_mfma_f32_16x16x32_bf16 v[106:109], v[228:231], v[162:165], v[106:109]
	v_mfma_f32_16x16x32_bf16 v[94:97], v[208:211], v[170:173], v[94:97]
	v_mfma_f32_16x16x32_bf16 v[90:93], v[228:231], v[170:173], v[90:93]
	v_mfma_f32_16x16x32_bf16 v[78:81], v[208:211], v[192:195], v[78:81]
	v_mfma_f32_16x16x32_bf16 v[74:77], v[228:231], v[192:195], v[74:77]
	v_mfma_f32_16x16x32_bf16 v[70:73], v[208:211], v[200:203], v[70:73]
	v_mfma_f32_16x16x32_bf16 v[66:69], v[228:231], v[200:203], v[66:69]
	v_mfma_f32_16x16x32_bf16 v[110:113], v[224:227], v[166:169], v[110:113]
	v_mfma_f32_16x16x32_bf16 v[106:109], v[232:235], v[166:169], v[106:109]
	v_mfma_f32_16x16x32_bf16 v[94:97], v[224:227], v[174:177], v[94:97]
	v_mfma_f32_16x16x32_bf16 v[90:93], v[232:235], v[174:177], v[90:93]
	v_mfma_f32_16x16x32_bf16 v[78:81], v[224:227], v[196:199], v[78:81]
	v_mfma_f32_16x16x32_bf16 v[74:77], v[232:235], v[196:199], v[74:77]
	v_mfma_f32_16x16x32_bf16 v[70:73], v[224:227], v[204:207], v[70:73]
	v_mfma_f32_16x16x32_bf16 v[66:69], v[232:235], v[204:207], v[66:69]
	s_mov_b32 m0, s42
	v_lshl_add_u64 v[178:179], v[236:237], 0, s[78:79]
	s_barrier
	ds_read_b128 v[162:165], v144 offset:49152
	ds_read_b128 v[166:169], v144 offset:50176
	ds_read_b128 v[170:173], v144 offset:51200
	ds_read_b128 v[174:177], v144 offset:52224
	ds_read_b128 v[192:195], v144 offset:53248
	ds_read_b128 v[196:199], v144 offset:54272
	ds_read_b128 v[200:203], v144 offset:55296
	ds_read_b128 v[204:207], v144 offset:56320
	global_load_lds_dwordx4 v[178:179], off
	v_lshl_add_u64 v[178:179], v[238:239], 0, s[78:79]
	s_mov_b32 m0, s43
	s_nop 0
	global_load_lds_dwordx4 v[178:179], off
	s_waitcnt vmcnt(10)
	s_barrier
	s_waitcnt lgkmcnt(0)
	v_mfma_f32_16x16x32_bf16 v[62:65], v[146:149], v[162:165], v[62:65]
	v_mfma_f32_16x16x32_bf16 v[58:61], v[154:157], v[162:165], v[58:61]
	v_mfma_f32_16x16x32_bf16 v[54:57], v[146:149], v[170:173], v[54:57]
	v_mfma_f32_16x16x32_bf16 v[50:53], v[154:157], v[170:173], v[50:53]
	v_mfma_f32_16x16x32_bf16 v[38:41], v[146:149], v[192:195], v[38:41]
	v_mfma_f32_16x16x32_bf16 v[34:37], v[154:157], v[192:195], v[34:37]
	v_mfma_f32_16x16x32_bf16 v[22:25], v[146:149], v[200:203], v[22:25]
	v_mfma_f32_16x16x32_bf16 v[18:21], v[154:157], v[200:203], v[18:21]
	v_mfma_f32_16x16x32_bf16 v[62:65], v[150:153], v[166:169], v[62:65]
	v_mfma_f32_16x16x32_bf16 v[58:61], v[158:161], v[166:169], v[58:61]
	v_mfma_f32_16x16x32_bf16 v[54:57], v[150:153], v[174:177], v[54:57]
	v_mfma_f32_16x16x32_bf16 v[50:53], v[158:161], v[174:177], v[50:53]
	v_mfma_f32_16x16x32_bf16 v[38:41], v[150:153], v[196:199], v[38:41]
	v_mfma_f32_16x16x32_bf16 v[34:37], v[158:161], v[196:199], v[34:37]
	v_mfma_f32_16x16x32_bf16 v[22:25], v[150:153], v[204:207], v[22:25]
	v_mfma_f32_16x16x32_bf16 v[18:21], v[158:161], v[204:207], v[18:21]
	s_barrier
	s_add_u32 s22, s84, 0x20080
	s_addc_u32 s23, s85, 0
	s_add_i32 s52, s53, s26
	v_lshl_add_u64 v[146:147], s[22:23], 0, v[134:135]
	s_mov_b32 m0, s52
	s_nop 0
	global_load_lds_dwordx4 v[146:147], off
	v_lshl_add_u64 v[146:147], s[22:23], 0, v[130:131]
	s_add_i32 m0, s52, 0x2000
	s_nop 0
	global_load_lds_dwordx4 v[146:147], off
	v_add_u32_e32 v145, 0x10000, v142
	ds_read_b128 v[146:149], v145
	ds_read_b128 v[150:153], v145 offset:1024
	ds_read_b128 v[154:157], v145 offset:2048
	ds_read_b128 v[158:161], v145 offset:3072
	s_waitcnt vmcnt(6)
	s_barrier
	v_mfma_f32_16x16x32_bf16 v[46:49], v[208:211], v[162:165], v[46:49]
	v_mfma_f32_16x16x32_bf16 v[42:45], v[228:231], v[162:165], v[42:45]
	v_mfma_f32_16x16x32_bf16 v[30:33], v[208:211], v[170:173], v[30:33]
	v_mfma_f32_16x16x32_bf16 v[26:29], v[228:231], v[170:173], v[26:29]
	v_mfma_f32_16x16x32_bf16 v[14:17], v[208:211], v[192:195], v[14:17]
	v_mfma_f32_16x16x32_bf16 v[10:13], v[228:231], v[192:195], v[10:13]
	v_mfma_f32_16x16x32_bf16 v[6:9], v[208:211], v[200:203], v[6:9]
	v_mfma_f32_16x16x32_bf16 v[2:5], v[228:231], v[200:203], v[2:5]
	v_mfma_f32_16x16x32_bf16 v[46:49], v[224:227], v[166:169], v[46:49]
	v_mfma_f32_16x16x32_bf16 v[42:45], v[232:235], v[166:169], v[42:45]
	v_mfma_f32_16x16x32_bf16 v[30:33], v[224:227], v[174:177], v[30:33]
	v_mfma_f32_16x16x32_bf16 v[26:29], v[232:235], v[174:177], v[26:29]
	v_mfma_f32_16x16x32_bf16 v[14:17], v[224:227], v[196:199], v[14:17]
	v_mfma_f32_16x16x32_bf16 v[10:13], v[232:235], v[196:199], v[10:13]
	v_mfma_f32_16x16x32_bf16 v[6:9], v[224:227], v[204:207], v[6:9]
	v_mfma_f32_16x16x32_bf16 v[2:5], v[232:235], v[204:207], v[2:5]
	s_add_i32 s51, s51, 2
	s_add_u32 s20, s20, 0x100
	s_addc_u32 s21, s21, 0
	s_add_u32 s49, s49, 0x100
	s_addc_u32 s50, s50, 0
	s_cmp_gt_u32 s51, 5
	s_barrier
	s_cbranch_scc0 .LBB0_357
	s_waitcnt lgkmcnt(0)
	v_lshl_add_u32 v146, s46, 8, v1
	v_lshl_or_b32 v148, s45, 8, v143
	v_ashrrev_i32_e32 v147, 31, v146
	v_readlane_b32 s48, v254, 40
	v_ashrrev_i32_e32 v149, 31, v148
	v_lshlrev_b64 v[150:151], 12, v[146:147]
	v_readlane_b32 s60, v254, 52
	v_readlane_b32 s61, v254, 53
	v_lshlrev_b64 v[148:149], 1, v[148:149]
	s_mov_b32 s19, 0x80000
	v_lshl_add_u64 v[150:151], s[60:61], 0, v[150:151]
	v_lshl_add_u64 v[150:151], v[150:151], 0, v[148:149]
	s_mov_b64 s[20:21], 0x80000
	v_cvt_pk_bf16_f32 v62, v62, v63
	v_cvt_pk_bf16_f32 v63, v64, v65
	v_cvt_pk_bf16_f32 v64, v58, v59
	v_add_co_u32_e32 v58, vcc, s19, v150
	v_cvt_pk_bf16_f32 v70, v70, v71
	v_cvt_pk_bf16_f32 v71, v72, v73
	v_cvt_pk_bf16_f32 v72, v66, v67
	v_lshl_add_u64 v[66:67], v[150:151], 0, s[20:21]
	v_addc_co_u32_e32 v59, vcc, 0, v151, vcc
	v_cvt_pk_bf16_f32 v46, v46, v47
	v_cvt_pk_bf16_f32 v47, v48, v49
	v_cvt_pk_bf16_f32 v48, v42, v43
	v_cvt_pk_bf16_f32 v49, v44, v45
	s_mov_b32 s19, 0x90000
	v_cvt_pk_bf16_f32 v110, v110, v111
	v_cvt_pk_bf16_f32 v111, v112, v113
	v_cvt_pk_bf16_f32 v112, v106, v107
	v_or_b32_e32 v106, 16, v146
	global_store_dwordx4 v[66:67], v[46:49], off offset:256
	s_mov_b64 s[20:21], 0x90000
	v_ashrrev_i32_e32 v107, 31, v106
	v_add_co_u32_e32 v48, vcc, s19, v150
	v_cvt_pk_bf16_f32 v94, v94, v95
	v_cvt_pk_bf16_f32 v95, v96, v97
	v_cvt_pk_bf16_f32 v96, v90, v91
	v_or_b32_e32 v90, 32, v146
	v_lshl_add_u64 v[46:47], v[150:151], 0, s[20:21]
	v_addc_co_u32_e32 v49, vcc, 0, v151, vcc
	v_cvt_pk_bf16_f32 v30, v30, v31
	v_cvt_pk_bf16_f32 v31, v32, v33
	v_cvt_pk_bf16_f32 v32, v26, v27
	v_cvt_pk_bf16_f32 v33, v28, v29
	s_mov_b32 s19, 0xa0000
	v_lshlrev_b64 v[106:107], 12, v[106:107]
	v_ashrrev_i32_e32 v91, 31, v90
	v_cvt_pk_bf16_f32 v78, v78, v79
	v_cvt_pk_bf16_f32 v79, v80, v81
	v_cvt_pk_bf16_f32 v80, v74, v75
	v_or_b32_e32 v74, 48, v146
	global_store_dwordx4 v[46:47], v[30:33], off offset:256
	s_mov_b64 s[20:21], 0xa0000
	v_cvt_pk_bf16_f32 v113, v108, v109
	v_add_co_u32_e32 v32, vcc, s19, v150
	v_lshl_add_u64 v[106:107], s[60:61], 0, v[106:107]
	v_lshlrev_b64 v[90:91], 12, v[90:91]
	v_ashrrev_i32_e32 v75, 31, v74
	v_lshl_add_u64 v[30:31], v[150:151], 0, s[20:21]
	v_addc_co_u32_e32 v33, vcc, 0, v151, vcc
	v_cvt_pk_bf16_f32 v14, v14, v15
	v_cvt_pk_bf16_f32 v15, v16, v17
	v_cvt_pk_bf16_f32 v16, v10, v11
	v_cvt_pk_bf16_f32 v17, v12, v13
	s_mov_b32 s19, 0xb0000
	global_store_dwordx4 v[150:151], v[110:113], off offset:256
	v_cvt_pk_bf16_f32 v97, v92, v93
	v_lshl_add_u64 v[90:91], s[60:61], 0, v[90:91]
	v_lshl_add_u64 v[110:111], v[106:107], 0, v[148:149]
	v_lshlrev_b64 v[74:75], 12, v[74:75]
	global_store_dwordx4 v[30:31], v[14:17], off offset:256
	global_store_dwordx4 v[110:111], v[94:97], off offset:256
	v_cvt_pk_bf16_f32 v81, v76, v77
	v_add_co_u32_e32 v16, vcc, s19, v150
	v_lshl_add_u64 v[94:95], v[90:91], 0, v[148:149]
	v_lshl_add_u64 v[74:75], s[60:61], 0, v[74:75]
	s_mov_b64 s[20:21], 0xb0000
	v_addc_co_u32_e32 v17, vcc, 0, v151, vcc
	v_cvt_pk_bf16_f32 v126, v126, v127
	v_cvt_pk_bf16_f32 v127, v128, v129
	v_cvt_pk_bf16_f32 v128, v122, v123
	v_cvt_pk_bf16_f32 v129, v124, v125
	v_cvt_pk_bf16_f32 v106, v118, v119
	v_cvt_pk_bf16_f32 v107, v120, v121
	v_cvt_pk_bf16_f32 v108, v114, v115
	v_cvt_pk_bf16_f32 v109, v116, v117
	v_cvt_pk_bf16_f32 v90, v102, v103
	v_cvt_pk_bf16_f32 v91, v104, v105
	v_cvt_pk_bf16_f32 v92, v98, v99
	v_cvt_pk_bf16_f32 v93, v100, v101
	global_store_dwordx4 v[94:95], v[78:81], off offset:256
	v_cvt_pk_bf16_f32 v76, v82, v83
	v_cvt_pk_bf16_f32 v77, v84, v85
	v_lshl_add_u64 v[78:79], v[74:75], 0, v[148:149]
	v_cvt_pk_bf16_f32 v74, v86, v87
	v_cvt_pk_bf16_f32 v75, v88, v89
	v_cvt_pk_bf16_f32 v73, v68, v69
	v_cvt_pk_bf16_f32 v65, v60, v61
	v_cvt_pk_bf16_f32 v42, v54, v55
	v_cvt_pk_bf16_f32 v43, v56, v57
	v_cvt_pk_bf16_f32 v44, v50, v51
	v_cvt_pk_bf16_f32 v45, v52, v53
	v_cvt_pk_bf16_f32 v26, v38, v39
	v_cvt_pk_bf16_f32 v27, v40, v41
	v_cvt_pk_bf16_f32 v28, v34, v35
	v_cvt_pk_bf16_f32 v29, v36, v37
	v_lshl_add_u64 v[14:15], v[150:151], 0, s[20:21]
	v_cvt_pk_bf16_f32 v10, v22, v23
	v_cvt_pk_bf16_f32 v11, v24, v25
	v_cvt_pk_bf16_f32 v12, v18, v19
	v_cvt_pk_bf16_f32 v13, v20, v21
	v_cvt_pk_bf16_f32 v6, v6, v7
	v_cvt_pk_bf16_f32 v7, v8, v9
	v_cvt_pk_bf16_f32 v8, v2, v3
	v_cvt_pk_bf16_f32 v9, v4, v5
	s_and_b64 vcc, exec, s[38:39]
	s_mov_b32 s45, s18
	s_mov_b32 s46, s30
	s_mov_b64 s[22:23], s[82:83]
	s_mov_b64 s[20:21], s[80:81]
	s_mov_b32 s64, 0x800000
	s_movk_i32 s65, 0x1fff
	v_readlane_b32 s49, v254, 41
	v_readlane_b32 s50, v254, 42
	v_readlane_b32 s51, v254, 43
	v_readlane_b32 s52, v254, 44
	v_readlane_b32 s53, v254, 45
	v_readlane_b32 s54, v254, 46
	v_readlane_b32 s55, v254, 47
	v_readlane_b32 s56, v254, 48
	v_readlane_b32 s57, v254, 49
	v_readlane_b32 s58, v254, 50
	v_readlane_b32 s59, v254, 51
	v_readlane_b32 s62, v254, 54
	v_readlane_b32 s63, v254, 55
	global_store_dwordx4 v[150:151], v[126:129], off
	global_store_dwordx4 v[110:111], v[106:109], off
	global_store_dwordx4 v[94:95], v[90:93], off
	global_store_dwordx4 v[78:79], v[74:77], off
	global_store_dwordx4 v[78:79], v[70:73], off offset:256
	global_store_dwordx4 v[58:59], v[62:65], off
	global_store_dwordx4 v[48:49], v[42:45], off
	global_store_dwordx4 v[32:33], v[26:29], off
	global_store_dwordx4 v[16:17], v[10:13], off
	global_store_dwordx4 v[14:15], v[6:9], off offset:256
	s_cbranch_vccz .LBB0_350
	s_waitcnt vmcnt(0)
	v_readlane_b32 s44, v255, 30
	s_mov_b32 s66, s90
	s_cmpk_gt_u32 s25, 0xff
	v_readlane_b32 s45, v255, 31
	v_readlane_b32 s42, v255, 32
	s_cbranch_scc1 .LBB0_361
	s_barrier

.LBB0_373:
	s_add_u32 s22, s20, 0xfffe0080
	s_addc_u32 s23, s21, -1
	s_add_i32 s52, 0, 0x10000
	s_cmp_eq_u32 s51, 4
	s_cselect_b32 s23, s31, s23
	s_cselect_b32 s22, s47, s22
	s_cselect_b32 s83, s19, s50
	s_cselect_b32 s82, s48, s49
	v_lshl_add_u64 v[178:179], s[20:21], 0, v[138:139]
	s_add_i32 m0, s27, 0xc000
	ds_read_b128 v[162:165], v144
	ds_read_b128 v[166:169], v144 offset:1024
	ds_read_b128 v[170:173], v144 offset:2048
	ds_read_b128 v[174:177], v144 offset:3072
	ds_read_b128 v[192:195], v144 offset:4096
	ds_read_b128 v[196:199], v144 offset:5120
	ds_read_b128 v[200:203], v144 offset:6144
	ds_read_b128 v[204:207], v144 offset:7168
	global_load_lds_dwordx4 v[178:179], off
	v_lshl_add_u64 v[178:179], s[20:21], 0, v[140:141]
	s_add_i32 m0, s27, 0xe000
	s_nop 0
	global_load_lds_dwordx4 v[178:179], off
	s_waitcnt lgkmcnt(8)
	s_barrier
	s_waitcnt lgkmcnt(0)
	v_mfma_f32_16x16x32_bf16 v[126:129], v[146:149], v[162:165], v[126:129]
	v_mfma_f32_16x16x32_bf16 v[122:125], v[154:157], v[162:165], v[122:125]
	v_mfma_f32_16x16x32_bf16 v[118:121], v[146:149], v[170:173], v[118:121]
	v_mfma_f32_16x16x32_bf16 v[114:117], v[154:157], v[170:173], v[114:117]
	v_mfma_f32_16x16x32_bf16 v[102:105], v[146:149], v[192:195], v[102:105]
	v_mfma_f32_16x16x32_bf16 v[98:101], v[154:157], v[192:195], v[98:101]
	v_mfma_f32_16x16x32_bf16 v[86:89], v[146:149], v[200:203], v[86:89]
	v_mfma_f32_16x16x32_bf16 v[82:85], v[154:157], v[200:203], v[82:85]
	v_mfma_f32_16x16x32_bf16 v[126:129], v[150:153], v[166:169], v[126:129]
	v_mfma_f32_16x16x32_bf16 v[122:125], v[158:161], v[166:169], v[122:125]
	v_mfma_f32_16x16x32_bf16 v[118:121], v[150:153], v[174:177], v[118:121]
	v_mfma_f32_16x16x32_bf16 v[114:117], v[158:161], v[174:177], v[114:117]
	v_mfma_f32_16x16x32_bf16 v[102:105], v[150:153], v[196:199], v[102:105]
	v_mfma_f32_16x16x32_bf16 v[98:101], v[158:161], v[196:199], v[98:101]
	v_mfma_f32_16x16x32_bf16 v[86:89], v[150:153], v[204:207], v[86:89]
	v_mfma_f32_16x16x32_bf16 v[82:85], v[158:161], v[204:207], v[82:85]
	s_barrier
	s_add_i32 s54, 0, 0x14000
	s_add_i32 s52, s52, s26
	v_add_u32_e32 v145, s54, v142
	v_lshl_add_u64 v[178:179], s[82:83], 0, v[134:135]
	s_mov_b32 m0, s52
	ds_read_b128 v[208:211], v145
	ds_read_b128 v[224:227], v145 offset:1024
	ds_read_b128 v[228:231], v145 offset:2048
	ds_read_b128 v[232:235], v145 offset:3072
	global_load_lds_dwordx4 v[178:179], off
	v_lshl_add_u64 v[212:213], s[82:83], 0, v[130:131]
	s_add_i32 m0, s52, 0x2000
	s_nop 0
	global_load_lds_dwordx4 v[212:213], off
	s_barrier
	s_waitcnt lgkmcnt(0)
	v_mfma_f32_16x16x32_bf16 v[110:113], v[208:211], v[162:165], v[110:113]
	v_mfma_f32_16x16x32_bf16 v[106:109], v[228:231], v[162:165], v[106:109]
	v_mfma_f32_16x16x32_bf16 v[94:97], v[208:211], v[170:173], v[94:97]
	v_mfma_f32_16x16x32_bf16 v[90:93], v[228:231], v[170:173], v[90:93]
	v_mfma_f32_16x16x32_bf16 v[78:81], v[208:211], v[192:195], v[78:81]
	v_mfma_f32_16x16x32_bf16 v[74:77], v[228:231], v[192:195], v[74:77]
	v_mfma_f32_16x16x32_bf16 v[70:73], v[208:211], v[200:203], v[70:73]
	v_mfma_f32_16x16x32_bf16 v[66:69], v[228:231], v[200:203], v[66:69]
	v_mfma_f32_16x16x32_bf16 v[110:113], v[224:227], v[166:169], v[110:113]
	v_mfma_f32_16x16x32_bf16 v[106:109], v[232:235], v[166:169], v[106:109]
	v_mfma_f32_16x16x32_bf16 v[94:97], v[224:227], v[174:177], v[94:97]
	v_mfma_f32_16x16x32_bf16 v[90:93], v[232:235], v[174:177], v[90:93]
	v_mfma_f32_16x16x32_bf16 v[78:81], v[224:227], v[196:199], v[78:81]
	v_mfma_f32_16x16x32_bf16 v[74:77], v[232:235], v[196:199], v[74:77]
	v_mfma_f32_16x16x32_bf16 v[70:73], v[224:227], v[204:207], v[70:73]
	v_mfma_f32_16x16x32_bf16 v[66:69], v[232:235], v[204:207], v[66:69]
	s_mov_b32 m0, s27
	v_lshl_add_u64 v[236:237], s[22:23], 0, v[136:137]
	s_barrier
	ds_read_b128 v[162:165], v144 offset:16384
	ds_read_b128 v[166:169], v144 offset:17408
	ds_read_b128 v[170:173], v144 offset:18432
	ds_read_b128 v[174:177], v144 offset:19456
	ds_read_b128 v[192:195], v144 offset:20480
	ds_read_b128 v[196:199], v144 offset:21504
	ds_read_b128 v[200:203], v144 offset:22528
	ds_read_b128 v[204:207], v144 offset:23552
	global_load_lds_dwordx4 v[236:237], off
	v_lshl_add_u64 v[238:239], s[22:23], 0, v[132:133]
	s_mov_b32 m0, s28
	s_nop 0
	global_load_lds_dwordx4 v[238:239], off
	s_waitcnt vmcnt(10)
	s_barrier
	s_waitcnt lgkmcnt(0)
	v_mfma_f32_16x16x32_bf16 v[62:65], v[146:149], v[162:165], v[62:65]
	v_mfma_f32_16x16x32_bf16 v[58:61], v[154:157], v[162:165], v[58:61]
	v_mfma_f32_16x16x32_bf16 v[54:57], v[146:149], v[170:173], v[54:57]
	v_mfma_f32_16x16x32_bf16 v[50:53], v[154:157], v[170:173], v[50:53]
	v_mfma_f32_16x16x32_bf16 v[38:41], v[146:149], v[192:195], v[38:41]
	v_mfma_f32_16x16x32_bf16 v[34:37], v[154:157], v[192:195], v[34:37]
	v_mfma_f32_16x16x32_bf16 v[22:25], v[146:149], v[200:203], v[22:25]
	v_mfma_f32_16x16x32_bf16 v[18:21], v[154:157], v[200:203], v[18:21]
	v_mfma_f32_16x16x32_bf16 v[62:65], v[150:153], v[166:169], v[62:65]
	v_mfma_f32_16x16x32_bf16 v[58:61], v[158:161], v[166:169], v[58:61]
	v_mfma_f32_16x16x32_bf16 v[54:57], v[150:153], v[174:177], v[54:57]
	v_mfma_f32_16x16x32_bf16 v[50:53], v[158:161], v[174:177], v[50:53]
	v_mfma_f32_16x16x32_bf16 v[38:41], v[150:153], v[196:199], v[38:41]
	v_mfma_f32_16x16x32_bf16 v[34:37], v[158:161], v[196:199], v[34:37]
	v_mfma_f32_16x16x32_bf16 v[22:25], v[150:153], v[204:207], v[22:25]
	v_mfma_f32_16x16x32_bf16 v[18:21], v[158:161], v[204:207], v[18:21]
	s_barrier
	s_add_u32 s52, s82, 0x20000
	s_addc_u32 s53, s83, 0
	s_add_i32 s54, s54, s26
	v_lshl_add_u64 v[146:147], s[52:53], 0, v[134:135]
	s_mov_b32 m0, s54
	s_nop 0
	global_load_lds_dwordx4 v[146:147], off
	v_lshl_add_u64 v[146:147], s[52:53], 0, v[130:131]
	s_add_i32 m0, s54, 0x2000
	s_nop 0
	global_load_lds_dwordx4 v[146:147], off
	v_add_u32_e32 v145, 0x18000, v142
	ds_read_b128 v[146:149], v145
	ds_read_b128 v[150:153], v145 offset:1024
	ds_read_b128 v[154:157], v145 offset:2048
	ds_read_b128 v[158:161], v145 offset:3072
	s_waitcnt vmcnt(6)
	s_barrier
	v_mfma_f32_16x16x32_bf16 v[46:49], v[208:211], v[162:165], v[46:49]
	v_mfma_f32_16x16x32_bf16 v[42:45], v[228:231], v[162:165], v[42:45]
	v_mfma_f32_16x16x32_bf16 v[30:33], v[208:211], v[170:173], v[30:33]
	v_mfma_f32_16x16x32_bf16 v[26:29], v[228:231], v[170:173], v[26:29]
	v_mfma_f32_16x16x32_bf16 v[14:17], v[208:211], v[192:195], v[14:17]
	v_mfma_f32_16x16x32_bf16 v[10:13], v[228:231], v[192:195], v[10:13]
	v_mfma_f32_16x16x32_bf16 v[6:9], v[208:211], v[200:203], v[6:9]
	v_mfma_f32_16x16x32_bf16 v[2:5], v[228:231], v[200:203], v[2:5]
	v_mfma_f32_16x16x32_bf16 v[46:49], v[224:227], v[166:169], v[46:49]
	v_mfma_f32_16x16x32_bf16 v[42:45], v[232:235], v[166:169], v[42:45]
	v_mfma_f32_16x16x32_bf16 v[30:33], v[224:227], v[174:177], v[30:33]
	v_mfma_f32_16x16x32_bf16 v[26:29], v[232:235], v[174:177], v[26:29]
	v_mfma_f32_16x16x32_bf16 v[14:17], v[224:227], v[196:199], v[14:17]
	v_mfma_f32_16x16x32_bf16 v[10:13], v[232:235], v[196:199], v[10:13]
	v_mfma_f32_16x16x32_bf16 v[6:9], v[224:227], v[204:207], v[6:9]
	v_mfma_f32_16x16x32_bf16 v[2:5], v[232:235], v[204:207], v[2:5]
	s_add_i32 s52, 0, 0x18000
	s_barrier
	s_add_u32 s22, s22, 0x20000
	s_addc_u32 s23, s23, 0
	s_mov_b32 m0, s29
	v_lshl_add_u64 v[208:209], s[22:23], 0, v[136:137]
	ds_read_b128 v[162:165], v144 offset:32768
	ds_read_b128 v[166:169], v144 offset:33792
	ds_read_b128 v[170:173], v144 offset:34816
	ds_read_b128 v[174:177], v144 offset:35840
	ds_read_b128 v[192:195], v144 offset:36864
	ds_read_b128 v[196:199], v144 offset:37888
	ds_read_b128 v[200:203], v144 offset:38912
	ds_read_b128 v[204:207], v144 offset:39936
	global_load_lds_dwordx4 v[208:209], off
	v_lshl_add_u64 v[208:209], s[22:23], 0, v[132:133]
	s_mov_b32 m0, s36
	s_nop 0
	global_load_lds_dwordx4 v[208:209], off
	s_waitcnt lgkmcnt(8)
	s_barrier
	s_waitcnt lgkmcnt(0)
	v_mfma_f32_16x16x32_bf16 v[126:129], v[146:149], v[162:165], v[126:129]
	v_mfma_f32_16x16x32_bf16 v[122:125], v[154:157], v[162:165], v[122:125]
	v_mfma_f32_16x16x32_bf16 v[118:121], v[146:149], v[170:173], v[118:121]
	v_mfma_f32_16x16x32_bf16 v[114:117], v[154:157], v[170:173], v[114:117]
	v_mfma_f32_16x16x32_bf16 v[102:105], v[146:149], v[192:195], v[102:105]
	v_mfma_f32_16x16x32_bf16 v[98:101], v[154:157], v[192:195], v[98:101]
	v_mfma_f32_16x16x32_bf16 v[86:89], v[146:149], v[200:203], v[86:89]
	v_mfma_f32_16x16x32_bf16 v[82:85], v[154:157], v[200:203], v[82:85]
	v_mfma_f32_16x16x32_bf16 v[126:129], v[150:153], v[166:169], v[126:129]
	v_mfma_f32_16x16x32_bf16 v[122:125], v[158:161], v[166:169], v[122:125]
	v_mfma_f32_16x16x32_bf16 v[118:121], v[150:153], v[174:177], v[118:121]
	v_mfma_f32_16x16x32_bf16 v[114:117], v[158:161], v[174:177], v[114:117]
	v_mfma_f32_16x16x32_bf16 v[102:105], v[150:153], v[196:199], v[102:105]
	v_mfma_f32_16x16x32_bf16 v[98:101], v[158:161], v[196:199], v[98:101]
	v_mfma_f32_16x16x32_bf16 v[86:89], v[150:153], v[204:207], v[86:89]
	v_mfma_f32_16x16x32_bf16 v[82:85], v[158:161], v[204:207], v[82:85]
	s_barrier
	s_add_i32 s53, 0, 0x1c000
	s_add_i32 s22, s52, s26
	v_add_u32_e32 v145, s53, v142
	v_lshl_add_u64 v[178:179], v[178:179], 0, s[78:79]
	s_mov_b32 m0, s22
	ds_read_b128 v[208:211], v145
	ds_read_b128 v[224:227], v145 offset:1024
	ds_read_b128 v[228:231], v145 offset:2048
	ds_read_b128 v[232:235], v145 offset:3072
	global_load_lds_dwordx4 v[178:179], off
	v_lshl_add_u64 v[178:179], v[212:213], 0, s[78:79]
	s_add_i32 m0, s22, 0x2000
	s_nop 0
	global_load_lds_dwordx4 v[178:179], off
	s_barrier
	s_waitcnt lgkmcnt(0)
	v_mfma_f32_16x16x32_bf16 v[110:113], v[208:211], v[162:165], v[110:113]
	v_mfma_f32_16x16x32_bf16 v[106:109], v[228:231], v[162:165], v[106:109]
	v_mfma_f32_16x16x32_bf16 v[94:97], v[208:211], v[170:173], v[94:97]
	v_mfma_f32_16x16x32_bf16 v[90:93], v[228:231], v[170:173], v[90:93]
	v_mfma_f32_16x16x32_bf16 v[78:81], v[208:211], v[192:195], v[78:81]
	v_mfma_f32_16x16x32_bf16 v[74:77], v[228:231], v[192:195], v[74:77]
	v_mfma_f32_16x16x32_bf16 v[70:73], v[208:211], v[200:203], v[70:73]
	v_mfma_f32_16x16x32_bf16 v[66:69], v[228:231], v[200:203], v[66:69]
	v_mfma_f32_16x16x32_bf16 v[110:113], v[224:227], v[166:169], v[110:113]
	v_mfma_f32_16x16x32_bf16 v[106:109], v[232:235], v[166:169], v[106:109]
	v_mfma_f32_16x16x32_bf16 v[94:97], v[224:227], v[174:177], v[94:97]
	v_mfma_f32_16x16x32_bf16 v[90:93], v[232:235], v[174:177], v[90:93]
	v_mfma_f32_16x16x32_bf16 v[78:81], v[224:227], v[196:199], v[78:81]
	v_mfma_f32_16x16x32_bf16 v[74:77], v[232:235], v[196:199], v[74:77]
	v_mfma_f32_16x16x32_bf16 v[70:73], v[224:227], v[204:207], v[70:73]
	v_mfma_f32_16x16x32_bf16 v[66:69], v[232:235], v[204:207], v[66:69]
	s_mov_b32 m0, s42
	v_lshl_add_u64 v[178:179], v[236:237], 0, s[78:79]
	s_barrier
	ds_read_b128 v[162:165], v144 offset:49152
	ds_read_b128 v[166:169], v144 offset:50176
	ds_read_b128 v[170:173], v144 offset:51200
	ds_read_b128 v[174:177], v144 offset:52224
	ds_read_b128 v[192:195], v144 offset:53248
	ds_read_b128 v[196:199], v144 offset:54272
	ds_read_b128 v[200:203], v144 offset:55296
	ds_read_b128 v[204:207], v144 offset:56320
	global_load_lds_dwordx4 v[178:179], off
	v_lshl_add_u64 v[178:179], v[238:239], 0, s[78:79]
	s_mov_b32 m0, s43
	s_nop 0
	global_load_lds_dwordx4 v[178:179], off
	s_waitcnt vmcnt(10)
	s_barrier
	s_waitcnt lgkmcnt(0)
	v_mfma_f32_16x16x32_bf16 v[62:65], v[146:149], v[162:165], v[62:65]
	v_mfma_f32_16x16x32_bf16 v[58:61], v[154:157], v[162:165], v[58:61]
	v_mfma_f32_16x16x32_bf16 v[54:57], v[146:149], v[170:173], v[54:57]
	v_mfma_f32_16x16x32_bf16 v[50:53], v[154:157], v[170:173], v[50:53]
	v_mfma_f32_16x16x32_bf16 v[38:41], v[146:149], v[192:195], v[38:41]
	v_mfma_f32_16x16x32_bf16 v[34:37], v[154:157], v[192:195], v[34:37]
	v_mfma_f32_16x16x32_bf16 v[22:25], v[146:149], v[200:203], v[22:25]
	v_mfma_f32_16x16x32_bf16 v[18:21], v[154:157], v[200:203], v[18:21]
	v_mfma_f32_16x16x32_bf16 v[62:65], v[150:153], v[166:169], v[62:65]
	v_mfma_f32_16x16x32_bf16 v[58:61], v[158:161], v[166:169], v[58:61]
	v_mfma_f32_16x16x32_bf16 v[54:57], v[150:153], v[174:177], v[54:57]
	v_mfma_f32_16x16x32_bf16 v[50:53], v[158:161], v[174:177], v[50:53]
	v_mfma_f32_16x16x32_bf16 v[38:41], v[150:153], v[196:199], v[38:41]
	v_mfma_f32_16x16x32_bf16 v[34:37], v[158:161], v[196:199], v[34:37]
	v_mfma_f32_16x16x32_bf16 v[22:25], v[150:153], v[204:207], v[22:25]
	v_mfma_f32_16x16x32_bf16 v[18:21], v[158:161], v[204:207], v[18:21]
	s_barrier
	s_add_u32 s22, s82, 0x20080
	s_addc_u32 s23, s83, 0
	s_add_i32 s52, s53, s26
	v_lshl_add_u64 v[146:147], s[22:23], 0, v[134:135]
	s_mov_b32 m0, s52
	s_nop 0
	global_load_lds_dwordx4 v[146:147], off
	v_lshl_add_u64 v[146:147], s[22:23], 0, v[130:131]
	s_add_i32 m0, s52, 0x2000
	s_nop 0
	global_load_lds_dwordx4 v[146:147], off
	v_add_u32_e32 v145, 0x10000, v142
	ds_read_b128 v[146:149], v145
	ds_read_b128 v[150:153], v145 offset:1024
	ds_read_b128 v[154:157], v145 offset:2048
	ds_read_b128 v[158:161], v145 offset:3072
	s_waitcnt vmcnt(6)
	s_barrier
	v_mfma_f32_16x16x32_bf16 v[46:49], v[208:211], v[162:165], v[46:49]
	v_mfma_f32_16x16x32_bf16 v[42:45], v[228:231], v[162:165], v[42:45]
	v_mfma_f32_16x16x32_bf16 v[30:33], v[208:211], v[170:173], v[30:33]
	v_mfma_f32_16x16x32_bf16 v[26:29], v[228:231], v[170:173], v[26:29]
	v_mfma_f32_16x16x32_bf16 v[14:17], v[208:211], v[192:195], v[14:17]
	v_mfma_f32_16x16x32_bf16 v[10:13], v[228:231], v[192:195], v[10:13]
	v_mfma_f32_16x16x32_bf16 v[6:9], v[208:211], v[200:203], v[6:9]
	v_mfma_f32_16x16x32_bf16 v[2:5], v[228:231], v[200:203], v[2:5]
	v_mfma_f32_16x16x32_bf16 v[46:49], v[224:227], v[166:169], v[46:49]
	v_mfma_f32_16x16x32_bf16 v[42:45], v[232:235], v[166:169], v[42:45]
	v_mfma_f32_16x16x32_bf16 v[30:33], v[224:227], v[174:177], v[30:33]
	v_mfma_f32_16x16x32_bf16 v[26:29], v[232:235], v[174:177], v[26:29]
	v_mfma_f32_16x16x32_bf16 v[14:17], v[224:227], v[196:199], v[14:17]
	v_mfma_f32_16x16x32_bf16 v[10:13], v[232:235], v[196:199], v[10:13]
	v_mfma_f32_16x16x32_bf16 v[6:9], v[224:227], v[204:207], v[6:9]
	v_mfma_f32_16x16x32_bf16 v[2:5], v[232:235], v[204:207], v[2:5]
	s_add_i32 s51, s51, 2
	s_add_u32 s20, s20, 0x100
	s_addc_u32 s21, s21, 0
	s_add_u32 s49, s49, 0x100
	s_addc_u32 s50, s50, 0
	s_cmp_gt_u32 s51, 5
	s_barrier
	s_cbranch_scc0 .LBB0_373
	s_waitcnt lgkmcnt(0)
	v_lshl_add_u32 v146, s46, 8, v1
	v_lshl_or_b32 v148, s45, 8, v143
	v_ashrrev_i32_e32 v147, 31, v146
	v_readlane_b32 s48, v254, 40
	v_ashrrev_i32_e32 v149, 31, v148
	v_lshlrev_b64 v[150:151], 14, v[146:147]
	v_readlane_b32 s62, v254, 54
	v_readlane_b32 s63, v254, 55
	v_lshlrev_b64 v[148:149], 1, v[148:149]
	s_mov_b32 s19, 0x200000
	v_lshl_add_u64 v[150:151], s[62:63], 0, v[150:151]
	v_lshl_add_u64 v[150:151], v[150:151], 0, v[148:149]
	s_mov_b64 s[20:21], 0x200000
	v_cvt_pk_bf16_f32 v62, v62, v63
	v_cvt_pk_bf16_f32 v63, v64, v65
	v_cvt_pk_bf16_f32 v64, v58, v59
	v_add_co_u32_e32 v58, vcc, s19, v150
	v_cvt_pk_bf16_f32 v70, v70, v71
	v_cvt_pk_bf16_f32 v71, v72, v73
	v_cvt_pk_bf16_f32 v72, v66, v67
	v_lshl_add_u64 v[66:67], v[150:151], 0, s[20:21]
	v_addc_co_u32_e32 v59, vcc, 0, v151, vcc
	v_cvt_pk_bf16_f32 v46, v46, v47
	v_cvt_pk_bf16_f32 v47, v48, v49
	v_cvt_pk_bf16_f32 v48, v42, v43
	v_cvt_pk_bf16_f32 v49, v44, v45
	s_mov_b32 s19, 0x240000
	v_cvt_pk_bf16_f32 v110, v110, v111
	v_cvt_pk_bf16_f32 v111, v112, v113
	v_cvt_pk_bf16_f32 v112, v106, v107
	v_or_b32_e32 v106, 16, v146
	global_store_dwordx4 v[66:67], v[46:49], off offset:256
	s_mov_b64 s[20:21], 0x240000
	v_ashrrev_i32_e32 v107, 31, v106
	v_add_co_u32_e32 v48, vcc, s19, v150
	v_cvt_pk_bf16_f32 v94, v94, v95
	v_cvt_pk_bf16_f32 v95, v96, v97
	v_cvt_pk_bf16_f32 v96, v90, v91
	v_or_b32_e32 v90, 32, v146
	v_lshl_add_u64 v[46:47], v[150:151], 0, s[20:21]
	v_addc_co_u32_e32 v49, vcc, 0, v151, vcc
	v_cvt_pk_bf16_f32 v30, v30, v31
	v_cvt_pk_bf16_f32 v31, v32, v33
	v_cvt_pk_bf16_f32 v32, v26, v27
	v_cvt_pk_bf16_f32 v33, v28, v29
	s_mov_b32 s19, 0x280000
	v_lshlrev_b64 v[106:107], 14, v[106:107]
	v_ashrrev_i32_e32 v91, 31, v90
	v_cvt_pk_bf16_f32 v78, v78, v79
	v_cvt_pk_bf16_f32 v79, v80, v81
	v_cvt_pk_bf16_f32 v80, v74, v75
	v_or_b32_e32 v74, 48, v146
	global_store_dwordx4 v[46:47], v[30:33], off offset:256
	s_mov_b64 s[20:21], 0x280000
	v_cvt_pk_bf16_f32 v113, v108, v109
	v_add_co_u32_e32 v32, vcc, s19, v150
	v_lshl_add_u64 v[106:107], s[62:63], 0, v[106:107]
	v_lshlrev_b64 v[90:91], 14, v[90:91]
	v_ashrrev_i32_e32 v75, 31, v74
	v_lshl_add_u64 v[30:31], v[150:151], 0, s[20:21]
	v_addc_co_u32_e32 v33, vcc, 0, v151, vcc
	v_cvt_pk_bf16_f32 v14, v14, v15
	v_cvt_pk_bf16_f32 v15, v16, v17
	v_cvt_pk_bf16_f32 v16, v10, v11
	v_cvt_pk_bf16_f32 v17, v12, v13
	s_mov_b32 s19, 0x2c0000
	global_store_dwordx4 v[150:151], v[110:113], off offset:256
	v_cvt_pk_bf16_f32 v97, v92, v93
	v_lshl_add_u64 v[90:91], s[62:63], 0, v[90:91]
	v_lshl_add_u64 v[110:111], v[106:107], 0, v[148:149]
	v_lshlrev_b64 v[74:75], 14, v[74:75]
	global_store_dwordx4 v[30:31], v[14:17], off offset:256
	global_store_dwordx4 v[110:111], v[94:97], off offset:256
	v_cvt_pk_bf16_f32 v81, v76, v77
	v_add_co_u32_e32 v16, vcc, s19, v150
	v_lshl_add_u64 v[94:95], v[90:91], 0, v[148:149]
	v_lshl_add_u64 v[74:75], s[62:63], 0, v[74:75]
	s_mov_b64 s[20:21], 0x2c0000
	v_addc_co_u32_e32 v17, vcc, 0, v151, vcc
	v_cvt_pk_bf16_f32 v126, v126, v127
	v_cvt_pk_bf16_f32 v127, v128, v129
	v_cvt_pk_bf16_f32 v128, v122, v123
	v_cvt_pk_bf16_f32 v129, v124, v125
	v_cvt_pk_bf16_f32 v106, v118, v119
	v_cvt_pk_bf16_f32 v107, v120, v121
	v_cvt_pk_bf16_f32 v108, v114, v115
	v_cvt_pk_bf16_f32 v109, v116, v117
	v_cvt_pk_bf16_f32 v90, v102, v103
	v_cvt_pk_bf16_f32 v91, v104, v105
	v_cvt_pk_bf16_f32 v92, v98, v99
	v_cvt_pk_bf16_f32 v93, v100, v101
	global_store_dwordx4 v[94:95], v[78:81], off offset:256
	v_cvt_pk_bf16_f32 v76, v82, v83
	v_cvt_pk_bf16_f32 v77, v84, v85
	v_lshl_add_u64 v[78:79], v[74:75], 0, v[148:149]
	v_cvt_pk_bf16_f32 v74, v86, v87
	v_cvt_pk_bf16_f32 v75, v88, v89
	v_cvt_pk_bf16_f32 v73, v68, v69
	v_cvt_pk_bf16_f32 v65, v60, v61
	v_cvt_pk_bf16_f32 v42, v54, v55
	v_cvt_pk_bf16_f32 v43, v56, v57
	v_cvt_pk_bf16_f32 v44, v50, v51
	v_cvt_pk_bf16_f32 v45, v52, v53
	v_cvt_pk_bf16_f32 v26, v38, v39
	v_cvt_pk_bf16_f32 v27, v40, v41
	v_cvt_pk_bf16_f32 v28, v34, v35
	v_cvt_pk_bf16_f32 v29, v36, v37
	v_lshl_add_u64 v[14:15], v[150:151], 0, s[20:21]
	v_cvt_pk_bf16_f32 v10, v22, v23
	v_cvt_pk_bf16_f32 v11, v24, v25
	v_cvt_pk_bf16_f32 v12, v18, v19
	v_cvt_pk_bf16_f32 v13, v20, v21
	v_cvt_pk_bf16_f32 v6, v6, v7
	v_cvt_pk_bf16_f32 v7, v8, v9
	v_cvt_pk_bf16_f32 v8, v2, v3
	v_cvt_pk_bf16_f32 v9, v4, v5
	s_and_b64 vcc, exec, s[0:1]
	s_mov_b32 s45, s18
	s_mov_b32 s46, s30
	s_mov_b64 s[22:23], s[80:81]
	s_mov_b64 s[20:21], s[38:39]
	s_mov_b32 s64, 0x800000
	s_movk_i32 s65, 0x1fff
	v_readlane_b32 s49, v254, 41
	v_readlane_b32 s50, v254, 42
	v_readlane_b32 s51, v254, 43
	v_readlane_b32 s52, v254, 44
	v_readlane_b32 s53, v254, 45
	v_readlane_b32 s54, v254, 46
	v_readlane_b32 s55, v254, 47
	v_readlane_b32 s56, v254, 48
	v_readlane_b32 s57, v254, 49
	v_readlane_b32 s58, v254, 50
	v_readlane_b32 s59, v254, 51
	v_readlane_b32 s60, v254, 52
	v_readlane_b32 s61, v254, 53
	global_store_dwordx4 v[150:151], v[126:129], off
	global_store_dwordx4 v[110:111], v[106:109], off
	global_store_dwordx4 v[94:95], v[90:93], off
	global_store_dwordx4 v[78:79], v[74:77], off
	global_store_dwordx4 v[78:79], v[70:73], off offset:256
	global_store_dwordx4 v[58:59], v[62:65], off
	global_store_dwordx4 v[48:49], v[42:45], off
	global_store_dwordx4 v[32:33], v[26:29], off
	global_store_dwordx4 v[16:17], v[10:13], off
	global_store_dwordx4 v[14:15], v[6:9], off offset:256
	s_cbranch_vccz .LBB0_366
	s_waitcnt vmcnt(0)
	v_readlane_b32 s44, v255, 30
	s_mov_b32 s66, s90
	s_cmpk_gt_u32 s25, 0xff
	v_readlane_b32 s45, v255, 31
	v_readlane_b32 s42, v255, 32
	s_cbranch_scc1 .LBB0_377
	s_barrier

.LBB0_386:
	s_add_u32 s20, s18, 0xfffe0080
	s_addc_u32 s21, s19, -1
	s_add_i32 s50, 0, 0x10000
	s_cmp_eq_u32 s49, 4
	s_cselect_b32 s23, s44, s21
	s_cselect_b32 s22, s45, s20
	s_cselect_b32 s21, s39, s48
	s_cselect_b32 s20, s46, s47
	v_lshl_add_u64 v[178:179], s[18:19], 0, v[146:147]
	s_add_i32 m0, s90, 0xc000
	ds_read_b128 v[162:165], v156
	ds_read_b128 v[166:169], v156 offset:1024
	ds_read_b128 v[170:173], v156 offset:2048
	ds_read_b128 v[174:177], v156 offset:3072
	ds_read_b128 v[192:195], v156 offset:4096
	ds_read_b128 v[196:199], v156 offset:5120
	ds_read_b128 v[200:203], v156 offset:6144
	ds_read_b128 v[204:207], v156 offset:7168
	global_load_lds_dwordx4 v[178:179], off
	v_lshl_add_u64 v[178:179], s[18:19], 0, v[148:149]
	s_add_i32 m0, s90, 0xe000
	s_nop 0
	global_load_lds_dwordx4 v[178:179], off
	s_waitcnt lgkmcnt(8)
	s_barrier
	s_waitcnt lgkmcnt(0)
	v_mfma_f32_16x16x32_bf16 v[126:129], v[130:133], v[162:165], v[126:129]
	v_mfma_f32_16x16x32_bf16 v[122:125], v[150:153], v[162:165], v[122:125]
	v_mfma_f32_16x16x32_bf16 v[118:121], v[130:133], v[170:173], v[118:121]
	v_mfma_f32_16x16x32_bf16 v[110:113], v[150:153], v[170:173], v[110:113]
	v_mfma_f32_16x16x32_bf16 v[102:105], v[130:133], v[192:195], v[102:105]
	v_mfma_f32_16x16x32_bf16 v[94:97], v[150:153], v[192:195], v[94:97]
	v_mfma_f32_16x16x32_bf16 v[86:89], v[130:133], v[200:203], v[86:89]
	v_mfma_f32_16x16x32_bf16 v[78:81], v[150:153], v[200:203], v[78:81]
	v_mfma_f32_16x16x32_bf16 v[126:129], v[134:137], v[166:169], v[126:129]
	v_mfma_f32_16x16x32_bf16 v[122:125], v[158:161], v[166:169], v[122:125]
	v_mfma_f32_16x16x32_bf16 v[118:121], v[134:137], v[174:177], v[118:121]
	v_mfma_f32_16x16x32_bf16 v[110:113], v[158:161], v[174:177], v[110:113]
	v_mfma_f32_16x16x32_bf16 v[102:105], v[134:137], v[196:199], v[102:105]
	v_mfma_f32_16x16x32_bf16 v[94:97], v[158:161], v[196:199], v[94:97]
	v_mfma_f32_16x16x32_bf16 v[86:89], v[134:137], v[204:207], v[86:89]
	v_mfma_f32_16x16x32_bf16 v[78:81], v[158:161], v[204:207], v[78:81]
	s_barrier
	s_add_i32 s52, 0, 0x14000
	s_add_i32 s50, s50, s36
	v_add_u32_e32 v157, s52, v154
	v_lshl_add_u64 v[178:179], s[20:21], 0, v[142:143]
	s_mov_b32 m0, s50
	ds_read_b128 v[208:211], v157
	ds_read_b128 v[224:227], v157 offset:1024
	ds_read_b128 v[228:231], v157 offset:2048
	ds_read_b128 v[232:235], v157 offset:3072
	global_load_lds_dwordx4 v[178:179], off
	v_lshl_add_u64 v[212:213], s[20:21], 0, v[138:139]
	s_add_i32 m0, s50, 0x2000
	s_nop 0
	global_load_lds_dwordx4 v[212:213], off
	s_barrier
	s_waitcnt lgkmcnt(0)
	v_mfma_f32_16x16x32_bf16 v[114:117], v[208:211], v[162:165], v[114:117]
	v_mfma_f32_16x16x32_bf16 v[106:109], v[228:231], v[162:165], v[106:109]
	v_mfma_f32_16x16x32_bf16 v[98:101], v[208:211], v[170:173], v[98:101]
	v_mfma_f32_16x16x32_bf16 v[90:93], v[228:231], v[170:173], v[90:93]
	v_mfma_f32_16x16x32_bf16 v[82:85], v[208:211], v[192:195], v[82:85]
	v_mfma_f32_16x16x32_bf16 v[74:77], v[228:231], v[192:195], v[74:77]
	v_mfma_f32_16x16x32_bf16 v[70:73], v[208:211], v[200:203], v[70:73]
	v_mfma_f32_16x16x32_bf16 v[66:69], v[228:231], v[200:203], v[66:69]
	v_mfma_f32_16x16x32_bf16 v[114:117], v[224:227], v[166:169], v[114:117]
	v_mfma_f32_16x16x32_bf16 v[106:109], v[232:235], v[166:169], v[106:109]
	v_mfma_f32_16x16x32_bf16 v[98:101], v[224:227], v[174:177], v[98:101]
	v_mfma_f32_16x16x32_bf16 v[90:93], v[232:235], v[174:177], v[90:93]
	v_mfma_f32_16x16x32_bf16 v[82:85], v[224:227], v[196:199], v[82:85]
	v_mfma_f32_16x16x32_bf16 v[74:77], v[232:235], v[196:199], v[74:77]
	v_mfma_f32_16x16x32_bf16 v[70:73], v[224:227], v[204:207], v[70:73]
	v_mfma_f32_16x16x32_bf16 v[66:69], v[232:235], v[204:207], v[66:69]
	s_mov_b32 m0, s90
	v_lshl_add_u64 v[236:237], s[22:23], 0, v[144:145]
	s_barrier
	ds_read_b128 v[162:165], v156 offset:16384
	ds_read_b128 v[166:169], v156 offset:17408
	ds_read_b128 v[170:173], v156 offset:18432
	ds_read_b128 v[174:177], v156 offset:19456
	ds_read_b128 v[192:195], v156 offset:20480
	ds_read_b128 v[196:199], v156 offset:21504
	ds_read_b128 v[200:203], v156 offset:22528
	ds_read_b128 v[204:207], v156 offset:23552
	global_load_lds_dwordx4 v[236:237], off
	v_lshl_add_u64 v[238:239], s[22:23], 0, v[140:141]
	s_mov_b32 m0, s91
	s_nop 0
	global_load_lds_dwordx4 v[238:239], off
	s_waitcnt vmcnt(10)
	s_barrier
	s_waitcnt lgkmcnt(0)
	v_mfma_f32_16x16x32_bf16 v[62:65], v[130:133], v[162:165], v[62:65]
	v_mfma_f32_16x16x32_bf16 v[58:61], v[150:153], v[162:165], v[58:61]
	v_mfma_f32_16x16x32_bf16 v[54:57], v[130:133], v[170:173], v[54:57]
	v_mfma_f32_16x16x32_bf16 v[46:49], v[150:153], v[170:173], v[46:49]
	v_mfma_f32_16x16x32_bf16 v[38:41], v[130:133], v[192:195], v[38:41]
	v_mfma_f32_16x16x32_bf16 v[30:33], v[150:153], v[192:195], v[30:33]
	v_mfma_f32_16x16x32_bf16 v[22:25], v[130:133], v[200:203], v[22:25]
	v_mfma_f32_16x16x32_bf16 v[14:17], v[150:153], v[200:203], v[14:17]
	v_mfma_f32_16x16x32_bf16 v[62:65], v[134:137], v[166:169], v[62:65]
	v_mfma_f32_16x16x32_bf16 v[58:61], v[158:161], v[166:169], v[58:61]
	v_mfma_f32_16x16x32_bf16 v[54:57], v[134:137], v[174:177], v[54:57]
	v_mfma_f32_16x16x32_bf16 v[46:49], v[158:161], v[174:177], v[46:49]
	v_mfma_f32_16x16x32_bf16 v[38:41], v[134:137], v[196:199], v[38:41]
	v_mfma_f32_16x16x32_bf16 v[30:33], v[158:161], v[196:199], v[30:33]
	v_mfma_f32_16x16x32_bf16 v[22:25], v[134:137], v[204:207], v[22:25]
	v_mfma_f32_16x16x32_bf16 v[14:17], v[158:161], v[204:207], v[14:17]
	s_barrier
	s_add_u32 s50, s20, 0x20000
	s_addc_u32 s51, s21, 0
	s_add_i32 s52, s52, s36
	v_lshl_add_u64 v[130:131], s[50:51], 0, v[142:143]
	s_mov_b32 m0, s52
	s_nop 0
	global_load_lds_dwordx4 v[130:131], off
	v_lshl_add_u64 v[130:131], s[50:51], 0, v[138:139]
	s_add_i32 m0, s52, 0x2000
	s_nop 0
	global_load_lds_dwordx4 v[130:131], off
	v_add_u32_e32 v157, 0x18000, v154
	ds_read_b128 v[130:133], v157
	ds_read_b128 v[134:137], v157 offset:1024
	ds_read_b128 v[150:153], v157 offset:2048
	ds_read_b128 v[158:161], v157 offset:3072
	s_waitcnt vmcnt(6)
	s_barrier
	v_mfma_f32_16x16x32_bf16 v[50:53], v[208:211], v[162:165], v[50:53]
	v_mfma_f32_16x16x32_bf16 v[42:45], v[228:231], v[162:165], v[42:45]
	v_mfma_f32_16x16x32_bf16 v[34:37], v[208:211], v[170:173], v[34:37]
	v_mfma_f32_16x16x32_bf16 v[26:29], v[228:231], v[170:173], v[26:29]
	v_mfma_f32_16x16x32_bf16 v[18:21], v[208:211], v[192:195], v[18:21]
	v_mfma_f32_16x16x32_bf16 v[10:13], v[228:231], v[192:195], v[10:13]
	v_mfma_f32_16x16x32_bf16 v[6:9], v[208:211], v[200:203], v[6:9]
	v_mfma_f32_16x16x32_bf16 v[2:5], v[228:231], v[200:203], v[2:5]
	v_mfma_f32_16x16x32_bf16 v[50:53], v[224:227], v[166:169], v[50:53]
	v_mfma_f32_16x16x32_bf16 v[42:45], v[232:235], v[166:169], v[42:45]
	v_mfma_f32_16x16x32_bf16 v[34:37], v[224:227], v[174:177], v[34:37]
	v_mfma_f32_16x16x32_bf16 v[26:29], v[232:235], v[174:177], v[26:29]
	v_mfma_f32_16x16x32_bf16 v[18:21], v[224:227], v[196:199], v[18:21]
	v_mfma_f32_16x16x32_bf16 v[10:13], v[232:235], v[196:199], v[10:13]
	v_mfma_f32_16x16x32_bf16 v[6:9], v[224:227], v[204:207], v[6:9]
	v_mfma_f32_16x16x32_bf16 v[2:5], v[232:235], v[204:207], v[2:5]
	s_add_i32 s50, 0, 0x18000
	s_barrier
	s_add_u32 s22, s22, 0x20000
	s_addc_u32 s23, s23, 0
	s_mov_b32 m0, s42
	v_lshl_add_u64 v[208:209], s[22:23], 0, v[144:145]
	ds_read_b128 v[162:165], v156 offset:32768
	ds_read_b128 v[166:169], v156 offset:33792
	ds_read_b128 v[170:173], v156 offset:34816
	ds_read_b128 v[174:177], v156 offset:35840
	ds_read_b128 v[192:195], v156 offset:36864
	ds_read_b128 v[196:199], v156 offset:37888
	ds_read_b128 v[200:203], v156 offset:38912
	ds_read_b128 v[204:207], v156 offset:39936
	global_load_lds_dwordx4 v[208:209], off
	v_lshl_add_u64 v[208:209], s[22:23], 0, v[140:141]
	s_mov_b32 m0, s43
	s_nop 0
	global_load_lds_dwordx4 v[208:209], off
	s_waitcnt lgkmcnt(8)
	s_barrier
	s_waitcnt lgkmcnt(0)
	v_mfma_f32_16x16x32_bf16 v[126:129], v[130:133], v[162:165], v[126:129]
	v_mfma_f32_16x16x32_bf16 v[122:125], v[150:153], v[162:165], v[122:125]
	v_mfma_f32_16x16x32_bf16 v[118:121], v[130:133], v[170:173], v[118:121]
	v_mfma_f32_16x16x32_bf16 v[110:113], v[150:153], v[170:173], v[110:113]
	v_mfma_f32_16x16x32_bf16 v[102:105], v[130:133], v[192:195], v[102:105]
	v_mfma_f32_16x16x32_bf16 v[94:97], v[150:153], v[192:195], v[94:97]
	v_mfma_f32_16x16x32_bf16 v[86:89], v[130:133], v[200:203], v[86:89]
	v_mfma_f32_16x16x32_bf16 v[78:81], v[150:153], v[200:203], v[78:81]
	v_mfma_f32_16x16x32_bf16 v[126:129], v[134:137], v[166:169], v[126:129]
	v_mfma_f32_16x16x32_bf16 v[122:125], v[158:161], v[166:169], v[122:125]
	v_mfma_f32_16x16x32_bf16 v[118:121], v[134:137], v[174:177], v[118:121]
	v_mfma_f32_16x16x32_bf16 v[110:113], v[158:161], v[174:177], v[110:113]
	v_mfma_f32_16x16x32_bf16 v[102:105], v[134:137], v[196:199], v[102:105]
	v_mfma_f32_16x16x32_bf16 v[94:97], v[158:161], v[196:199], v[94:97]
	v_mfma_f32_16x16x32_bf16 v[86:89], v[134:137], v[204:207], v[86:89]
	v_mfma_f32_16x16x32_bf16 v[78:81], v[158:161], v[204:207], v[78:81]
	s_barrier
	s_add_i32 s22, 0, 0x1c000
	s_add_i32 s23, s50, s36
	v_add_u32_e32 v157, s22, v154
	v_lshl_add_u64 v[178:179], v[178:179], 0, s[78:79]
	s_mov_b32 m0, s23
	ds_read_b128 v[208:211], v157
	ds_read_b128 v[224:227], v157 offset:1024
	ds_read_b128 v[228:231], v157 offset:2048
	ds_read_b128 v[232:235], v157 offset:3072
	global_load_lds_dwordx4 v[178:179], off
	v_lshl_add_u64 v[178:179], v[212:213], 0, s[78:79]
	s_add_i32 m0, s23, 0x2000
	s_nop 0
	global_load_lds_dwordx4 v[178:179], off
	s_barrier
	s_waitcnt lgkmcnt(0)
	v_mfma_f32_16x16x32_bf16 v[114:117], v[208:211], v[162:165], v[114:117]
	v_mfma_f32_16x16x32_bf16 v[106:109], v[228:231], v[162:165], v[106:109]
	v_mfma_f32_16x16x32_bf16 v[98:101], v[208:211], v[170:173], v[98:101]
	v_mfma_f32_16x16x32_bf16 v[90:93], v[228:231], v[170:173], v[90:93]
	v_mfma_f32_16x16x32_bf16 v[82:85], v[208:211], v[192:195], v[82:85]
	v_mfma_f32_16x16x32_bf16 v[74:77], v[228:231], v[192:195], v[74:77]
	v_mfma_f32_16x16x32_bf16 v[70:73], v[208:211], v[200:203], v[70:73]
	v_mfma_f32_16x16x32_bf16 v[66:69], v[228:231], v[200:203], v[66:69]
	v_mfma_f32_16x16x32_bf16 v[114:117], v[224:227], v[166:169], v[114:117]
	v_mfma_f32_16x16x32_bf16 v[106:109], v[232:235], v[166:169], v[106:109]
	v_mfma_f32_16x16x32_bf16 v[98:101], v[224:227], v[174:177], v[98:101]
	v_mfma_f32_16x16x32_bf16 v[90:93], v[232:235], v[174:177], v[90:93]
	v_mfma_f32_16x16x32_bf16 v[82:85], v[224:227], v[196:199], v[82:85]
	v_mfma_f32_16x16x32_bf16 v[74:77], v[232:235], v[196:199], v[74:77]
	v_mfma_f32_16x16x32_bf16 v[70:73], v[224:227], v[204:207], v[70:73]
	v_mfma_f32_16x16x32_bf16 v[66:69], v[232:235], v[204:207], v[66:69]
	s_mov_b32 m0, s25
	v_lshl_add_u64 v[178:179], v[236:237], 0, s[78:79]
	s_barrier
	ds_read_b128 v[162:165], v156 offset:49152
	ds_read_b128 v[166:169], v156 offset:50176
	ds_read_b128 v[170:173], v156 offset:51200
	ds_read_b128 v[174:177], v156 offset:52224
	ds_read_b128 v[192:195], v156 offset:53248
	ds_read_b128 v[196:199], v156 offset:54272
	ds_read_b128 v[200:203], v156 offset:55296
	ds_read_b128 v[204:207], v156 offset:56320
	global_load_lds_dwordx4 v[178:179], off
	v_lshl_add_u64 v[178:179], v[238:239], 0, s[78:79]
	s_mov_b32 m0, s26
	s_nop 0
	global_load_lds_dwordx4 v[178:179], off
	s_waitcnt vmcnt(10)
	s_barrier
	s_waitcnt lgkmcnt(0)
	v_mfma_f32_16x16x32_bf16 v[62:65], v[130:133], v[162:165], v[62:65]
	v_mfma_f32_16x16x32_bf16 v[58:61], v[150:153], v[162:165], v[58:61]
	v_mfma_f32_16x16x32_bf16 v[54:57], v[130:133], v[170:173], v[54:57]
	v_mfma_f32_16x16x32_bf16 v[46:49], v[150:153], v[170:173], v[46:49]
	v_mfma_f32_16x16x32_bf16 v[38:41], v[130:133], v[192:195], v[38:41]
	v_mfma_f32_16x16x32_bf16 v[30:33], v[150:153], v[192:195], v[30:33]
	v_mfma_f32_16x16x32_bf16 v[22:25], v[130:133], v[200:203], v[22:25]
	v_mfma_f32_16x16x32_bf16 v[14:17], v[150:153], v[200:203], v[14:17]
	v_mfma_f32_16x16x32_bf16 v[62:65], v[134:137], v[166:169], v[62:65]
	v_mfma_f32_16x16x32_bf16 v[58:61], v[158:161], v[166:169], v[58:61]
	v_mfma_f32_16x16x32_bf16 v[54:57], v[134:137], v[174:177], v[54:57]
	v_mfma_f32_16x16x32_bf16 v[46:49], v[158:161], v[174:177], v[46:49]
	v_mfma_f32_16x16x32_bf16 v[38:41], v[134:137], v[196:199], v[38:41]
	v_mfma_f32_16x16x32_bf16 v[30:33], v[158:161], v[196:199], v[30:33]
	v_mfma_f32_16x16x32_bf16 v[22:25], v[134:137], v[204:207], v[22:25]
	v_mfma_f32_16x16x32_bf16 v[14:17], v[158:161], v[204:207], v[14:17]
	s_barrier
	s_add_u32 s20, s20, 0x20080
	s_addc_u32 s21, s21, 0
	s_add_i32 s22, s22, s36
	v_lshl_add_u64 v[130:131], s[20:21], 0, v[142:143]
	s_mov_b32 m0, s22
	s_nop 0
	global_load_lds_dwordx4 v[130:131], off
	v_lshl_add_u64 v[130:131], s[20:21], 0, v[138:139]
	s_add_i32 m0, s22, 0x2000
	s_nop 0
	global_load_lds_dwordx4 v[130:131], off
	v_add_u32_e32 v157, 0x10000, v154
	ds_read_b128 v[130:133], v157
	ds_read_b128 v[134:137], v157 offset:1024
	ds_read_b128 v[150:153], v157 offset:2048
	ds_read_b128 v[158:161], v157 offset:3072
	s_waitcnt vmcnt(6)
	s_barrier
	v_mfma_f32_16x16x32_bf16 v[50:53], v[208:211], v[162:165], v[50:53]
	v_mfma_f32_16x16x32_bf16 v[42:45], v[228:231], v[162:165], v[42:45]
	v_mfma_f32_16x16x32_bf16 v[34:37], v[208:211], v[170:173], v[34:37]
	v_mfma_f32_16x16x32_bf16 v[26:29], v[228:231], v[170:173], v[26:29]
	v_mfma_f32_16x16x32_bf16 v[18:21], v[208:211], v[192:195], v[18:21]
	v_mfma_f32_16x16x32_bf16 v[10:13], v[228:231], v[192:195], v[10:13]
	v_mfma_f32_16x16x32_bf16 v[6:9], v[208:211], v[200:203], v[6:9]
	v_mfma_f32_16x16x32_bf16 v[2:5], v[228:231], v[200:203], v[2:5]
	v_mfma_f32_16x16x32_bf16 v[50:53], v[224:227], v[166:169], v[50:53]
	v_mfma_f32_16x16x32_bf16 v[42:45], v[232:235], v[166:169], v[42:45]
	v_mfma_f32_16x16x32_bf16 v[34:37], v[224:227], v[174:177], v[34:37]
	v_mfma_f32_16x16x32_bf16 v[26:29], v[232:235], v[174:177], v[26:29]
	v_mfma_f32_16x16x32_bf16 v[18:21], v[224:227], v[196:199], v[18:21]
	v_mfma_f32_16x16x32_bf16 v[10:13], v[232:235], v[196:199], v[10:13]
	v_mfma_f32_16x16x32_bf16 v[6:9], v[224:227], v[204:207], v[6:9]
	v_mfma_f32_16x16x32_bf16 v[2:5], v[232:235], v[204:207], v[2:5]
	s_add_i32 s49, s49, 2
	s_add_u32 s18, s18, 0x100
	s_addc_u32 s19, s19, 0
	s_add_u32 s47, s47, 0x100
	s_addc_u32 s48, s48, 0
	s_cmp_gt_u32 s49, 5
	s_barrier
	s_cbranch_scc0 .LBB0_386
	s_waitcnt lgkmcnt(0)
	v_lshl_add_u32 v164, s29, 8, v1
	v_lshl_or_b32 v150, s28, 8, v155
	s_mov_b64 s[18:19], -1
	s_cmp_lt_i32 s28, 8
	v_or_b32_e32 v163, 16, v164
	v_or_b32_e32 v162, 32, v164
	v_or_b32_e32 v161, 48, v164
	v_add_u32_e32 v160, 0x80, v164
	v_add_u32_e32 v159, 0x90, v164
	v_add_u32_e32 v158, 0xa0, v164
	v_add_u32_e32 v157, 0xb0, v164
	s_cbranch_scc1 .LBB0_389
	v_lshlrev_b32_e32 v130, 7, v164
	v_readlane_b32 s4, v255, 4
	v_and_b32_e32 v132, 0x3e780, v130
	v_mov_b32_e32 v133, v0
	v_readlane_b32 s5, v255, 5
	v_readlane_b32 s6, v255, 6
	v_readlane_b32 s7, v255, 7
	v_lshlrev_b32_e32 v130, 1, v150
	v_lshl_add_u64 v[134:135], s[4:5], 0, v[132:133]
	v_and_b32_e32 v130, 0x70, v130
	v_mov_b32_e32 v131, v0
	v_lshl_add_u64 v[132:133], s[6:7], 0, v[132:133]
	v_lshl_add_u64 v[152:153], v[132:133], 0, v[130:131]
	v_lshl_add_u64 v[136:137], v[134:135], 0, v[130:131]
	global_load_dwordx4 v[170:173], v[152:153], off
	global_load_dwordx4 v[166:169], v[136:137], off
	v_readlane_b32 s8, v255, 8
	v_readlane_b32 s9, v255, 9
	v_mov_b32_e32 v151, v0
	v_lshlrev_b64 v[134:135], 1, v[150:151]
	v_mov_b64_e32 v[132:133], s[8:9]
	v_mad_i64_i32 v[174:175], s[18:19], v164, s24, v[132:133]
	v_lshl_add_u64 v[174:175], v[174:175], 0, v[134:135]
	v_readlane_b32 s10, v255, 10
	v_readlane_b32 s11, v255, 11
	s_waitcnt vmcnt(0)
	v_pk_mul_f32 v[172:173], v[172:173], s[86:87] op_sel_hi:[1,0]
	v_pk_mul_f32 v[170:171], v[170:171], s[86:87] op_sel_hi:[1,0]
	v_pk_mul_f32 v[168:169], v[168:169], s[86:87] op_sel_hi:[1,0]
	v_pk_mul_f32 v[166:167], v[166:167], s[86:87] op_sel_hi:[1,0]
	v_pk_mul_f32 v[176:177], v[124:125], v[172:173]
	v_pk_mul_f32 v[178:179], v[122:123], v[170:171]
	v_pk_mul_f32 v[172:173], v[128:129], v[172:173]
	v_pk_mul_f32 v[170:171], v[126:127], v[170:171]
	v_pk_fma_f32 v[176:177], v[128:129], v[168:169], v[176:177] neg_lo:[0,0,1] neg_hi:[0,0,1]
	v_pk_fma_f32 v[178:179], v[126:127], v[166:167], v[178:179] neg_lo:[0,0,1] neg_hi:[0,0,1]
	v_pk_fma_f32 v[172:173], v[124:125], v[168:169], v[172:173]
	v_pk_fma_f32 v[168:169], v[122:123], v[166:167], v[170:171]
	v_cvt_pk_bf16_f32 v166, v178, v179
	v_cvt_pk_bf16_f32 v167, v176, v177
	v_cvt_pk_bf16_f32 v168, v168, v169
	v_cvt_pk_bf16_f32 v169, v172, v173
	global_store_dwordx4 v[174:175], v[166:169], off
	global_load_dwordx4 v[166:169], v[136:137], off
	s_nop 0
	global_load_dwordx4 v[170:173], v[152:153], off
	v_lshlrev_b32_e32 v136, 7, v163
	v_mov_b32_e32 v137, v0
	v_and_b32_e32 v136, 0x3ef80, v136
	v_lshl_add_u64 v[152:153], s[4:5], 0, v[136:137]
	v_lshl_add_u64 v[136:137], s[6:7], 0, v[136:137]
	v_lshl_add_u64 v[136:137], v[136:137], 0, v[130:131]
	v_lshl_add_u64 v[152:153], v[152:153], 0, v[130:131]
	s_waitcnt vmcnt(0)
	v_pk_mul_f32 v[168:169], v[168:169], s[86:87] op_sel_hi:[1,0]
	v_pk_mul_f32 v[172:173], v[172:173], s[86:87] op_sel_hi:[1,0]
	v_pk_mul_f32 v[170:171], v[170:171], s[86:87] op_sel_hi:[1,0]
	v_pk_mul_f32 v[166:167], v[166:167], s[86:87] op_sel_hi:[1,0]
	v_pk_mul_f32 v[176:177], v[108:109], v[172:173]
	v_pk_mul_f32 v[178:179], v[106:107], v[170:171]
	v_pk_mul_f32 v[172:173], v[116:117], v[172:173]
	v_pk_mul_f32 v[170:171], v[114:115], v[170:171]
	v_pk_fma_f32 v[176:177], v[116:117], v[168:169], v[176:177] neg_lo:[0,0,1] neg_hi:[0,0,1]
	v_pk_fma_f32 v[178:179], v[114:115], v[166:167], v[178:179] neg_lo:[0,0,1] neg_hi:[0,0,1]
	v_pk_fma_f32 v[172:173], v[108:109], v[168:169], v[172:173]
	v_pk_fma_f32 v[168:169], v[106:107], v[166:167], v[170:171]
	v_cvt_pk_bf16_f32 v166, v178, v179
	v_cvt_pk_bf16_f32 v167, v176, v177
	v_cvt_pk_bf16_f32 v168, v168, v169
	v_cvt_pk_bf16_f32 v169, v172, v173
	global_store_dwordx4 v[174:175], v[166:169], off offset:256
	global_load_dwordx4 v[170:173], v[136:137], off
	v_mad_i64_i32 v[174:175], s[18:19], v163, s24, v[132:133]
	global_load_dwordx4 v[166:169], v[152:153], off
	v_lshl_add_u64 v[174:175], v[174:175], 0, v[134:135]
	s_waitcnt vmcnt(0)
	v_pk_mul_f32 v[172:173], v[172:173], s[86:87] op_sel_hi:[1,0]
	v_pk_mul_f32 v[170:171], v[170:171], s[86:87] op_sel_hi:[1,0]
	v_pk_mul_f32 v[176:177], v[112:113], v[172:173]
	v_pk_mul_f32 v[168:169], v[168:169], s[86:87] op_sel_hi:[1,0]
	v_pk_mul_f32 v[166:167], v[166:167], s[86:87] op_sel_hi:[1,0]
	v_pk_mul_f32 v[178:179], v[110:111], v[170:171]
	v_pk_mul_f32 v[172:173], v[120:121], v[172:173]
	v_pk_mul_f32 v[170:171], v[118:119], v[170:171]
	v_pk_fma_f32 v[176:177], v[120:121], v[168:169], v[176:177] neg_lo:[0,0,1] neg_hi:[0,0,1]
	v_pk_fma_f32 v[178:179], v[118:119], v[166:167], v[178:179] neg_lo:[0,0,1] neg_hi:[0,0,1]
	v_pk_fma_f32 v[172:173], v[112:113], v[168:169], v[172:173]
	v_pk_fma_f32 v[168:169], v[110:111], v[166:167], v[170:171]
	v_cvt_pk_bf16_f32 v166, v178, v179
	v_cvt_pk_bf16_f32 v167, v176, v177
	v_cvt_pk_bf16_f32 v168, v168, v169
	v_cvt_pk_bf16_f32 v169, v172, v173
	global_store_dwordx4 v[174:175], v[166:169], off
	global_load_dwordx4 v[166:169], v[152:153], off
	s_nop 0
	global_load_dwordx4 v[170:173], v[136:137], off
	v_lshlrev_b32_e32 v136, 7, v162
	v_mov_b32_e32 v137, v0
	v_and_b32_e32 v136, 0x3f780, v136
	v_lshl_add_u64 v[152:153], s[4:5], 0, v[136:137]
	v_lshl_add_u64 v[136:137], s[6:7], 0, v[136:137]
	v_lshl_add_u64 v[136:137], v[136:137], 0, v[130:131]
	v_lshl_add_u64 v[152:153], v[152:153], 0, v[130:131]
	s_waitcnt vmcnt(0)
	v_pk_mul_f32 v[168:169], v[168:169], s[86:87] op_sel_hi:[1,0]
	v_pk_mul_f32 v[172:173], v[172:173], s[86:87] op_sel_hi:[1,0]
	v_pk_mul_f32 v[170:171], v[170:171], s[86:87] op_sel_hi:[1,0]
	v_pk_mul_f32 v[166:167], v[166:167], s[86:87] op_sel_hi:[1,0]
	v_pk_mul_f32 v[176:177], v[92:93], v[172:173]
	v_pk_mul_f32 v[178:179], v[90:91], v[170:171]
	v_pk_mul_f32 v[172:173], v[100:101], v[172:173]
	v_pk_mul_f32 v[170:171], v[98:99], v[170:171]
	v_pk_fma_f32 v[176:177], v[100:101], v[168:169], v[176:177] neg_lo:[0,0,1] neg_hi:[0,0,1]
	v_pk_fma_f32 v[178:179], v[98:99], v[166:167], v[178:179] neg_lo:[0,0,1] neg_hi:[0,0,1]
	v_pk_fma_f32 v[172:173], v[92:93], v[168:169], v[172:173]
	v_pk_fma_f32 v[168:169], v[90:91], v[166:167], v[170:171]
	v_cvt_pk_bf16_f32 v166, v178, v179
	v_cvt_pk_bf16_f32 v167, v176, v177
	v_cvt_pk_bf16_f32 v168, v168, v169
	v_cvt_pk_bf16_f32 v169, v172, v173
	global_store_dwordx4 v[174:175], v[166:169], off offset:256
	global_load_dwordx4 v[170:173], v[136:137], off
	v_mad_i64_i32 v[174:175], s[18:19], v162, s24, v[132:133]
	global_load_dwordx4 v[166:169], v[152:153], off
	v_lshl_add_u64 v[174:175], v[174:175], 0, v[134:135]
	s_waitcnt vmcnt(0)
	v_pk_mul_f32 v[172:173], v[172:173], s[86:87] op_sel_hi:[1,0]
	v_pk_mul_f32 v[170:171], v[170:171], s[86:87] op_sel_hi:[1,0]
	v_pk_mul_f32 v[176:177], v[96:97], v[172:173]
	v_pk_mul_f32 v[168:169], v[168:169], s[86:87] op_sel_hi:[1,0]
	v_pk_mul_f32 v[166:167], v[166:167], s[86:87] op_sel_hi:[1,0]
	v_pk_mul_f32 v[178:179], v[94:95], v[170:171]
	v_pk_mul_f32 v[172:173], v[104:105], v[172:173]
	v_pk_mul_f32 v[170:171], v[102:103], v[170:171]
	v_pk_fma_f32 v[176:177], v[104:105], v[168:169], v[176:177] neg_lo:[0,0,1] neg_hi:[0,0,1]
	v_pk_fma_f32 v[178:179], v[102:103], v[166:167], v[178:179] neg_lo:[0,0,1] neg_hi:[0,0,1]
	v_pk_fma_f32 v[172:173], v[96:97], v[168:169], v[172:173]
	v_pk_fma_f32 v[168:169], v[94:95], v[166:167], v[170:171]
	v_cvt_pk_bf16_f32 v166, v178, v179
	v_cvt_pk_bf16_f32 v167, v176, v177
	v_cvt_pk_bf16_f32 v168, v168, v169
	v_cvt_pk_bf16_f32 v169, v172, v173
	global_store_dwordx4 v[174:175], v[166:169], off
	global_load_dwordx4 v[166:169], v[152:153], off
	s_nop 0
	global_load_dwordx4 v[170:173], v[136:137], off
	v_lshlrev_b32_e32 v136, 7, v161
	v_mov_b32_e32 v137, v0
	v_and_b32_e32 v136, 0x3ff80, v136
	v_lshl_add_u64 v[152:153], s[4:5], 0, v[136:137]
	v_lshl_add_u64 v[136:137], s[6:7], 0, v[136:137]
	v_lshl_add_u64 v[136:137], v[136:137], 0, v[130:131]
	v_lshl_add_u64 v[152:153], v[152:153], 0, v[130:131]
	s_waitcnt vmcnt(0)
	v_pk_mul_f32 v[168:169], v[168:169], s[86:87] op_sel_hi:[1,0]
	v_pk_mul_f32 v[172:173], v[172:173], s[86:87] op_sel_hi:[1,0]
	v_pk_mul_f32 v[170:171], v[170:171], s[86:87] op_sel_hi:[1,0]
	v_pk_mul_f32 v[166:167], v[166:167], s[86:87] op_sel_hi:[1,0]
	v_pk_mul_f32 v[176:177], v[76:77], v[172:173]
	v_pk_mul_f32 v[178:179], v[74:75], v[170:171]
	v_pk_mul_f32 v[172:173], v[84:85], v[172:173]
	v_pk_mul_f32 v[170:171], v[82:83], v[170:171]
	v_pk_fma_f32 v[176:177], v[84:85], v[168:169], v[176:177] neg_lo:[0,0,1] neg_hi:[0,0,1]
	v_pk_fma_f32 v[178:179], v[82:83], v[166:167], v[178:179] neg_lo:[0,0,1] neg_hi:[0,0,1]
	v_pk_fma_f32 v[172:173], v[76:77], v[168:169], v[172:173]
	v_pk_fma_f32 v[168:169], v[74:75], v[166:167], v[170:171]
	v_cvt_pk_bf16_f32 v166, v178, v179
	v_cvt_pk_bf16_f32 v167, v176, v177
	v_cvt_pk_bf16_f32 v168, v168, v169
	v_cvt_pk_bf16_f32 v169, v172, v173
	global_store_dwordx4 v[174:175], v[166:169], off offset:256
	global_load_dwordx4 v[170:173], v[136:137], off
	v_mad_i64_i32 v[174:175], s[18:19], v161, s24, v[132:133]
	global_load_dwordx4 v[166:169], v[152:153], off
	v_lshl_add_u64 v[174:175], v[174:175], 0, v[134:135]
	s_waitcnt vmcnt(0)
	v_pk_mul_f32 v[172:173], v[172:173], s[86:87] op_sel_hi:[1,0]
	v_pk_mul_f32 v[170:171], v[170:171], s[86:87] op_sel_hi:[1,0]
	v_pk_mul_f32 v[176:177], v[80:81], v[172:173]
	v_pk_mul_f32 v[168:169], v[168:169], s[86:87] op_sel_hi:[1,0]
	v_pk_mul_f32 v[166:167], v[166:167], s[86:87] op_sel_hi:[1,0]
	v_pk_mul_f32 v[178:179], v[78:79], v[170:171]
	v_pk_mul_f32 v[172:173], v[88:89], v[172:173]
	v_pk_mul_f32 v[170:171], v[86:87], v[170:171]
	v_pk_fma_f32 v[176:177], v[88:89], v[168:169], v[176:177] neg_lo:[0,0,1] neg_hi:[0,0,1]
	v_pk_fma_f32 v[178:179], v[86:87], v[166:167], v[178:179] neg_lo:[0,0,1] neg_hi:[0,0,1]
	v_pk_fma_f32 v[172:173], v[80:81], v[168:169], v[172:173]
	v_pk_fma_f32 v[168:169], v[78:79], v[166:167], v[170:171]
	v_cvt_pk_bf16_f32 v166, v178, v179
	v_cvt_pk_bf16_f32 v167, v176, v177
	v_cvt_pk_bf16_f32 v168, v168, v169
	v_cvt_pk_bf16_f32 v169, v172, v173
	global_store_dwordx4 v[174:175], v[166:169], off
	global_load_dwordx4 v[166:169], v[152:153], off
	s_nop 0
	global_load_dwordx4 v[170:173], v[136:137], off
	v_lshlrev_b32_e32 v136, 7, v160
	v_mov_b32_e32 v137, v0
	v_and_b32_e32 v136, 0x3e780, v136
	v_lshl_add_u64 v[152:153], s[4:5], 0, v[136:137]
	v_lshl_add_u64 v[136:137], s[6:7], 0, v[136:137]
	v_lshl_add_u64 v[136:137], v[136:137], 0, v[130:131]
	v_lshl_add_u64 v[152:153], v[152:153], 0, v[130:131]
	s_waitcnt vmcnt(0)
	v_pk_mul_f32 v[168:169], v[168:169], s[86:87] op_sel_hi:[1,0]
	v_pk_mul_f32 v[172:173], v[172:173], s[86:87] op_sel_hi:[1,0]
	v_pk_mul_f32 v[170:171], v[170:171], s[86:87] op_sel_hi:[1,0]
	v_pk_mul_f32 v[166:167], v[166:167], s[86:87] op_sel_hi:[1,0]
	v_pk_mul_f32 v[176:177], v[68:69], v[172:173]
	v_pk_mul_f32 v[178:179], v[66:67], v[170:171]
	v_pk_mul_f32 v[172:173], v[72:73], v[172:173]
	v_pk_mul_f32 v[170:171], v[70:71], v[170:171]
	v_pk_fma_f32 v[176:177], v[72:73], v[168:169], v[176:177] neg_lo:[0,0,1] neg_hi:[0,0,1]
	v_pk_fma_f32 v[178:179], v[70:71], v[166:167], v[178:179] neg_lo:[0,0,1] neg_hi:[0,0,1]
	v_pk_fma_f32 v[172:173], v[68:69], v[168:169], v[172:173]
	v_pk_fma_f32 v[168:169], v[66:67], v[166:167], v[170:171]
	v_cvt_pk_bf16_f32 v166, v178, v179
	v_cvt_pk_bf16_f32 v167, v176, v177
	v_cvt_pk_bf16_f32 v168, v168, v169
	v_cvt_pk_bf16_f32 v169, v172, v173
	global_store_dwordx4 v[174:175], v[166:169], off offset:256
	global_load_dwordx4 v[170:173], v[136:137], off
	v_mad_i64_i32 v[174:175], s[18:19], v160, s24, v[132:133]
	global_load_dwordx4 v[166:169], v[152:153], off
	v_lshl_add_u64 v[174:175], v[174:175], 0, v[134:135]
	s_waitcnt vmcnt(0)
	v_pk_mul_f32 v[172:173], v[172:173], s[86:87] op_sel_hi:[1,0]
	v_pk_mul_f32 v[170:171], v[170:171], s[86:87] op_sel_hi:[1,0]
	v_pk_mul_f32 v[176:177], v[60:61], v[172:173]
	v_pk_mul_f32 v[168:169], v[168:169], s[86:87] op_sel_hi:[1,0]
	v_pk_mul_f32 v[166:167], v[166:167], s[86:87] op_sel_hi:[1,0]
	v_pk_mul_f32 v[178:179], v[58:59], v[170:171]
	v_pk_mul_f32 v[172:173], v[64:65], v[172:173]
	v_pk_mul_f32 v[170:171], v[62:63], v[170:171]
	v_pk_fma_f32 v[176:177], v[64:65], v[168:169], v[176:177] neg_lo:[0,0,1] neg_hi:[0,0,1]
	v_pk_fma_f32 v[178:179], v[62:63], v[166:167], v[178:179] neg_lo:[0,0,1] neg_hi:[0,0,1]
	v_pk_fma_f32 v[172:173], v[60:61], v[168:169], v[172:173]
	v_pk_fma_f32 v[168:169], v[58:59], v[166:167], v[170:171]
	v_cvt_pk_bf16_f32 v166, v178, v179
	v_cvt_pk_bf16_f32 v167, v176, v177
	v_cvt_pk_bf16_f32 v168, v168, v169
	v_cvt_pk_bf16_f32 v169, v172, v173
	global_store_dwordx4 v[174:175], v[166:169], off
	global_load_dwordx4 v[166:169], v[152:153], off
	s_nop 0
	global_load_dwordx4 v[170:173], v[136:137], off
	v_lshlrev_b32_e32 v136, 7, v159
	v_mov_b32_e32 v137, v0
	v_and_b32_e32 v136, 0x3ef80, v136
	v_lshl_add_u64 v[152:153], s[4:5], 0, v[136:137]
	v_lshl_add_u64 v[136:137], s[6:7], 0, v[136:137]
	v_lshl_add_u64 v[136:137], v[136:137], 0, v[130:131]
	v_lshl_add_u64 v[152:153], v[152:153], 0, v[130:131]
	s_waitcnt vmcnt(0)
	v_pk_mul_f32 v[168:169], v[168:169], s[86:87] op_sel_hi:[1,0]
	v_pk_mul_f32 v[172:173], v[172:173], s[86:87] op_sel_hi:[1,0]
	v_pk_mul_f32 v[170:171], v[170:171], s[86:87] op_sel_hi:[1,0]
	v_pk_mul_f32 v[166:167], v[166:167], s[86:87] op_sel_hi:[1,0]
	v_pk_mul_f32 v[176:177], v[44:45], v[172:173]
	v_pk_mul_f32 v[178:179], v[42:43], v[170:171]
	v_pk_mul_f32 v[172:173], v[52:53], v[172:173]
	v_pk_mul_f32 v[170:171], v[50:51], v[170:171]
	v_pk_fma_f32 v[176:177], v[52:53], v[168:169], v[176:177] neg_lo:[0,0,1] neg_hi:[0,0,1]
	v_pk_fma_f32 v[178:179], v[50:51], v[166:167], v[178:179] neg_lo:[0,0,1] neg_hi:[0,0,1]
	v_pk_fma_f32 v[172:173], v[44:45], v[168:169], v[172:173]
	v_pk_fma_f32 v[168:169], v[42:43], v[166:167], v[170:171]
	v_cvt_pk_bf16_f32 v166, v178, v179
	v_cvt_pk_bf16_f32 v167, v176, v177
	v_cvt_pk_bf16_f32 v168, v168, v169
	v_cvt_pk_bf16_f32 v169, v172, v173
	global_store_dwordx4 v[174:175], v[166:169], off offset:256
	global_load_dwordx4 v[170:173], v[136:137], off
	v_mad_i64_i32 v[174:175], s[18:19], v159, s24, v[132:133]
	global_load_dwordx4 v[166:169], v[152:153], off
	v_lshl_add_u64 v[174:175], v[174:175], 0, v[134:135]
	s_waitcnt vmcnt(0)
	v_pk_mul_f32 v[172:173], v[172:173], s[86:87] op_sel_hi:[1,0]
	v_pk_mul_f32 v[170:171], v[170:171], s[86:87] op_sel_hi:[1,0]
	v_pk_mul_f32 v[176:177], v[48:49], v[172:173]
	v_pk_mul_f32 v[168:169], v[168:169], s[86:87] op_sel_hi:[1,0]
	v_pk_mul_f32 v[166:167], v[166:167], s[86:87] op_sel_hi:[1,0]
	v_pk_mul_f32 v[178:179], v[46:47], v[170:171]
	v_pk_mul_f32 v[172:173], v[56:57], v[172:173]
	v_pk_mul_f32 v[170:171], v[54:55], v[170:171]
	v_pk_fma_f32 v[176:177], v[56:57], v[168:169], v[176:177] neg_lo:[0,0,1] neg_hi:[0,0,1]
	v_pk_fma_f32 v[178:179], v[54:55], v[166:167], v[178:179] neg_lo:[0,0,1] neg_hi:[0,0,1]
	v_pk_fma_f32 v[172:173], v[48:49], v[168:169], v[172:173]
	v_pk_fma_f32 v[168:169], v[46:47], v[166:167], v[170:171]
	v_cvt_pk_bf16_f32 v166, v178, v179
	v_cvt_pk_bf16_f32 v167, v176, v177
	v_cvt_pk_bf16_f32 v168, v168, v169
	v_cvt_pk_bf16_f32 v169, v172, v173
	global_store_dwordx4 v[174:175], v[166:169], off
	global_load_dwordx4 v[166:169], v[152:153], off
	s_nop 0
	global_load_dwordx4 v[170:173], v[136:137], off
	v_lshlrev_b32_e32 v136, 7, v158
	v_mov_b32_e32 v137, v0
	v_and_b32_e32 v136, 0x3f780, v136
	v_lshl_add_u64 v[152:153], s[4:5], 0, v[136:137]
	v_lshl_add_u64 v[136:137], s[6:7], 0, v[136:137]
	v_lshl_add_u64 v[136:137], v[136:137], 0, v[130:131]
	v_lshl_add_u64 v[152:153], v[152:153], 0, v[130:131]
	s_waitcnt vmcnt(0)
	v_pk_mul_f32 v[168:169], v[168:169], s[86:87] op_sel_hi:[1,0]
	v_pk_mul_f32 v[172:173], v[172:173], s[86:87] op_sel_hi:[1,0]
	v_pk_mul_f32 v[170:171], v[170:171], s[86:87] op_sel_hi:[1,0]
	v_pk_mul_f32 v[166:167], v[166:167], s[86:87] op_sel_hi:[1,0]
	v_pk_mul_f32 v[176:177], v[28:29], v[172:173]
	v_pk_mul_f32 v[178:179], v[26:27], v[170:171]
	v_pk_mul_f32 v[172:173], v[36:37], v[172:173]
	v_pk_mul_f32 v[170:171], v[34:35], v[170:171]
	v_pk_fma_f32 v[176:177], v[36:37], v[168:169], v[176:177] neg_lo:[0,0,1] neg_hi:[0,0,1]
	v_pk_fma_f32 v[178:179], v[34:35], v[166:167], v[178:179] neg_lo:[0,0,1] neg_hi:[0,0,1]
	v_pk_fma_f32 v[172:173], v[28:29], v[168:169], v[172:173]
	v_pk_fma_f32 v[168:169], v[26:27], v[166:167], v[170:171]
	v_cvt_pk_bf16_f32 v166, v178, v179
	v_cvt_pk_bf16_f32 v167, v176, v177
	v_cvt_pk_bf16_f32 v168, v168, v169
	v_cvt_pk_bf16_f32 v169, v172, v173
	global_store_dwordx4 v[174:175], v[166:169], off offset:256
	global_load_dwordx4 v[170:173], v[136:137], off
	v_mad_i64_i32 v[174:175], s[18:19], v158, s24, v[132:133]
	global_load_dwordx4 v[166:169], v[152:153], off
	v_lshl_add_u64 v[174:175], v[174:175], 0, v[134:135]
	s_waitcnt vmcnt(0)
	v_pk_mul_f32 v[172:173], v[172:173], s[86:87] op_sel_hi:[1,0]
	v_pk_mul_f32 v[170:171], v[170:171], s[86:87] op_sel_hi:[1,0]
	v_pk_mul_f32 v[176:177], v[32:33], v[172:173]
	v_pk_mul_f32 v[168:169], v[168:169], s[86:87] op_sel_hi:[1,0]
	v_pk_mul_f32 v[166:167], v[166:167], s[86:87] op_sel_hi:[1,0]
	v_pk_mul_f32 v[178:179], v[30:31], v[170:171]
	v_pk_mul_f32 v[172:173], v[40:41], v[172:173]
	v_pk_mul_f32 v[170:171], v[38:39], v[170:171]
	v_pk_fma_f32 v[176:177], v[40:41], v[168:169], v[176:177] neg_lo:[0,0,1] neg_hi:[0,0,1]
	v_pk_fma_f32 v[178:179], v[38:39], v[166:167], v[178:179] neg_lo:[0,0,1] neg_hi:[0,0,1]
	v_pk_fma_f32 v[172:173], v[32:33], v[168:169], v[172:173]
	v_pk_fma_f32 v[168:169], v[30:31], v[166:167], v[170:171]
	v_cvt_pk_bf16_f32 v166, v178, v179
	v_cvt_pk_bf16_f32 v167, v176, v177
	v_cvt_pk_bf16_f32 v168, v168, v169
	v_cvt_pk_bf16_f32 v169, v172, v173
	global_store_dwordx4 v[174:175], v[166:169], off
	global_load_dwordx4 v[166:169], v[152:153], off
	s_nop 0
	global_load_dwordx4 v[170:173], v[136:137], off
	v_lshlrev_b32_e32 v136, 7, v157
	v_mov_b32_e32 v137, v0
	v_and_b32_e32 v136, 0x3ff80, v136
	v_lshl_add_u64 v[152:153], s[4:5], 0, v[136:137]
	v_lshl_add_u64 v[176:177], v[152:153], 0, v[130:131]
	v_lshl_add_u64 v[136:137], s[6:7], 0, v[136:137]
	v_lshl_add_u64 v[136:137], v[136:137], 0, v[130:131]
	v_mad_i64_i32 v[130:131], s[18:19], v157, s24, v[132:133]
	s_mov_b64 s[18:19], 0
	s_waitcnt vmcnt(0)
	v_pk_mul_f32 v[152:153], v[168:169], s[86:87] op_sel_hi:[1,0]
	v_pk_mul_f32 v[168:169], v[172:173], s[86:87] op_sel_hi:[1,0]
	v_pk_mul_f32 v[170:171], v[170:171], s[86:87] op_sel_hi:[1,0]
	v_pk_mul_f32 v[166:167], v[166:167], s[86:87] op_sel_hi:[1,0]
	v_pk_mul_f32 v[172:173], v[12:13], v[168:169]
	v_pk_mul_f32 v[178:179], v[10:11], v[170:171]
	v_pk_mul_f32 v[168:169], v[20:21], v[168:169]
	v_pk_mul_f32 v[170:171], v[18:19], v[170:171]
	v_pk_fma_f32 v[172:173], v[20:21], v[152:153], v[172:173] neg_lo:[0,0,1] neg_hi:[0,0,1]
	v_pk_fma_f32 v[178:179], v[18:19], v[166:167], v[178:179] neg_lo:[0,0,1] neg_hi:[0,0,1]
	v_pk_fma_f32 v[152:153], v[12:13], v[152:153], v[168:169]
	v_pk_fma_f32 v[168:169], v[10:11], v[166:167], v[170:171]
	v_cvt_pk_bf16_f32 v166, v178, v179
	v_cvt_pk_bf16_f32 v167, v172, v173
	v_cvt_pk_bf16_f32 v168, v168, v169
	v_cvt_pk_bf16_f32 v169, v152, v153
	global_store_dwordx4 v[174:175], v[166:169], off offset:256
	global_load_dwordx4 v[166:169], v[176:177], off
	v_lshl_add_u64 v[152:153], v[130:131], 0, v[134:135]
	global_load_dwordx4 v[170:173], v[136:137], off
	s_waitcnt vmcnt(0)
	v_pk_mul_f32 v[132:133], v[166:167], s[86:87] op_sel_hi:[1,0]
	v_pk_mul_f32 v[130:131], v[168:169], s[86:87] op_sel_hi:[1,0]
	v_pk_mul_f32 v[134:135], v[172:173], s[86:87] op_sel_hi:[1,0]
	v_pk_mul_f32 v[166:167], v[170:171], s[86:87] op_sel_hi:[1,0]
	v_pk_mul_f32 v[168:169], v[16:17], v[134:135]
	v_pk_mul_f32 v[170:171], v[14:15], v[166:167]
	v_pk_mul_f32 v[134:135], v[24:25], v[134:135]
	v_pk_mul_f32 v[166:167], v[22:23], v[166:167]
	v_pk_fma_f32 v[168:169], v[24:25], v[130:131], v[168:169] neg_lo:[0,0,1] neg_hi:[0,0,1]
	v_pk_fma_f32 v[170:171], v[22:23], v[132:133], v[170:171] neg_lo:[0,0,1] neg_hi:[0,0,1]
	v_pk_fma_f32 v[134:135], v[16:17], v[130:131], v[134:135]
	v_pk_fma_f32 v[132:133], v[14:15], v[132:133], v[166:167]
	v_cvt_pk_bf16_f32 v130, v170, v171
	v_cvt_pk_bf16_f32 v131, v168, v169
	v_cvt_pk_bf16_f32 v132, v132, v133
	v_cvt_pk_bf16_f32 v133, v134, v135
	global_store_dwordx4 v[152:153], v[130:133], off
	global_load_dwordx4 v[130:133], v[176:177], off
	s_nop 0
	global_load_dwordx4 v[134:137], v[136:137], off
	s_waitcnt vmcnt(0)
	v_pk_mul_f32 v[166:167], v[132:133], s[86:87] op_sel_hi:[1,0]
	v_pk_mul_f32 v[168:169], v[130:131], s[86:87] op_sel_hi:[1,0]
	v_pk_mul_f32 v[130:131], v[136:137], s[86:87] op_sel_hi:[1,0]
	v_pk_mul_f32 v[132:133], v[134:135], s[86:87] op_sel_hi:[1,0]
	v_pk_mul_f32 v[134:135], v[4:5], v[130:131]
	v_pk_mul_f32 v[136:137], v[2:3], v[132:133]
	v_pk_mul_f32 v[170:171], v[8:9], v[130:131]
	v_pk_mul_f32 v[172:173], v[6:7], v[132:133]
	v_pk_fma_f32 v[132:133], v[8:9], v[166:167], v[134:135] neg_lo:[0,0,1] neg_hi:[0,0,1]
	v_pk_fma_f32 v[130:131], v[6:7], v[168:169], v[136:137] neg_lo:[0,0,1] neg_hi:[0,0,1]
	v_pk_fma_f32 v[136:137], v[4:5], v[166:167], v[170:171]
	v_pk_fma_f32 v[134:135], v[2:3], v[168:169], v[172:173]

.LBB0_526:
	s_add_u32 s20, s18, 0xfff80080
	s_addc_u32 s21, s19, -1
	s_add_i32 s56, 0, 0x10000
	s_cmp_eq_u32 s55, 28
	s_cselect_b32 s23, s39, s21
	s_cselect_b32 s22, s51, s20
	s_cselect_b32 s21, s31, s54
	s_cselect_b32 s20, s52, s53
	v_lshl_add_u64 v[152:153], s[18:19], 0, v[140:141]
	s_add_i32 m0, s29, 0xc000
	ds_read_b128 v[164:167], v154
	ds_read_b128 v[168:171], v154 offset:1024
	ds_read_b128 v[172:175], v154 offset:2048
	ds_read_b128 v[176:179], v154 offset:3072
	ds_read_b128 v[192:195], v154 offset:4096
	ds_read_b128 v[196:199], v154 offset:5120
	ds_read_b128 v[200:203], v154 offset:6144
	ds_read_b128 v[204:207], v154 offset:7168
	global_load_lds_dwordx4 v[152:153], off
	v_lshl_add_u64 v[152:153], s[18:19], 0, v[142:143]
	s_add_i32 m0, s29, 0xe000
	s_nop 0
	global_load_lds_dwordx4 v[152:153], off
	s_waitcnt lgkmcnt(8)
	s_barrier
	s_waitcnt lgkmcnt(0)
	v_mfma_f32_16x16x32_bf16 v[126:129], v[144:147], v[164:167], v[126:129]
	v_mfma_f32_16x16x32_bf16 v[122:125], v[156:159], v[164:167], v[122:125]
	v_mfma_f32_16x16x32_bf16 v[118:121], v[144:147], v[172:175], v[118:121]
	v_mfma_f32_16x16x32_bf16 v[114:117], v[156:159], v[172:175], v[114:117]
	v_mfma_f32_16x16x32_bf16 v[102:105], v[144:147], v[192:195], v[102:105]
	v_mfma_f32_16x16x32_bf16 v[98:101], v[156:159], v[192:195], v[98:101]
	v_mfma_f32_16x16x32_bf16 v[86:89], v[144:147], v[200:203], v[86:89]
	v_mfma_f32_16x16x32_bf16 v[82:85], v[156:159], v[200:203], v[82:85]
	v_mfma_f32_16x16x32_bf16 v[126:129], v[148:151], v[168:171], v[126:129]
	v_mfma_f32_16x16x32_bf16 v[122:125], v[160:163], v[168:171], v[122:125]
	v_mfma_f32_16x16x32_bf16 v[118:121], v[148:151], v[176:179], v[118:121]
	v_mfma_f32_16x16x32_bf16 v[114:117], v[160:163], v[176:179], v[114:117]
	v_mfma_f32_16x16x32_bf16 v[102:105], v[148:151], v[196:199], v[102:105]
	v_mfma_f32_16x16x32_bf16 v[98:101], v[160:163], v[196:199], v[98:101]
	v_mfma_f32_16x16x32_bf16 v[86:89], v[148:151], v[204:207], v[86:89]
	v_mfma_f32_16x16x32_bf16 v[82:85], v[160:163], v[204:207], v[82:85]
	s_barrier
	s_add_i32 s58, 0, 0x14000
	v_add_u32_e32 v152, s58, v139
	s_add_i32 s56, s56, s28
	ds_read_b128 v[208:211], v152
	ds_read_b128 v[224:227], v152 offset:1024
	ds_read_b128 v[228:231], v152 offset:2048
	ds_read_b128 v[232:235], v152 offset:3072
	v_lshl_add_u64 v[152:153], s[20:21], 0, v[134:135]
	s_mov_b32 m0, s56
	v_lshl_add_u64 v[212:213], s[20:21], 0, v[130:131]
	global_load_lds_dwordx4 v[152:153], off
	s_add_i32 m0, s56, 0x2000
	s_nop 0
	global_load_lds_dwordx4 v[212:213], off
	s_barrier
	s_waitcnt lgkmcnt(0)
	v_mfma_f32_16x16x32_bf16 v[110:113], v[208:211], v[164:167], v[110:113]
	v_mfma_f32_16x16x32_bf16 v[106:109], v[228:231], v[164:167], v[106:109]
	v_mfma_f32_16x16x32_bf16 v[94:97], v[208:211], v[172:175], v[94:97]
	v_mfma_f32_16x16x32_bf16 v[90:93], v[228:231], v[172:175], v[90:93]
	v_mfma_f32_16x16x32_bf16 v[78:81], v[208:211], v[192:195], v[78:81]
	v_mfma_f32_16x16x32_bf16 v[74:77], v[228:231], v[192:195], v[74:77]
	v_mfma_f32_16x16x32_bf16 v[70:73], v[208:211], v[200:203], v[70:73]
	v_mfma_f32_16x16x32_bf16 v[66:69], v[228:231], v[200:203], v[66:69]
	v_mfma_f32_16x16x32_bf16 v[110:113], v[224:227], v[168:171], v[110:113]
	v_mfma_f32_16x16x32_bf16 v[106:109], v[232:235], v[168:171], v[106:109]
	v_mfma_f32_16x16x32_bf16 v[94:97], v[224:227], v[176:179], v[94:97]
	v_mfma_f32_16x16x32_bf16 v[90:93], v[232:235], v[176:179], v[90:93]
	v_mfma_f32_16x16x32_bf16 v[78:81], v[224:227], v[196:199], v[78:81]
	v_mfma_f32_16x16x32_bf16 v[74:77], v[232:235], v[196:199], v[74:77]
	v_mfma_f32_16x16x32_bf16 v[70:73], v[224:227], v[204:207], v[70:73]
	v_mfma_f32_16x16x32_bf16 v[66:69], v[232:235], v[204:207], v[66:69]
	s_mov_b32 m0, s29
	v_lshl_add_u64 v[236:237], s[22:23], 0, v[136:137]
	s_barrier
	ds_read_b128 v[164:167], v154 offset:16384
	ds_read_b128 v[168:171], v154 offset:17408
	ds_read_b128 v[172:175], v154 offset:18432
	ds_read_b128 v[176:179], v154 offset:19456
	ds_read_b128 v[192:195], v154 offset:20480
	ds_read_b128 v[196:199], v154 offset:21504
	ds_read_b128 v[200:203], v154 offset:22528
	ds_read_b128 v[204:207], v154 offset:23552
	global_load_lds_dwordx4 v[236:237], off
	v_lshl_add_u64 v[238:239], s[22:23], 0, v[132:133]
	s_mov_b32 m0, s44
	s_nop 0
	global_load_lds_dwordx4 v[238:239], off
	s_waitcnt vmcnt(10)
	s_barrier
	s_waitcnt lgkmcnt(0)
	v_mfma_f32_16x16x32_bf16 v[62:65], v[144:147], v[164:167], v[62:65]
	v_mfma_f32_16x16x32_bf16 v[58:61], v[156:159], v[164:167], v[58:61]
	v_mfma_f32_16x16x32_bf16 v[54:57], v[144:147], v[172:175], v[54:57]
	v_mfma_f32_16x16x32_bf16 v[50:53], v[156:159], v[172:175], v[50:53]
	v_mfma_f32_16x16x32_bf16 v[38:41], v[144:147], v[192:195], v[38:41]
	v_mfma_f32_16x16x32_bf16 v[34:37], v[156:159], v[192:195], v[34:37]
	v_mfma_f32_16x16x32_bf16 v[22:25], v[144:147], v[200:203], v[22:25]
	v_mfma_f32_16x16x32_bf16 v[18:21], v[156:159], v[200:203], v[18:21]
	v_mfma_f32_16x16x32_bf16 v[62:65], v[148:151], v[168:171], v[62:65]
	v_mfma_f32_16x16x32_bf16 v[58:61], v[160:163], v[168:171], v[58:61]
	v_mfma_f32_16x16x32_bf16 v[54:57], v[148:151], v[176:179], v[54:57]
	v_mfma_f32_16x16x32_bf16 v[50:53], v[160:163], v[176:179], v[50:53]
	v_mfma_f32_16x16x32_bf16 v[38:41], v[148:151], v[196:199], v[38:41]
	v_mfma_f32_16x16x32_bf16 v[34:37], v[160:163], v[196:199], v[34:37]
	v_mfma_f32_16x16x32_bf16 v[22:25], v[148:151], v[204:207], v[22:25]
	v_mfma_f32_16x16x32_bf16 v[18:21], v[160:163], v[204:207], v[18:21]
	s_barrier
	s_add_u32 s56, s20, 0x80000
	s_addc_u32 s57, s21, 0
	s_add_i32 s58, s58, s28
	v_lshl_add_u64 v[144:145], s[56:57], 0, v[134:135]
	s_mov_b32 m0, s58
	s_nop 0
	global_load_lds_dwordx4 v[144:145], off
	v_lshl_add_u64 v[144:145], s[56:57], 0, v[130:131]
	s_add_i32 m0, s58, 0x2000
	s_nop 0
	global_load_lds_dwordx4 v[144:145], off
	v_add_u32_e32 v155, 0x18000, v139
	ds_read_b128 v[144:147], v155
	ds_read_b128 v[148:151], v155 offset:1024
	ds_read_b128 v[156:159], v155 offset:2048
	ds_read_b128 v[160:163], v155 offset:3072
	s_waitcnt vmcnt(6)
	s_barrier
	v_mfma_f32_16x16x32_bf16 v[46:49], v[208:211], v[164:167], v[46:49]
	v_mfma_f32_16x16x32_bf16 v[42:45], v[228:231], v[164:167], v[42:45]
	v_mfma_f32_16x16x32_bf16 v[30:33], v[208:211], v[172:175], v[30:33]
	v_mfma_f32_16x16x32_bf16 v[26:29], v[228:231], v[172:175], v[26:29]
	v_mfma_f32_16x16x32_bf16 v[14:17], v[208:211], v[192:195], v[14:17]
	v_mfma_f32_16x16x32_bf16 v[10:13], v[228:231], v[192:195], v[10:13]
	v_mfma_f32_16x16x32_bf16 v[6:9], v[208:211], v[200:203], v[6:9]
	v_mfma_f32_16x16x32_bf16 v[2:5], v[228:231], v[200:203], v[2:5]
	v_mfma_f32_16x16x32_bf16 v[46:49], v[224:227], v[168:171], v[46:49]
	v_mfma_f32_16x16x32_bf16 v[42:45], v[232:235], v[168:171], v[42:45]
	v_mfma_f32_16x16x32_bf16 v[30:33], v[224:227], v[176:179], v[30:33]
	v_mfma_f32_16x16x32_bf16 v[26:29], v[232:235], v[176:179], v[26:29]
	v_mfma_f32_16x16x32_bf16 v[14:17], v[224:227], v[196:199], v[14:17]
	v_mfma_f32_16x16x32_bf16 v[10:13], v[232:235], v[196:199], v[10:13]
	v_mfma_f32_16x16x32_bf16 v[6:9], v[224:227], v[204:207], v[6:9]
	v_mfma_f32_16x16x32_bf16 v[2:5], v[232:235], v[204:207], v[2:5]
	s_add_i32 s56, 0, 0x18000
	s_barrier
	s_add_u32 s22, s22, 0x80000
	s_addc_u32 s23, s23, 0
	s_mov_b32 m0, s45
	v_lshl_add_u64 v[208:209], s[22:23], 0, v[136:137]
	ds_read_b128 v[164:167], v154 offset:32768
	ds_read_b128 v[168:171], v154 offset:33792
	ds_read_b128 v[172:175], v154 offset:34816
	ds_read_b128 v[176:179], v154 offset:35840
	ds_read_b128 v[192:195], v154 offset:36864
	ds_read_b128 v[196:199], v154 offset:37888
	ds_read_b128 v[200:203], v154 offset:38912
	ds_read_b128 v[204:207], v154 offset:39936
	global_load_lds_dwordx4 v[208:209], off
	v_lshl_add_u64 v[208:209], s[22:23], 0, v[132:133]
	s_mov_b32 m0, s46
	s_nop 0
	global_load_lds_dwordx4 v[208:209], off
	s_waitcnt lgkmcnt(8)
	s_barrier
	s_waitcnt lgkmcnt(0)
	v_mfma_f32_16x16x32_bf16 v[126:129], v[144:147], v[164:167], v[126:129]
	v_mfma_f32_16x16x32_bf16 v[122:125], v[156:159], v[164:167], v[122:125]
	v_mfma_f32_16x16x32_bf16 v[118:121], v[144:147], v[172:175], v[118:121]
	v_mfma_f32_16x16x32_bf16 v[114:117], v[156:159], v[172:175], v[114:117]
	v_mfma_f32_16x16x32_bf16 v[102:105], v[144:147], v[192:195], v[102:105]
	v_mfma_f32_16x16x32_bf16 v[98:101], v[156:159], v[192:195], v[98:101]
	v_mfma_f32_16x16x32_bf16 v[86:89], v[144:147], v[200:203], v[86:89]
	v_mfma_f32_16x16x32_bf16 v[82:85], v[156:159], v[200:203], v[82:85]
	v_mfma_f32_16x16x32_bf16 v[126:129], v[148:151], v[168:171], v[126:129]
	v_mfma_f32_16x16x32_bf16 v[122:125], v[160:163], v[168:171], v[122:125]
	v_mfma_f32_16x16x32_bf16 v[118:121], v[148:151], v[176:179], v[118:121]
	v_mfma_f32_16x16x32_bf16 v[114:117], v[160:163], v[176:179], v[114:117]
	v_mfma_f32_16x16x32_bf16 v[102:105], v[148:151], v[196:199], v[102:105]
	v_mfma_f32_16x16x32_bf16 v[98:101], v[160:163], v[196:199], v[98:101]
	v_mfma_f32_16x16x32_bf16 v[86:89], v[148:151], v[204:207], v[86:89]
	v_mfma_f32_16x16x32_bf16 v[82:85], v[160:163], v[204:207], v[82:85]
	s_barrier
	s_add_i32 s22, 0, 0x1c000
	s_add_i32 s23, s56, s28
	v_add_u32_e32 v155, s22, v139
	v_lshl_add_u64 v[152:153], v[152:153], 0, s[78:79]
	s_mov_b32 m0, s23
	ds_read_b128 v[208:211], v155
	ds_read_b128 v[224:227], v155 offset:1024
	ds_read_b128 v[228:231], v155 offset:2048
	ds_read_b128 v[232:235], v155 offset:3072
	global_load_lds_dwordx4 v[152:153], off
	v_lshl_add_u64 v[152:153], v[212:213], 0, s[78:79]
	s_add_i32 m0, s23, 0x2000
	s_nop 0
	global_load_lds_dwordx4 v[152:153], off
	s_barrier
	s_waitcnt lgkmcnt(0)
	v_mfma_f32_16x16x32_bf16 v[110:113], v[208:211], v[164:167], v[110:113]
	v_mfma_f32_16x16x32_bf16 v[106:109], v[228:231], v[164:167], v[106:109]
	v_mfma_f32_16x16x32_bf16 v[94:97], v[208:211], v[172:175], v[94:97]
	v_mfma_f32_16x16x32_bf16 v[90:93], v[228:231], v[172:175], v[90:93]
	v_mfma_f32_16x16x32_bf16 v[78:81], v[208:211], v[192:195], v[78:81]
	v_mfma_f32_16x16x32_bf16 v[74:77], v[228:231], v[192:195], v[74:77]
	v_mfma_f32_16x16x32_bf16 v[70:73], v[208:211], v[200:203], v[70:73]
	v_mfma_f32_16x16x32_bf16 v[66:69], v[228:231], v[200:203], v[66:69]
	v_mfma_f32_16x16x32_bf16 v[110:113], v[224:227], v[168:171], v[110:113]
	v_mfma_f32_16x16x32_bf16 v[106:109], v[232:235], v[168:171], v[106:109]
	v_mfma_f32_16x16x32_bf16 v[94:97], v[224:227], v[176:179], v[94:97]
	v_mfma_f32_16x16x32_bf16 v[90:93], v[232:235], v[176:179], v[90:93]
	v_mfma_f32_16x16x32_bf16 v[78:81], v[224:227], v[196:199], v[78:81]
	v_mfma_f32_16x16x32_bf16 v[74:77], v[232:235], v[196:199], v[74:77]
	v_mfma_f32_16x16x32_bf16 v[70:73], v[224:227], v[204:207], v[70:73]
	v_mfma_f32_16x16x32_bf16 v[66:69], v[232:235], v[204:207], v[66:69]
	s_mov_b32 m0, s47
	v_lshl_add_u64 v[152:153], v[236:237], 0, s[78:79]
	s_barrier
	ds_read_b128 v[164:167], v154 offset:49152
	ds_read_b128 v[168:171], v154 offset:50176
	ds_read_b128 v[172:175], v154 offset:51200
	ds_read_b128 v[176:179], v154 offset:52224
	ds_read_b128 v[192:195], v154 offset:53248
	ds_read_b128 v[196:199], v154 offset:54272
	ds_read_b128 v[200:203], v154 offset:55296
	ds_read_b128 v[204:207], v154 offset:56320
	global_load_lds_dwordx4 v[152:153], off
	v_lshl_add_u64 v[152:153], v[238:239], 0, s[78:79]
	s_mov_b32 m0, s48
	s_nop 0
	global_load_lds_dwordx4 v[152:153], off
	s_waitcnt vmcnt(10)
	s_barrier
	s_waitcnt lgkmcnt(0)
	v_mfma_f32_16x16x32_bf16 v[62:65], v[144:147], v[164:167], v[62:65]
	v_mfma_f32_16x16x32_bf16 v[58:61], v[156:159], v[164:167], v[58:61]
	v_mfma_f32_16x16x32_bf16 v[54:57], v[144:147], v[172:175], v[54:57]
	v_mfma_f32_16x16x32_bf16 v[50:53], v[156:159], v[172:175], v[50:53]
	v_mfma_f32_16x16x32_bf16 v[38:41], v[144:147], v[192:195], v[38:41]
	v_mfma_f32_16x16x32_bf16 v[34:37], v[156:159], v[192:195], v[34:37]
	v_mfma_f32_16x16x32_bf16 v[22:25], v[144:147], v[200:203], v[22:25]
	v_mfma_f32_16x16x32_bf16 v[18:21], v[156:159], v[200:203], v[18:21]
	v_mfma_f32_16x16x32_bf16 v[62:65], v[148:151], v[168:171], v[62:65]
	v_mfma_f32_16x16x32_bf16 v[58:61], v[160:163], v[168:171], v[58:61]
	v_mfma_f32_16x16x32_bf16 v[54:57], v[148:151], v[176:179], v[54:57]
	v_mfma_f32_16x16x32_bf16 v[50:53], v[160:163], v[176:179], v[50:53]
	v_mfma_f32_16x16x32_bf16 v[38:41], v[148:151], v[196:199], v[38:41]
	v_mfma_f32_16x16x32_bf16 v[34:37], v[160:163], v[196:199], v[34:37]
	v_mfma_f32_16x16x32_bf16 v[22:25], v[148:151], v[204:207], v[22:25]
	v_mfma_f32_16x16x32_bf16 v[18:21], v[160:163], v[204:207], v[18:21]
	s_barrier
	s_add_u32 s20, s20, 0x80080
	s_addc_u32 s21, s21, 0
	s_add_i32 s22, s22, s28
	v_lshl_add_u64 v[144:145], s[20:21], 0, v[134:135]
	s_mov_b32 m0, s22
	s_nop 0
	global_load_lds_dwordx4 v[144:145], off
	v_lshl_add_u64 v[144:145], s[20:21], 0, v[130:131]
	s_add_i32 m0, s22, 0x2000
	s_nop 0
	global_load_lds_dwordx4 v[144:145], off
	v_add_u32_e32 v152, 0x10000, v139
	ds_read_b128 v[144:147], v152
	ds_read_b128 v[148:151], v152 offset:1024
	ds_read_b128 v[156:159], v152 offset:2048
	ds_read_b128 v[160:163], v152 offset:3072
	s_waitcnt vmcnt(6)
	s_barrier
	v_mfma_f32_16x16x32_bf16 v[46:49], v[208:211], v[164:167], v[46:49]
	v_mfma_f32_16x16x32_bf16 v[42:45], v[228:231], v[164:167], v[42:45]
	v_mfma_f32_16x16x32_bf16 v[30:33], v[208:211], v[172:175], v[30:33]
	v_mfma_f32_16x16x32_bf16 v[26:29], v[228:231], v[172:175], v[26:29]
	v_mfma_f32_16x16x32_bf16 v[14:17], v[208:211], v[192:195], v[14:17]
	v_mfma_f32_16x16x32_bf16 v[10:13], v[228:231], v[192:195], v[10:13]
	v_mfma_f32_16x16x32_bf16 v[6:9], v[208:211], v[200:203], v[6:9]
	v_mfma_f32_16x16x32_bf16 v[2:5], v[228:231], v[200:203], v[2:5]
	v_mfma_f32_16x16x32_bf16 v[46:49], v[224:227], v[168:171], v[46:49]
	v_mfma_f32_16x16x32_bf16 v[42:45], v[232:235], v[168:171], v[42:45]
	v_mfma_f32_16x16x32_bf16 v[30:33], v[224:227], v[176:179], v[30:33]
	v_mfma_f32_16x16x32_bf16 v[26:29], v[232:235], v[176:179], v[26:29]
	v_mfma_f32_16x16x32_bf16 v[14:17], v[224:227], v[196:199], v[14:17]
	v_mfma_f32_16x16x32_bf16 v[10:13], v[232:235], v[196:199], v[10:13]
	v_mfma_f32_16x16x32_bf16 v[6:9], v[224:227], v[204:207], v[6:9]
	v_mfma_f32_16x16x32_bf16 v[2:5], v[232:235], v[204:207], v[2:5]
	s_add_i32 s55, s55, 2
	s_add_u32 s18, s18, 0x100
	s_addc_u32 s19, s19, 0
	s_add_u32 s53, s53, 0x100
	s_addc_u32 s54, s54, 0
	s_cmp_gt_u32 s55, 29
	s_barrier
	s_cbranch_scc0 .LBB0_526
	s_waitcnt lgkmcnt(0)
	v_lshl_add_u32 v152, s36, 8, v1
	v_or_b32_e32 v150, 16, v152
	v_or_b32_e32 v148, 32, v152
	v_or_b32_e32 v146, 48, v152
	s_mov_b64 s[18:19], -1
	s_cmp_lt_i32 s50, 8
	v_ashrrev_i32_e32 v153, 31, v152
	v_lshlrev_b32_e32 v144, 1, v138
	v_ashrrev_i32_e32 v151, 31, v150
	v_ashrrev_i32_e32 v149, 31, v148
	v_ashrrev_i32_e32 v147, 31, v146
	s_cbranch_scc1 .LBB0_529
	s_lshl_b32 s18, s50, 7
	s_add_i32 s36, s18, 0xfffffc00
	v_lshlrev_b64 v[156:157], 12, v[152:153]
	v_lshl_add_u64 v[156:157], s[72:73], 0, v[156:157]
	s_lshl_b64 s[18:19], s[36:37], 1
	v_lshl_add_u64 v[156:157], v[156:157], 0, s[18:19]
	v_mov_b32_e32 v145, v0
	v_lshl_add_u64 v[160:161], v[156:157], 0, v[144:145]
	v_pk_mul_f32 v[158:159], v[128:129], v[112:113]
	v_pk_mul_f32 v[156:157], v[126:127], v[110:111]
	v_pk_mul_f32 v[162:163], v[124:125], v[108:109]
	v_pk_mul_f32 v[164:165], v[122:123], v[106:107]
	v_cvt_pk_bf16_f32 v156, v156, v157
	v_cvt_pk_bf16_f32 v157, v158, v159
	v_cvt_pk_bf16_f32 v158, v164, v165
	v_cvt_pk_bf16_f32 v159, v162, v163
	global_store_dwordx4 v[160:161], v[156:159], off
	v_pk_mul_f32 v[164:165], v[116:117], v[92:93]
	v_pk_mul_f32 v[166:167], v[114:115], v[90:91]
	v_lshlrev_b64 v[156:157], 12, v[150:151]
	v_lshl_add_u64 v[156:157], s[72:73], 0, v[156:157]
	v_lshl_add_u64 v[156:157], v[156:157], 0, s[18:19]
	v_lshl_add_u64 v[162:163], v[156:157], 0, v[144:145]
	v_pk_mul_f32 v[158:159], v[120:121], v[96:97]
	v_pk_mul_f32 v[156:157], v[118:119], v[94:95]
	s_nop 0
	v_cvt_pk_bf16_f32 v156, v156, v157
	v_cvt_pk_bf16_f32 v157, v158, v159
	v_cvt_pk_bf16_f32 v158, v166, v167
	v_cvt_pk_bf16_f32 v159, v164, v165
	global_store_dwordx4 v[162:163], v[156:159], off
	v_pk_mul_f32 v[164:165], v[100:101], v[76:77]
	v_pk_mul_f32 v[166:167], v[98:99], v[74:75]
	v_lshlrev_b64 v[156:157], 12, v[148:149]
	v_lshl_add_u64 v[156:157], s[72:73], 0, v[156:157]
	v_lshl_add_u64 v[156:157], v[156:157], 0, s[18:19]
	v_lshl_add_u64 v[162:163], v[156:157], 0, v[144:145]
	v_pk_mul_f32 v[158:159], v[104:105], v[80:81]
	v_pk_mul_f32 v[156:157], v[102:103], v[78:79]
	s_nop 0
	v_cvt_pk_bf16_f32 v156, v156, v157
	v_cvt_pk_bf16_f32 v157, v158, v159
	v_cvt_pk_bf16_f32 v158, v166, v167
	v_cvt_pk_bf16_f32 v159, v164, v165
	global_store_dwordx4 v[162:163], v[156:159], off
	v_pk_mul_f32 v[164:165], v[84:85], v[68:69]
	v_pk_mul_f32 v[166:167], v[82:83], v[66:67]
	v_lshlrev_b64 v[156:157], 12, v[146:147]
	v_lshl_add_u64 v[156:157], s[72:73], 0, v[156:157]
	v_lshl_add_u64 v[156:157], v[156:157], 0, s[18:19]
	v_lshl_add_u64 v[162:163], v[156:157], 0, v[144:145]
	v_pk_mul_f32 v[158:159], v[88:89], v[72:73]
	v_pk_mul_f32 v[156:157], v[86:87], v[70:71]
	s_mov_b32 s18, 0x80000
	v_cvt_pk_bf16_f32 v156, v156, v157
	v_cvt_pk_bf16_f32 v157, v158, v159
	v_cvt_pk_bf16_f32 v158, v166, v167
	v_cvt_pk_bf16_f32 v159, v164, v165
	global_store_dwordx4 v[162:163], v[156:159], off
	v_pk_mul_f32 v[162:163], v[60:61], v[44:45]
	v_pk_mul_f32 v[164:165], v[58:59], v[42:43]
	v_pk_mul_f32 v[158:159], v[64:65], v[48:49]
	v_pk_mul_f32 v[156:157], v[62:63], v[46:47]
	s_nop 0
	v_cvt_pk_bf16_f32 v156, v156, v157
	v_cvt_pk_bf16_f32 v157, v158, v159
	v_cvt_pk_bf16_f32 v159, v162, v163
	v_add_co_u32_e32 v162, vcc, s18, v160
	v_cvt_pk_bf16_f32 v158, v164, v165
	s_nop 0
	v_addc_co_u32_e32 v163, vcc, 0, v161, vcc
	global_store_dwordx4 v[162:163], v[156:159], off
	v_pk_mul_f32 v[162:163], v[52:53], v[28:29]
	s_mov_b32 s18, 0x90000
	v_pk_mul_f32 v[158:159], v[56:57], v[32:33]
	v_pk_mul_f32 v[156:157], v[54:55], v[30:31]
	v_pk_mul_f32 v[164:165], v[50:51], v[26:27]
	v_cvt_pk_bf16_f32 v156, v156, v157
	v_cvt_pk_bf16_f32 v157, v158, v159
	v_cvt_pk_bf16_f32 v159, v162, v163
	v_add_co_u32_e32 v162, vcc, s18, v160
	v_cvt_pk_bf16_f32 v158, v164, v165
	s_nop 0
	v_addc_co_u32_e32 v163, vcc, 0, v161, vcc
	global_store_dwordx4 v[162:163], v[156:159], off
	v_pk_mul_f32 v[162:163], v[36:37], v[12:13]
	s_mov_b32 s18, 0xa0000
	v_pk_mul_f32 v[158:159], v[40:41], v[16:17]
	v_pk_mul_f32 v[156:157], v[38:39], v[14:15]
	v_pk_mul_f32 v[164:165], v[34:35], v[10:11]
	v_cvt_pk_bf16_f32 v156, v156, v157
	v_cvt_pk_bf16_f32 v157, v158, v159
	v_cvt_pk_bf16_f32 v159, v162, v163
	v_add_co_u32_e32 v162, vcc, s18, v160
	v_cvt_pk_bf16_f32 v158, v164, v165
	s_nop 0
	v_addc_co_u32_e32 v163, vcc, 0, v161, vcc
	global_store_dwordx4 v[162:163], v[156:159], off
	v_pk_mul_f32 v[162:163], v[20:21], v[4:5]
	v_pk_mul_f32 v[164:165], v[18:19], v[2:3]
	v_pk_mul_f32 v[158:159], v[24:25], v[8:9]
	v_pk_mul_f32 v[156:157], v[22:23], v[6:7]
	v_add_co_u32_e32 v160, vcc, 0xb0000, v160
	v_cvt_pk_bf16_f32 v156, v156, v157
	v_cvt_pk_bf16_f32 v157, v158, v159
	v_cvt_pk_bf16_f32 v158, v164, v165
	v_cvt_pk_bf16_f32 v159, v162, v163
	v_addc_co_u32_e32 v161, vcc, 0, v161, vcc
	s_mov_b64 s[18:19], 0
	global_store_dwordx4 v[160:161], v[156:159], off

.LBB0_649:
	s_add_u32 s18, s38, vcc_lo
	s_addc_u32 s19, s39, vcc_hi
	s_add_u32 s18, s18, 0x100
	s_addc_u32 s19, s19, 0
	s_add_u32 s57, s50, vcc_lo
	s_addc_u32 s58, s51, vcc_hi
	s_add_i32 s59, 0, 0x10000
	s_cmpk_eq_i32 vcc_lo, 0xf00
	s_cselect_b32 s23, s52, s19
	s_cselect_b32 s22, s53, s18
	s_cselect_b32 s19, s54, s58
	s_cselect_b32 s18, s55, s57
	v_lshl_add_u64 v[162:163], v[142:143], 0, vcc
	s_add_i32 m0, s28, 0xc000
	ds_read_b128 v[170:173], v148
	ds_read_b128 v[174:177], v148 offset:1024
	ds_read_b128 v[192:195], v148 offset:2048
	ds_read_b128 v[196:199], v148 offset:3072
	ds_read_b128 v[200:203], v148 offset:4096
	ds_read_b128 v[204:207], v148 offset:5120
	ds_read_b128 v[208:211], v148 offset:6144
	ds_read_b128 v[224:227], v148 offset:7168
	global_load_lds_dwordx4 v[162:163], off
	v_lshl_add_u64 v[162:163], v[144:145], 0, vcc
	s_add_i32 m0, s28, 0xe000
	s_nop 0
	global_load_lds_dwordx4 v[162:163], off
	s_waitcnt lgkmcnt(8)
	s_barrier
	s_waitcnt lgkmcnt(0)
	v_mfma_f32_16x16x32_bf16 v[90:93], v[150:153], v[170:173], v[90:93]
	v_mfma_f32_16x16x32_bf16 v[94:97], v[158:161], v[170:173], v[94:97]
	v_mfma_f32_16x16x32_bf16 v[102:105], v[150:153], v[192:195], v[102:105]
	v_mfma_f32_16x16x32_bf16 v[106:109], v[158:161], v[192:195], v[106:109]
	v_mfma_f32_16x16x32_bf16 v[114:117], v[150:153], v[200:203], v[114:117]
	v_mfma_f32_16x16x32_bf16 v[118:121], v[158:161], v[200:203], v[118:121]
	v_mfma_f32_16x16x32_bf16 v[122:125], v[150:153], v[208:211], v[122:125]
	v_mfma_f32_16x16x32_bf16 v[126:129], v[158:161], v[208:211], v[126:129]
	v_mfma_f32_16x16x32_bf16 v[90:93], v[154:157], v[174:177], v[90:93]
	v_mfma_f32_16x16x32_bf16 v[94:97], v[166:169], v[174:177], v[94:97]
	v_mfma_f32_16x16x32_bf16 v[102:105], v[154:157], v[196:199], v[102:105]
	v_mfma_f32_16x16x32_bf16 v[106:109], v[166:169], v[196:199], v[106:109]
	v_mfma_f32_16x16x32_bf16 v[114:117], v[154:157], v[204:207], v[114:117]
	v_mfma_f32_16x16x32_bf16 v[118:121], v[166:169], v[204:207], v[118:121]
	v_mfma_f32_16x16x32_bf16 v[122:125], v[154:157], v[224:227], v[122:125]
	v_mfma_f32_16x16x32_bf16 v[126:129], v[166:169], v[224:227], v[126:129]
	s_barrier
	s_add_i32 s57, 0, 0x14000
	s_add_i32 s58, s59, s85
	v_add_u32_e32 v149, s57, v147
	v_lshl_add_u64 v[162:163], s[18:19], 0, v[134:135]
	s_mov_b32 m0, s58
	ds_read_b128 v[228:231], v149
	ds_read_b128 v[232:235], v149 offset:1024
	ds_read_b128 v[236:239], v149 offset:2048
	ds_read_b128 v[240:243], v149 offset:3072
	global_load_lds_dwordx4 v[162:163], off
	v_lshl_add_u64 v[178:179], s[18:19], 0, v[130:131]
	s_add_i32 m0, s58, 0x2000
	s_nop 0
	global_load_lds_dwordx4 v[178:179], off
	s_barrier
	s_waitcnt lgkmcnt(0)
	v_mfma_f32_16x16x32_bf16 v[10:13], v[228:231], v[170:173], v[10:13]
	v_mfma_f32_16x16x32_bf16 v[14:17], v[236:239], v[170:173], v[14:17]
	v_mfma_f32_16x16x32_bf16 v[26:29], v[228:231], v[192:195], v[26:29]
	v_mfma_f32_16x16x32_bf16 v[38:41], v[236:239], v[192:195], v[38:41]
	v_mfma_f32_16x16x32_bf16 v[58:61], v[228:231], v[200:203], v[58:61]
	v_mfma_f32_16x16x32_bf16 v[62:65], v[236:239], v[200:203], v[62:65]
	v_mfma_f32_16x16x32_bf16 v[74:77], v[228:231], v[208:211], v[74:77]
	v_mfma_f32_16x16x32_bf16 v[78:81], v[236:239], v[208:211], v[78:81]
	v_mfma_f32_16x16x32_bf16 v[10:13], v[232:235], v[174:177], v[10:13]
	v_mfma_f32_16x16x32_bf16 v[14:17], v[240:243], v[174:177], v[14:17]
	v_mfma_f32_16x16x32_bf16 v[26:29], v[232:235], v[196:199], v[26:29]
	v_mfma_f32_16x16x32_bf16 v[38:41], v[240:243], v[196:199], v[38:41]
	v_mfma_f32_16x16x32_bf16 v[58:61], v[232:235], v[204:207], v[58:61]
	v_mfma_f32_16x16x32_bf16 v[62:65], v[240:243], v[204:207], v[62:65]
	v_mfma_f32_16x16x32_bf16 v[74:77], v[232:235], v[224:227], v[74:77]
	v_mfma_f32_16x16x32_bf16 v[78:81], v[240:243], v[224:227], v[78:81]
	s_mov_b32 m0, s28
	v_lshl_add_u64 v[212:213], s[22:23], 0, v[136:137]
	s_barrier
	ds_read_b128 v[170:173], v148 offset:16384
	ds_read_b128 v[174:177], v148 offset:17408
	ds_read_b128 v[192:195], v148 offset:18432
	ds_read_b128 v[196:199], v148 offset:19456
	ds_read_b128 v[200:203], v148 offset:20480
	ds_read_b128 v[204:207], v148 offset:21504
	ds_read_b128 v[208:211], v148 offset:22528
	ds_read_b128 v[224:227], v148 offset:23552
	global_load_lds_dwordx4 v[212:213], off
	v_lshl_add_u64 v[244:245], s[22:23], 0, v[132:133]
	s_mov_b32 m0, s29
	s_nop 0
	global_load_lds_dwordx4 v[244:245], off
	s_waitcnt vmcnt(10)
	s_barrier
	s_waitcnt lgkmcnt(0)
	v_mfma_f32_16x16x32_bf16 v[110:113], v[150:153], v[170:173], v[110:113]
	v_mfma_f32_16x16x32_bf16 v[98:101], v[158:161], v[170:173], v[98:101]
	v_mfma_f32_16x16x32_bf16 v[82:85], v[150:153], v[192:195], v[82:85]
	v_mfma_f32_16x16x32_bf16 v[66:69], v[158:161], v[192:195], v[66:69]
	v_mfma_f32_16x16x32_bf16 v[50:53], v[150:153], v[200:203], v[50:53]
	v_mfma_f32_16x16x32_bf16 v[42:45], v[158:161], v[200:203], v[42:45]
	v_mfma_f32_16x16x32_bf16 v[30:33], v[150:153], v[208:211], v[30:33]
	v_mfma_f32_16x16x32_bf16 v[18:21], v[158:161], v[208:211], v[18:21]
	v_mfma_f32_16x16x32_bf16 v[110:113], v[154:157], v[174:177], v[110:113]
	v_mfma_f32_16x16x32_bf16 v[98:101], v[166:169], v[174:177], v[98:101]
	v_mfma_f32_16x16x32_bf16 v[82:85], v[154:157], v[196:199], v[82:85]
	v_mfma_f32_16x16x32_bf16 v[66:69], v[166:169], v[196:199], v[66:69]
	v_mfma_f32_16x16x32_bf16 v[50:53], v[154:157], v[204:207], v[50:53]
	v_mfma_f32_16x16x32_bf16 v[42:45], v[166:169], v[204:207], v[42:45]
	v_mfma_f32_16x16x32_bf16 v[30:33], v[154:157], v[224:227], v[30:33]
	v_mfma_f32_16x16x32_bf16 v[18:21], v[166:169], v[224:227], v[18:21]
	s_barrier
	s_add_u32 s58, s18, 0x80000
	s_addc_u32 s59, s19, 0
	s_add_i32 s57, s57, s85
	v_lshl_add_u64 v[150:151], s[58:59], 0, v[134:135]
	s_mov_b32 m0, s57
	s_nop 0
	global_load_lds_dwordx4 v[150:151], off
	v_lshl_add_u64 v[150:151], s[58:59], 0, v[130:131]
	s_add_i32 m0, s57, 0x2000
	s_nop 0
	global_load_lds_dwordx4 v[150:151], off
	v_add_u32_e32 v149, 0x18000, v147
	ds_read_b128 v[150:153], v149
	ds_read_b128 v[154:157], v149 offset:1024
	ds_read_b128 v[158:161], v149 offset:2048
	ds_read_b128 v[166:169], v149 offset:3072
	s_waitcnt vmcnt(6)
	s_barrier
	v_mfma_f32_16x16x32_bf16 v[86:89], v[228:231], v[170:173], v[86:89]
	v_mfma_f32_16x16x32_bf16 v[70:73], v[236:239], v[170:173], v[70:73]
	v_mfma_f32_16x16x32_bf16 v[54:57], v[228:231], v[192:195], v[54:57]
	v_mfma_f32_16x16x32_bf16 v[46:49], v[236:239], v[192:195], v[46:49]
	v_mfma_f32_16x16x32_bf16 v[34:37], v[228:231], v[200:203], v[34:37]
	v_mfma_f32_16x16x32_bf16 v[22:25], v[236:239], v[200:203], v[22:25]
	v_mfma_f32_16x16x32_bf16 v[6:9], v[228:231], v[208:211], v[6:9]
	v_mfma_f32_16x16x32_bf16 v[2:5], v[236:239], v[208:211], v[2:5]
	v_mfma_f32_16x16x32_bf16 v[86:89], v[232:235], v[174:177], v[86:89]
	v_mfma_f32_16x16x32_bf16 v[70:73], v[240:243], v[174:177], v[70:73]
	v_mfma_f32_16x16x32_bf16 v[54:57], v[232:235], v[196:199], v[54:57]
	v_mfma_f32_16x16x32_bf16 v[46:49], v[240:243], v[196:199], v[46:49]
	v_mfma_f32_16x16x32_bf16 v[34:37], v[232:235], v[204:207], v[34:37]
	v_mfma_f32_16x16x32_bf16 v[22:25], v[240:243], v[204:207], v[22:25]
	v_mfma_f32_16x16x32_bf16 v[6:9], v[232:235], v[224:227], v[6:9]
	v_mfma_f32_16x16x32_bf16 v[2:5], v[240:243], v[224:227], v[2:5]
	s_add_i32 s57, 0, 0x18000
	s_barrier
	s_add_u32 s22, s22, 0x80000
	s_addc_u32 s23, s23, 0
	s_mov_b32 m0, s97
	v_lshl_add_u64 v[228:229], s[22:23], 0, v[136:137]
	ds_read_b128 v[170:173], v148 offset:32768
	ds_read_b128 v[174:177], v148 offset:33792
	ds_read_b128 v[192:195], v148 offset:34816
	ds_read_b128 v[196:199], v148 offset:35840
	ds_read_b128 v[200:203], v148 offset:36864
	ds_read_b128 v[204:207], v148 offset:37888
	ds_read_b128 v[208:211], v148 offset:38912
	ds_read_b128 v[224:227], v148 offset:39936
	global_load_lds_dwordx4 v[228:229], off
	v_lshl_add_u64 v[228:229], s[22:23], 0, v[132:133]
	s_mov_b32 m0, s44
	s_nop 0
	global_load_lds_dwordx4 v[228:229], off
	s_waitcnt lgkmcnt(8)
	s_barrier
	s_waitcnt lgkmcnt(0)
	v_mfma_f32_16x16x32_bf16 v[90:93], v[150:153], v[170:173], v[90:93]
	v_mfma_f32_16x16x32_bf16 v[94:97], v[158:161], v[170:173], v[94:97]
	v_mfma_f32_16x16x32_bf16 v[102:105], v[150:153], v[192:195], v[102:105]
	v_mfma_f32_16x16x32_bf16 v[106:109], v[158:161], v[192:195], v[106:109]
	v_mfma_f32_16x16x32_bf16 v[114:117], v[150:153], v[200:203], v[114:117]
	v_mfma_f32_16x16x32_bf16 v[118:121], v[158:161], v[200:203], v[118:121]
	v_mfma_f32_16x16x32_bf16 v[122:125], v[150:153], v[208:211], v[122:125]
	v_mfma_f32_16x16x32_bf16 v[126:129], v[158:161], v[208:211], v[126:129]
	v_mfma_f32_16x16x32_bf16 v[90:93], v[154:157], v[174:177], v[90:93]
	v_mfma_f32_16x16x32_bf16 v[94:97], v[166:169], v[174:177], v[94:97]
	v_mfma_f32_16x16x32_bf16 v[102:105], v[154:157], v[196:199], v[102:105]
	v_mfma_f32_16x16x32_bf16 v[106:109], v[166:169], v[196:199], v[106:109]
	v_mfma_f32_16x16x32_bf16 v[114:117], v[154:157], v[204:207], v[114:117]
	v_mfma_f32_16x16x32_bf16 v[118:121], v[166:169], v[204:207], v[118:121]
	v_mfma_f32_16x16x32_bf16 v[122:125], v[154:157], v[224:227], v[122:125]
	v_mfma_f32_16x16x32_bf16 v[126:129], v[166:169], v[224:227], v[126:129]
	s_barrier
	s_add_i32 s22, 0, 0x1c000
	s_add_i32 s23, s57, s85
	v_add_u32_e32 v149, s22, v147
	v_lshl_add_u64 v[162:163], v[162:163], 0, s[78:79]
	s_mov_b32 m0, s23
	ds_read_b128 v[228:231], v149
	ds_read_b128 v[232:235], v149 offset:1024
	ds_read_b128 v[236:239], v149 offset:2048
	ds_read_b128 v[240:243], v149 offset:3072
	global_load_lds_dwordx4 v[162:163], off
	v_lshl_add_u64 v[162:163], v[178:179], 0, s[78:79]
	s_add_i32 m0, s23, 0x2000
	s_nop 0
	global_load_lds_dwordx4 v[162:163], off
	s_barrier
	s_waitcnt lgkmcnt(0)
	v_mfma_f32_16x16x32_bf16 v[10:13], v[228:231], v[170:173], v[10:13]
	v_mfma_f32_16x16x32_bf16 v[14:17], v[236:239], v[170:173], v[14:17]
	v_mfma_f32_16x16x32_bf16 v[26:29], v[228:231], v[192:195], v[26:29]
	v_mfma_f32_16x16x32_bf16 v[38:41], v[236:239], v[192:195], v[38:41]
	v_mfma_f32_16x16x32_bf16 v[58:61], v[228:231], v[200:203], v[58:61]
	v_mfma_f32_16x16x32_bf16 v[62:65], v[236:239], v[200:203], v[62:65]
	v_mfma_f32_16x16x32_bf16 v[74:77], v[228:231], v[208:211], v[74:77]
	v_mfma_f32_16x16x32_bf16 v[78:81], v[236:239], v[208:211], v[78:81]
	v_mfma_f32_16x16x32_bf16 v[10:13], v[232:235], v[174:177], v[10:13]
	v_mfma_f32_16x16x32_bf16 v[14:17], v[240:243], v[174:177], v[14:17]
	v_mfma_f32_16x16x32_bf16 v[26:29], v[232:235], v[196:199], v[26:29]
	v_mfma_f32_16x16x32_bf16 v[38:41], v[240:243], v[196:199], v[38:41]
	v_mfma_f32_16x16x32_bf16 v[58:61], v[232:235], v[204:207], v[58:61]
	v_mfma_f32_16x16x32_bf16 v[62:65], v[240:243], v[204:207], v[62:65]
	v_mfma_f32_16x16x32_bf16 v[74:77], v[232:235], v[224:227], v[74:77]
	v_mfma_f32_16x16x32_bf16 v[78:81], v[240:243], v[224:227], v[78:81]
	s_mov_b32 m0, s46
	v_lshl_add_u64 v[162:163], v[212:213], 0, s[78:79]
	s_barrier
	ds_read_b128 v[170:173], v148 offset:49152
	ds_read_b128 v[174:177], v148 offset:50176
	ds_read_b128 v[192:195], v148 offset:51200
	ds_read_b128 v[196:199], v148 offset:52224
	ds_read_b128 v[200:203], v148 offset:53248
	ds_read_b128 v[204:207], v148 offset:54272
	ds_read_b128 v[208:211], v148 offset:55296
	ds_read_b128 v[224:227], v148 offset:56320
	global_load_lds_dwordx4 v[162:163], off
	v_lshl_add_u64 v[162:163], v[244:245], 0, s[78:79]
	s_mov_b32 m0, s47
	s_nop 0
	global_load_lds_dwordx4 v[162:163], off
	s_waitcnt vmcnt(10)
	s_barrier
	s_waitcnt lgkmcnt(0)
	v_mfma_f32_16x16x32_bf16 v[110:113], v[150:153], v[170:173], v[110:113]
	v_mfma_f32_16x16x32_bf16 v[98:101], v[158:161], v[170:173], v[98:101]
	v_mfma_f32_16x16x32_bf16 v[82:85], v[150:153], v[192:195], v[82:85]
	v_mfma_f32_16x16x32_bf16 v[66:69], v[158:161], v[192:195], v[66:69]
	v_mfma_f32_16x16x32_bf16 v[50:53], v[150:153], v[200:203], v[50:53]
	v_mfma_f32_16x16x32_bf16 v[42:45], v[158:161], v[200:203], v[42:45]
	v_mfma_f32_16x16x32_bf16 v[30:33], v[150:153], v[208:211], v[30:33]
	v_mfma_f32_16x16x32_bf16 v[18:21], v[158:161], v[208:211], v[18:21]
	v_mfma_f32_16x16x32_bf16 v[110:113], v[154:157], v[174:177], v[110:113]
	v_mfma_f32_16x16x32_bf16 v[98:101], v[166:169], v[174:177], v[98:101]
	v_mfma_f32_16x16x32_bf16 v[82:85], v[154:157], v[196:199], v[82:85]
	v_mfma_f32_16x16x32_bf16 v[66:69], v[166:169], v[196:199], v[66:69]
	v_mfma_f32_16x16x32_bf16 v[50:53], v[154:157], v[204:207], v[50:53]
	v_mfma_f32_16x16x32_bf16 v[42:45], v[166:169], v[204:207], v[42:45]
	v_mfma_f32_16x16x32_bf16 v[30:33], v[154:157], v[224:227], v[30:33]
	v_mfma_f32_16x16x32_bf16 v[18:21], v[166:169], v[224:227], v[18:21]
	s_barrier
	s_add_u32 s18, s18, 0x80080
	s_addc_u32 s19, s19, 0
	s_add_i32 s22, s22, s85
	v_lshl_add_u64 v[150:151], s[18:19], 0, v[134:135]
	s_mov_b32 m0, s22
	s_nop 0
	global_load_lds_dwordx4 v[150:151], off
	v_lshl_add_u64 v[150:151], s[18:19], 0, v[130:131]
	s_add_i32 m0, s22, 0x2000
	s_nop 0
	global_load_lds_dwordx4 v[150:151], off
	v_add_u32_e32 v149, 0x10000, v147
	ds_read_b128 v[150:153], v149
	ds_read_b128 v[154:157], v149 offset:1024
	ds_read_b128 v[158:161], v149 offset:2048
	ds_read_b128 v[166:169], v149 offset:3072
	s_waitcnt vmcnt(6)
	s_barrier
	v_mfma_f32_16x16x32_bf16 v[86:89], v[228:231], v[170:173], v[86:89]
	v_mfma_f32_16x16x32_bf16 v[70:73], v[236:239], v[170:173], v[70:73]
	v_mfma_f32_16x16x32_bf16 v[54:57], v[228:231], v[192:195], v[54:57]
	v_mfma_f32_16x16x32_bf16 v[46:49], v[236:239], v[192:195], v[46:49]
	v_mfma_f32_16x16x32_bf16 v[34:37], v[228:231], v[200:203], v[34:37]
	v_mfma_f32_16x16x32_bf16 v[22:25], v[236:239], v[200:203], v[22:25]
	v_mfma_f32_16x16x32_bf16 v[6:9], v[228:231], v[208:211], v[6:9]
	v_mfma_f32_16x16x32_bf16 v[2:5], v[236:239], v[208:211], v[2:5]
	v_mfma_f32_16x16x32_bf16 v[86:89], v[232:235], v[174:177], v[86:89]
	v_mfma_f32_16x16x32_bf16 v[70:73], v[240:243], v[174:177], v[70:73]
	v_mfma_f32_16x16x32_bf16 v[54:57], v[232:235], v[196:199], v[54:57]
	v_mfma_f32_16x16x32_bf16 v[46:49], v[240:243], v[196:199], v[46:49]
	v_mfma_f32_16x16x32_bf16 v[34:37], v[232:235], v[204:207], v[34:37]
	v_mfma_f32_16x16x32_bf16 v[22:25], v[240:243], v[204:207], v[22:25]
	v_mfma_f32_16x16x32_bf16 v[6:9], v[232:235], v[224:227], v[6:9]
	v_mfma_f32_16x16x32_bf16 v[2:5], v[240:243], v[224:227], v[2:5]
	s_add_i32 s56, s56, 2
	s_add_u32 vcc_lo, vcc_lo, 0x100
	s_addc_u32 vcc_hi, vcc_hi, 0
	s_cmp_gt_u32 s56, 29
	s_barrier
	s_cbranch_scc0 .LBB0_649
	s_waitcnt lgkmcnt(0)
	s_add_u32 s18, s50, 0xffffff00
	s_addc_u32 s19, s51, -1
	s_andn2_b64 vcc, exec, s[42:43]
	s_cbranch_vccnz .LBB0_652
	v_mov_b32_e32 v2, 0
	s_mov_b32 s84, s80
	s_mov_b32 s25, s82
	s_mov_b64 s[38:39], s[20:21]
	s_mov_b32 s48, s49
	v_mov_b32_e32 v3, v2
	v_mov_b32_e32 v4, v2
	v_mov_b32_e32 v5, v2
	v_mov_b32_e32 v6, v2
	v_mov_b32_e32 v7, v2
	v_mov_b32_e32 v8, v2
	v_mov_b32_e32 v9, v2
	v_mov_b32_e32 v22, v2
	v_mov_b32_e32 v23, v2
	v_mov_b32_e32 v24, v2
	v_mov_b32_e32 v25, v2
	v_mov_b32_e32 v34, v2
	v_mov_b32_e32 v35, v2
	v_mov_b32_e32 v36, v2
	v_mov_b32_e32 v37, v2
	v_mov_b32_e32 v46, v2
	v_mov_b32_e32 v47, v2
	v_mov_b32_e32 v48, v2
	v_mov_b32_e32 v49, v2
	v_mov_b32_e32 v54, v2
	v_mov_b32_e32 v55, v2
	v_mov_b32_e32 v56, v2
	v_mov_b32_e32 v57, v2
	v_mov_b32_e32 v70, v2
	v_mov_b32_e32 v71, v2
	v_mov_b32_e32 v72, v2
	v_mov_b32_e32 v73, v2
	v_mov_b32_e32 v86, v2
	v_mov_b32_e32 v87, v2
	v_mov_b32_e32 v88, v2
	v_mov_b32_e32 v89, v2
	v_mov_b32_e32 v18, v2
	v_mov_b32_e32 v19, v2
	v_mov_b32_e32 v20, v2
	v_mov_b32_e32 v21, v2
	v_mov_b32_e32 v30, v2
	v_mov_b32_e32 v31, v2
	v_mov_b32_e32 v32, v2
	v_mov_b32_e32 v33, v2
	v_mov_b32_e32 v42, v2
	v_mov_b32_e32 v43, v2
	v_mov_b32_e32 v44, v2
	v_mov_b32_e32 v45, v2
	v_mov_b32_e32 v50, v2
	v_mov_b32_e32 v51, v2
	v_mov_b32_e32 v52, v2
	v_mov_b32_e32 v53, v2
	v_mov_b32_e32 v66, v2
	v_mov_b32_e32 v67, v2
	v_mov_b32_e32 v68, v2
	v_mov_b32_e32 v69, v2
	v_mov_b32_e32 v82, v2
	v_mov_b32_e32 v83, v2
	v_mov_b32_e32 v84, v2
	v_mov_b32_e32 v85, v2
	v_mov_b32_e32 v98, v2
	v_mov_b32_e32 v99, v2
	v_mov_b32_e32 v100, v2
	v_mov_b32_e32 v101, v2
	v_mov_b32_e32 v110, v2
	v_mov_b32_e32 v111, v2
	v_mov_b32_e32 v112, v2
	v_mov_b32_e32 v113, v2
	v_mov_b32_e32 v78, v2
	v_mov_b32_e32 v79, v2
	v_mov_b32_e32 v80, v2
	v_mov_b32_e32 v81, v2
	v_mov_b32_e32 v74, v2
	v_mov_b32_e32 v75, v2
	v_mov_b32_e32 v76, v2
	v_mov_b32_e32 v77, v2
	v_mov_b32_e32 v62, v2
	v_mov_b32_e32 v63, v2
	v_mov_b32_e32 v64, v2
	v_mov_b32_e32 v65, v2
	v_mov_b32_e32 v58, v2
	v_mov_b32_e32 v59, v2
	v_mov_b32_e32 v60, v2
	v_mov_b32_e32 v61, v2
	v_mov_b32_e32 v38, v2
	v_mov_b32_e32 v39, v2
	v_mov_b32_e32 v40, v2
	v_mov_b32_e32 v41, v2
	v_mov_b32_e32 v26, v2
	v_mov_b32_e32 v27, v2
	v_mov_b32_e32 v28, v2
	v_mov_b32_e32 v29, v2
	v_mov_b32_e32 v14, v2
	v_mov_b32_e32 v15, v2
	v_mov_b32_e32 v16, v2
	v_mov_b32_e32 v17, v2
	v_mov_b32_e32 v10, v2
	v_mov_b32_e32 v11, v2
	v_mov_b32_e32 v12, v2
	v_mov_b32_e32 v13, v2
	v_mov_b32_e32 v126, v2
	v_mov_b32_e32 v127, v2
	v_mov_b32_e32 v128, v2
	v_mov_b32_e32 v129, v2
	v_mov_b32_e32 v122, v2
	v_mov_b32_e32 v123, v2
	v_mov_b32_e32 v124, v2
	v_mov_b32_e32 v125, v2
	v_mov_b32_e32 v118, v2
	v_mov_b32_e32 v119, v2
	v_mov_b32_e32 v120, v2
	v_mov_b32_e32 v121, v2
	v_mov_b32_e32 v114, v2
	v_mov_b32_e32 v115, v2
	v_mov_b32_e32 v116, v2
	v_mov_b32_e32 v117, v2
	v_mov_b32_e32 v106, v2
	v_mov_b32_e32 v107, v2
	v_mov_b32_e32 v108, v2
	v_mov_b32_e32 v109, v2
	v_mov_b32_e32 v102, v2
	v_mov_b32_e32 v103, v2
	v_mov_b32_e32 v104, v2
	v_mov_b32_e32 v105, v2
	v_mov_b32_e32 v94, v2
	v_mov_b32_e32 v95, v2
	v_mov_b32_e32 v96, v2
	v_mov_b32_e32 v97, v2
	v_mov_b32_e32 v90, v2
	v_mov_b32_e32 v91, v2
	v_mov_b32_e32 v92, v2
	v_mov_b32_e32 v93, v2
	s_andn2_b64 vcc, exec, s[0:1]
	s_cbranch_vccnz .LBB0_653
	s_branch .LBB0_654

.LBB0_749:
	s_add_u32 s20, s18, 0xfff80080
	s_addc_u32 s21, s19, -1
	s_add_i32 s58, 0, 0x10000
	s_cmp_eq_u32 s57, 28
	s_cselect_b32 s23, s39, s21
	s_cselect_b32 s22, s53, s20
	s_cselect_b32 s21, s31, s56
	s_cselect_b32 s20, s54, s55
	v_lshl_add_u64 v[212:213], s[18:19], 0, v[154:155]
	s_add_i32 m0, s44, 0xc000
	ds_read_b128 v[176:179], v158
	ds_read_b128 v[192:195], v158 offset:1024
	ds_read_b128 v[196:199], v158 offset:2048
	ds_read_b128 v[200:203], v158 offset:3072
	ds_read_b128 v[204:207], v158 offset:4096
	ds_read_b128 v[208:211], v158 offset:5120
	ds_read_b128 v[224:227], v158 offset:6144
	ds_read_b128 v[228:231], v158 offset:7168
	global_load_lds_dwordx4 v[212:213], off
	v_lshl_add_u64 v[212:213], s[18:19], 0, v[156:157]
	s_add_i32 m0, s44, 0xe000
	s_nop 0
	global_load_lds_dwordx4 v[212:213], off
	s_waitcnt lgkmcnt(8)
	s_barrier
	s_waitcnt lgkmcnt(0)
	v_mfma_f32_16x16x32_bf16 v[126:129], v[160:163], v[176:179], v[126:129]
	v_mfma_f32_16x16x32_bf16 v[122:125], v[168:171], v[176:179], v[122:125]
	v_mfma_f32_16x16x32_bf16 v[110:113], v[160:163], v[196:199], v[110:113]
	v_mfma_f32_16x16x32_bf16 v[106:109], v[168:171], v[196:199], v[106:109]
	v_mfma_f32_16x16x32_bf16 v[94:97], v[160:163], v[204:207], v[94:97]
	v_mfma_f32_16x16x32_bf16 v[90:93], v[168:171], v[204:207], v[90:93]
	v_mfma_f32_16x16x32_bf16 v[78:81], v[160:163], v[224:227], v[78:81]
	v_mfma_f32_16x16x32_bf16 v[74:77], v[168:171], v[224:227], v[74:77]
	v_mfma_f32_16x16x32_bf16 v[126:129], v[164:167], v[192:195], v[126:129]
	v_mfma_f32_16x16x32_bf16 v[122:125], v[172:175], v[192:195], v[122:125]
	v_mfma_f32_16x16x32_bf16 v[110:113], v[164:167], v[200:203], v[110:113]
	v_mfma_f32_16x16x32_bf16 v[106:109], v[172:175], v[200:203], v[106:109]
	v_mfma_f32_16x16x32_bf16 v[94:97], v[164:167], v[208:211], v[94:97]
	v_mfma_f32_16x16x32_bf16 v[90:93], v[172:175], v[208:211], v[90:93]
	v_mfma_f32_16x16x32_bf16 v[78:81], v[164:167], v[228:231], v[78:81]
	v_mfma_f32_16x16x32_bf16 v[74:77], v[172:175], v[228:231], v[74:77]
	s_barrier
	s_add_i32 s82, 0, 0x14000
	s_add_i32 s58, s58, s29
	v_add_u32_e32 v159, s82, v1
	v_lshl_add_u64 v[212:213], s[20:21], 0, v[134:135]
	s_mov_b32 m0, s58
	ds_read_b128 v[232:235], v159
	ds_read_b128 v[236:239], v159 offset:1024
	ds_read_b128 v[240:243], v159 offset:2048
	ds_read_b128 v[244:247], v159 offset:3072
	global_load_lds_dwordx4 v[212:213], off
	v_lshl_add_u64 v[248:249], s[20:21], 0, v[130:131]
	s_add_i32 m0, s58, 0x2000
	s_nop 0
	global_load_lds_dwordx4 v[248:249], off
	s_barrier
	s_waitcnt lgkmcnt(0)
	v_mfma_f32_16x16x32_bf16 v[118:121], v[232:235], v[176:179], v[118:121]
	v_mfma_f32_16x16x32_bf16 v[114:117], v[240:243], v[176:179], v[114:117]
	v_mfma_f32_16x16x32_bf16 v[102:105], v[232:235], v[196:199], v[102:105]
	v_mfma_f32_16x16x32_bf16 v[98:101], v[240:243], v[196:199], v[98:101]
	v_mfma_f32_16x16x32_bf16 v[86:89], v[232:235], v[204:207], v[86:89]
	v_mfma_f32_16x16x32_bf16 v[82:85], v[240:243], v[204:207], v[82:85]
	v_mfma_f32_16x16x32_bf16 v[70:73], v[232:235], v[224:227], v[70:73]
	v_mfma_f32_16x16x32_bf16 v[66:69], v[240:243], v[224:227], v[66:69]
	v_mfma_f32_16x16x32_bf16 v[118:121], v[236:239], v[192:195], v[118:121]
	v_mfma_f32_16x16x32_bf16 v[114:117], v[244:247], v[192:195], v[114:117]
	v_mfma_f32_16x16x32_bf16 v[102:105], v[236:239], v[200:203], v[102:105]
	v_mfma_f32_16x16x32_bf16 v[98:101], v[244:247], v[200:203], v[98:101]
	v_mfma_f32_16x16x32_bf16 v[86:89], v[236:239], v[208:211], v[86:89]
	v_mfma_f32_16x16x32_bf16 v[82:85], v[244:247], v[208:211], v[82:85]
	v_mfma_f32_16x16x32_bf16 v[70:73], v[236:239], v[228:231], v[70:73]
	v_mfma_f32_16x16x32_bf16 v[66:69], v[244:247], v[228:231], v[66:69]
	s_mov_b32 m0, s44
	v_lshl_add_u64 v[250:251], s[22:23], 0, v[136:137]
	s_barrier
	ds_read_b128 v[176:179], v158 offset:16384
	ds_read_b128 v[192:195], v158 offset:17408
	ds_read_b128 v[196:199], v158 offset:18432
	ds_read_b128 v[200:203], v158 offset:19456
	ds_read_b128 v[204:207], v158 offset:20480
	ds_read_b128 v[208:211], v158 offset:21504
	ds_read_b128 v[224:227], v158 offset:22528
	ds_read_b128 v[228:231], v158 offset:23552
	global_load_lds_dwordx4 v[250:251], off
	v_lshl_add_u64 v[222:223], s[22:23], 0, v[132:133]
	s_mov_b32 m0, s45
	s_nop 0
	global_load_lds_dwordx4 v[222:223], off
	s_waitcnt vmcnt(10)
	s_barrier
	s_waitcnt lgkmcnt(0)
	v_mfma_f32_16x16x32_bf16 v[62:65], v[160:163], v[176:179], v[62:65]
	v_mfma_f32_16x16x32_bf16 v[58:61], v[168:171], v[176:179], v[58:61]
	v_mfma_f32_16x16x32_bf16 v[46:49], v[160:163], v[196:199], v[46:49]
	v_mfma_f32_16x16x32_bf16 v[42:45], v[168:171], v[196:199], v[42:45]
	v_mfma_f32_16x16x32_bf16 v[30:33], v[160:163], v[204:207], v[30:33]
	v_mfma_f32_16x16x32_bf16 v[26:29], v[168:171], v[204:207], v[26:29]
	v_mfma_f32_16x16x32_bf16 v[14:17], v[160:163], v[224:227], v[14:17]
	v_mfma_f32_16x16x32_bf16 v[10:13], v[168:171], v[224:227], v[10:13]
	v_mfma_f32_16x16x32_bf16 v[62:65], v[164:167], v[192:195], v[62:65]
	v_mfma_f32_16x16x32_bf16 v[58:61], v[172:175], v[192:195], v[58:61]
	v_mfma_f32_16x16x32_bf16 v[46:49], v[164:167], v[200:203], v[46:49]
	v_mfma_f32_16x16x32_bf16 v[42:45], v[172:175], v[200:203], v[42:45]
	v_mfma_f32_16x16x32_bf16 v[30:33], v[164:167], v[208:211], v[30:33]
	v_mfma_f32_16x16x32_bf16 v[26:29], v[172:175], v[208:211], v[26:29]
	v_mfma_f32_16x16x32_bf16 v[14:17], v[164:167], v[228:231], v[14:17]
	v_mfma_f32_16x16x32_bf16 v[10:13], v[172:175], v[228:231], v[10:13]
	s_barrier
	s_add_u32 s58, s20, 0x80000
	s_addc_u32 s59, s21, 0
	s_add_i32 s82, s82, s29
	v_lshl_add_u64 v[160:161], s[58:59], 0, v[134:135]
	s_mov_b32 m0, s82
	s_nop 0
	global_load_lds_dwordx4 v[160:161], off
	v_lshl_add_u64 v[160:161], s[58:59], 0, v[130:131]
	s_add_i32 m0, s82, 0x2000
	s_nop 0
	global_load_lds_dwordx4 v[160:161], off
	v_add_u32_e32 v159, 0x18000, v1
	ds_read_b128 v[160:163], v159
	ds_read_b128 v[164:167], v159 offset:1024
	ds_read_b128 v[168:171], v159 offset:2048
	ds_read_b128 v[172:175], v159 offset:3072
	s_waitcnt vmcnt(6)
	s_barrier
	v_mfma_f32_16x16x32_bf16 v[54:57], v[232:235], v[176:179], v[54:57]
	v_mfma_f32_16x16x32_bf16 v[50:53], v[240:243], v[176:179], v[50:53]
	v_mfma_f32_16x16x32_bf16 v[38:41], v[232:235], v[196:199], v[38:41]
	v_mfma_f32_16x16x32_bf16 v[34:37], v[240:243], v[196:199], v[34:37]
	v_mfma_f32_16x16x32_bf16 v[22:25], v[232:235], v[204:207], v[22:25]
	v_mfma_f32_16x16x32_bf16 v[18:21], v[240:243], v[204:207], v[18:21]
	v_mfma_f32_16x16x32_bf16 v[6:9], v[232:235], v[224:227], v[6:9]
	v_mfma_f32_16x16x32_bf16 v[2:5], v[240:243], v[224:227], v[2:5]
	v_mfma_f32_16x16x32_bf16 v[54:57], v[236:239], v[192:195], v[54:57]
	v_mfma_f32_16x16x32_bf16 v[50:53], v[244:247], v[192:195], v[50:53]
	v_mfma_f32_16x16x32_bf16 v[38:41], v[236:239], v[200:203], v[38:41]
	v_mfma_f32_16x16x32_bf16 v[34:37], v[244:247], v[200:203], v[34:37]
	v_mfma_f32_16x16x32_bf16 v[22:25], v[236:239], v[208:211], v[22:25]
	v_mfma_f32_16x16x32_bf16 v[18:21], v[244:247], v[208:211], v[18:21]
	v_mfma_f32_16x16x32_bf16 v[6:9], v[236:239], v[228:231], v[6:9]
	v_mfma_f32_16x16x32_bf16 v[2:5], v[244:247], v[228:231], v[2:5]
	s_add_i32 s58, 0, 0x18000
	s_barrier
	s_add_u32 s22, s22, 0x80000
	s_addc_u32 s23, s23, 0
	s_mov_b32 m0, s46
	v_lshl_add_u64 v[232:233], s[22:23], 0, v[136:137]
	ds_read_b128 v[176:179], v158 offset:32768
	ds_read_b128 v[192:195], v158 offset:33792
	ds_read_b128 v[196:199], v158 offset:34816
	ds_read_b128 v[200:203], v158 offset:35840
	ds_read_b128 v[204:207], v158 offset:36864
	ds_read_b128 v[208:211], v158 offset:37888
	ds_read_b128 v[224:227], v158 offset:38912
	ds_read_b128 v[228:231], v158 offset:39936
	global_load_lds_dwordx4 v[232:233], off
	v_lshl_add_u64 v[232:233], s[22:23], 0, v[132:133]
	s_mov_b32 m0, s47
	s_nop 0
	global_load_lds_dwordx4 v[232:233], off
	s_waitcnt lgkmcnt(8)
	s_barrier
	s_waitcnt lgkmcnt(0)
	v_mfma_f32_16x16x32_bf16 v[126:129], v[160:163], v[176:179], v[126:129]
	v_mfma_f32_16x16x32_bf16 v[122:125], v[168:171], v[176:179], v[122:125]
	v_mfma_f32_16x16x32_bf16 v[110:113], v[160:163], v[196:199], v[110:113]
	v_mfma_f32_16x16x32_bf16 v[106:109], v[168:171], v[196:199], v[106:109]
	v_mfma_f32_16x16x32_bf16 v[94:97], v[160:163], v[204:207], v[94:97]
	v_mfma_f32_16x16x32_bf16 v[90:93], v[168:171], v[204:207], v[90:93]
	v_mfma_f32_16x16x32_bf16 v[78:81], v[160:163], v[224:227], v[78:81]
	v_mfma_f32_16x16x32_bf16 v[74:77], v[168:171], v[224:227], v[74:77]
	v_mfma_f32_16x16x32_bf16 v[126:129], v[164:167], v[192:195], v[126:129]
	v_mfma_f32_16x16x32_bf16 v[122:125], v[172:175], v[192:195], v[122:125]
	v_mfma_f32_16x16x32_bf16 v[110:113], v[164:167], v[200:203], v[110:113]
	v_mfma_f32_16x16x32_bf16 v[106:109], v[172:175], v[200:203], v[106:109]
	v_mfma_f32_16x16x32_bf16 v[94:97], v[164:167], v[208:211], v[94:97]
	v_mfma_f32_16x16x32_bf16 v[90:93], v[172:175], v[208:211], v[90:93]
	v_mfma_f32_16x16x32_bf16 v[78:81], v[164:167], v[228:231], v[78:81]
	v_mfma_f32_16x16x32_bf16 v[74:77], v[172:175], v[228:231], v[74:77]
	s_barrier
	s_add_i32 s22, 0, 0x1c000
	s_add_i32 s23, s58, s29
	v_add_u32_e32 v159, s22, v1
	v_lshl_add_u64 v[212:213], v[212:213], 0, s[78:79]
	s_mov_b32 m0, s23
	ds_read_b128 v[232:235], v159
	ds_read_b128 v[236:239], v159 offset:1024
	ds_read_b128 v[240:243], v159 offset:2048
	ds_read_b128 v[244:247], v159 offset:3072
	global_load_lds_dwordx4 v[212:213], off
	v_lshl_add_u64 v[212:213], v[248:249], 0, s[78:79]
	s_add_i32 m0, s23, 0x2000
	s_nop 0
	global_load_lds_dwordx4 v[212:213], off
	s_barrier
	s_waitcnt lgkmcnt(0)
	v_mfma_f32_16x16x32_bf16 v[118:121], v[232:235], v[176:179], v[118:121]
	v_mfma_f32_16x16x32_bf16 v[114:117], v[240:243], v[176:179], v[114:117]
	v_mfma_f32_16x16x32_bf16 v[102:105], v[232:235], v[196:199], v[102:105]
	v_mfma_f32_16x16x32_bf16 v[98:101], v[240:243], v[196:199], v[98:101]
	v_mfma_f32_16x16x32_bf16 v[86:89], v[232:235], v[204:207], v[86:89]
	v_mfma_f32_16x16x32_bf16 v[82:85], v[240:243], v[204:207], v[82:85]
	v_mfma_f32_16x16x32_bf16 v[70:73], v[232:235], v[224:227], v[70:73]
	v_mfma_f32_16x16x32_bf16 v[66:69], v[240:243], v[224:227], v[66:69]
	v_mfma_f32_16x16x32_bf16 v[118:121], v[236:239], v[192:195], v[118:121]
	v_mfma_f32_16x16x32_bf16 v[114:117], v[244:247], v[192:195], v[114:117]
	v_mfma_f32_16x16x32_bf16 v[102:105], v[236:239], v[200:203], v[102:105]
	v_mfma_f32_16x16x32_bf16 v[98:101], v[244:247], v[200:203], v[98:101]
	v_mfma_f32_16x16x32_bf16 v[86:89], v[236:239], v[208:211], v[86:89]
	v_mfma_f32_16x16x32_bf16 v[82:85], v[244:247], v[208:211], v[82:85]
	v_mfma_f32_16x16x32_bf16 v[70:73], v[236:239], v[228:231], v[70:73]
	v_mfma_f32_16x16x32_bf16 v[66:69], v[244:247], v[228:231], v[66:69]
	s_mov_b32 m0, s48
	v_lshl_add_u64 v[212:213], v[250:251], 0, s[78:79]
	s_barrier
	ds_read_b128 v[176:179], v158 offset:49152
	ds_read_b128 v[192:195], v158 offset:50176
	ds_read_b128 v[196:199], v158 offset:51200
	ds_read_b128 v[200:203], v158 offset:52224
	ds_read_b128 v[204:207], v158 offset:53248
	ds_read_b128 v[208:211], v158 offset:54272
	ds_read_b128 v[224:227], v158 offset:55296
	ds_read_b128 v[228:231], v158 offset:56320
	global_load_lds_dwordx4 v[212:213], off
	v_lshl_add_u64 v[212:213], v[222:223], 0, s[78:79]
	s_mov_b32 m0, s49
	s_nop 0
	global_load_lds_dwordx4 v[212:213], off
	s_waitcnt vmcnt(10)
	s_barrier
	s_waitcnt lgkmcnt(0)
	v_mfma_f32_16x16x32_bf16 v[62:65], v[160:163], v[176:179], v[62:65]
	v_mfma_f32_16x16x32_bf16 v[58:61], v[168:171], v[176:179], v[58:61]
	v_mfma_f32_16x16x32_bf16 v[46:49], v[160:163], v[196:199], v[46:49]
	v_mfma_f32_16x16x32_bf16 v[42:45], v[168:171], v[196:199], v[42:45]
	v_mfma_f32_16x16x32_bf16 v[30:33], v[160:163], v[204:207], v[30:33]
	v_mfma_f32_16x16x32_bf16 v[26:29], v[168:171], v[204:207], v[26:29]
	v_mfma_f32_16x16x32_bf16 v[14:17], v[160:163], v[224:227], v[14:17]
	v_mfma_f32_16x16x32_bf16 v[10:13], v[168:171], v[224:227], v[10:13]
	v_mfma_f32_16x16x32_bf16 v[62:65], v[164:167], v[192:195], v[62:65]
	v_mfma_f32_16x16x32_bf16 v[58:61], v[172:175], v[192:195], v[58:61]
	v_mfma_f32_16x16x32_bf16 v[46:49], v[164:167], v[200:203], v[46:49]
	v_mfma_f32_16x16x32_bf16 v[42:45], v[172:175], v[200:203], v[42:45]
	v_mfma_f32_16x16x32_bf16 v[30:33], v[164:167], v[208:211], v[30:33]
	v_mfma_f32_16x16x32_bf16 v[26:29], v[172:175], v[208:211], v[26:29]
	v_mfma_f32_16x16x32_bf16 v[14:17], v[164:167], v[228:231], v[14:17]
	v_mfma_f32_16x16x32_bf16 v[10:13], v[172:175], v[228:231], v[10:13]
	s_barrier
	s_add_u32 s20, s20, 0x80080
	s_addc_u32 s21, s21, 0
	s_add_i32 s22, s22, s29
	v_lshl_add_u64 v[160:161], s[20:21], 0, v[134:135]
	s_mov_b32 m0, s22
	s_nop 0
	global_load_lds_dwordx4 v[160:161], off
	v_lshl_add_u64 v[160:161], s[20:21], 0, v[130:131]
	s_add_i32 m0, s22, 0x2000
	s_nop 0
	global_load_lds_dwordx4 v[160:161], off
	v_add_u32_e32 v159, 0x10000, v1
	ds_read_b128 v[160:163], v159
	ds_read_b128 v[164:167], v159 offset:1024
	ds_read_b128 v[168:171], v159 offset:2048
	ds_read_b128 v[172:175], v159 offset:3072
	s_waitcnt vmcnt(6)
	s_barrier
	v_mfma_f32_16x16x32_bf16 v[54:57], v[232:235], v[176:179], v[54:57]
	v_mfma_f32_16x16x32_bf16 v[50:53], v[240:243], v[176:179], v[50:53]
	v_mfma_f32_16x16x32_bf16 v[38:41], v[232:235], v[196:199], v[38:41]
	v_mfma_f32_16x16x32_bf16 v[34:37], v[240:243], v[196:199], v[34:37]
	v_mfma_f32_16x16x32_bf16 v[22:25], v[232:235], v[204:207], v[22:25]
	v_mfma_f32_16x16x32_bf16 v[18:21], v[240:243], v[204:207], v[18:21]
	v_mfma_f32_16x16x32_bf16 v[6:9], v[232:235], v[224:227], v[6:9]
	v_mfma_f32_16x16x32_bf16 v[2:5], v[240:243], v[224:227], v[2:5]
	v_mfma_f32_16x16x32_bf16 v[54:57], v[236:239], v[192:195], v[54:57]
	v_mfma_f32_16x16x32_bf16 v[50:53], v[244:247], v[192:195], v[50:53]
	v_mfma_f32_16x16x32_bf16 v[38:41], v[236:239], v[200:203], v[38:41]
	v_mfma_f32_16x16x32_bf16 v[34:37], v[244:247], v[200:203], v[34:37]
	v_mfma_f32_16x16x32_bf16 v[22:25], v[236:239], v[208:211], v[22:25]
	v_mfma_f32_16x16x32_bf16 v[18:21], v[244:247], v[208:211], v[18:21]
	v_mfma_f32_16x16x32_bf16 v[6:9], v[236:239], v[228:231], v[6:9]
	v_mfma_f32_16x16x32_bf16 v[2:5], v[244:247], v[228:231], v[2:5]
	s_add_i32 s57, s57, 2
	s_add_u32 s18, s18, 0x100
	s_addc_u32 s19, s19, 0
	s_add_u32 s55, s55, 0x100
	s_addc_u32 s56, s56, 0
	s_cmp_gt_u32 s57, 29
	s_barrier
	s_cbranch_scc0 .LBB0_749
	s_waitcnt lgkmcnt(0)
	s_lshl_b32 s18, s52, 5
	s_add_i32 s18, s18, s51
	v_max_f32_e32 v122, 0, v122
	v_max_f32_e32 v123, 0, v123
	s_ashr_i32 s19, s18, 31
	v_pk_mul_f32 v[162:163], v[122:123], v[122:123]
	v_max_f32_e32 v123, v124, v124
	s_lshl_b64 s[18:19], s[18:19], 17
	v_max_f32_e32 v122, v128, v128
	v_max_f32_e32 v124, 0, v123
	v_max_f32_e32 v123, v129, v129
	s_add_u32 s18, s68, s18
	v_max_f32_e32 v126, 0, v126
	v_max_f32_e32 v127, 0, v127
	v_max_f32_e32 v122, 0, v122
	v_max_f32_e32 v123, 0, v123
	v_max_f32_e32 v125, 0, v125
	s_addc_u32 s19, s69, s19
	v_pk_mul_f32 v[126:127], v[126:127], v[126:127]
	v_pk_mul_f32 v[128:129], v[122:123], v[122:123]
	v_pk_mul_f32 v[164:165], v[124:125], v[124:125]
	v_lshl_add_u64 v[160:161], v[138:139], 1, s[18:19]
	v_cvt_pk_bf16_f32 v122, v126, v127
	v_cvt_pk_bf16_f32 v123, v128, v129
	v_cvt_pk_bf16_f32 v124, v162, v163
	v_cvt_pk_bf16_f32 v125, v164, v165
	v_max_f32_e32 v114, 0, v114
	v_max_f32_e32 v115, 0, v115
	global_store_dwordx4 v[160:161], v[122:125], off
	v_max_f32_e32 v118, v118, v118
	v_max_f32_e32 v119, v119, v119
	v_pk_mul_f32 v[122:123], v[114:115], v[114:115]
	v_max_f32_e32 v115, v116, v116
	v_max_f32_e32 v114, v120, v120
	v_max_f32_e32 v116, 0, v115
	v_max_f32_e32 v115, v121, v121
	v_max_f32_e32 v118, 0, v118
	v_max_f32_e32 v119, 0, v119
	v_max_f32_e32 v114, 0, v114
	v_max_f32_e32 v115, 0, v115
	v_max_f32_e32 v117, 0, v117
	v_pk_mul_f32 v[118:119], v[118:119], v[118:119]
	v_pk_mul_f32 v[120:121], v[114:115], v[114:115]
	v_pk_mul_f32 v[124:125], v[116:117], v[116:117]
	v_cvt_pk_bf16_f32 v114, v118, v119
	v_cvt_pk_bf16_f32 v115, v120, v121
	v_cvt_pk_bf16_f32 v116, v122, v123
	v_cvt_pk_bf16_f32 v117, v124, v125
	v_max_f32_e32 v106, 0, v106
	v_max_f32_e32 v107, 0, v107
	global_store_dwordx4 v[160:161], v[114:117], off offset:256
	v_max_f32_e32 v110, v110, v110
	v_max_f32_e32 v111, v111, v111
	v_pk_mul_f32 v[116:117], v[106:107], v[106:107]
	v_max_f32_e32 v107, v108, v108
	v_max_f32_e32 v106, v112, v112
	v_max_f32_e32 v108, 0, v107
	v_max_f32_e32 v107, v113, v113
	v_max_f32_e32 v110, 0, v110
	v_max_f32_e32 v111, 0, v111
	v_max_f32_e32 v106, 0, v106
	v_max_f32_e32 v107, 0, v107
	v_max_f32_e32 v109, 0, v109
	v_pk_mul_f32 v[110:111], v[110:111], v[110:111]
	v_pk_mul_f32 v[112:113], v[106:107], v[106:107]
	v_pk_mul_f32 v[118:119], v[108:109], v[108:109]
	v_lshl_add_u64 v[114:115], v[140:141], 1, s[18:19]
	v_cvt_pk_bf16_f32 v106, v110, v111
	v_cvt_pk_bf16_f32 v107, v112, v113
	v_cvt_pk_bf16_f32 v108, v116, v117
	v_cvt_pk_bf16_f32 v109, v118, v119
	v_max_f32_e32 v98, 0, v98
	v_max_f32_e32 v99, 0, v99
	global_store_dwordx4 v[114:115], v[106:109], off
	v_max_f32_e32 v102, v102, v102
	v_max_f32_e32 v103, v103, v103
	v_pk_mul_f32 v[106:107], v[98:99], v[98:99]
	v_max_f32_e32 v99, v100, v100
	v_max_f32_e32 v98, v104, v104
	v_max_f32_e32 v100, 0, v99
	v_max_f32_e32 v99, v105, v105
	v_max_f32_e32 v102, 0, v102
	v_max_f32_e32 v103, 0, v103
	v_max_f32_e32 v98, 0, v98
	v_max_f32_e32 v99, 0, v99
	v_max_f32_e32 v101, 0, v101
	v_pk_mul_f32 v[102:103], v[102:103], v[102:103]
	v_pk_mul_f32 v[104:105], v[98:99], v[98:99]
	v_pk_mul_f32 v[108:109], v[100:101], v[100:101]
	v_cvt_pk_bf16_f32 v98, v102, v103
	v_cvt_pk_bf16_f32 v99, v104, v105
	v_cvt_pk_bf16_f32 v100, v106, v107
	v_cvt_pk_bf16_f32 v101, v108, v109
	v_max_f32_e32 v90, 0, v90
	v_max_f32_e32 v91, 0, v91
	global_store_dwordx4 v[114:115], v[98:101], off offset:256
	v_max_f32_e32 v94, v94, v94
	v_max_f32_e32 v95, v95, v95
	v_pk_mul_f32 v[100:101], v[90:91], v[90:91]
	v_max_f32_e32 v91, v92, v92
	v_max_f32_e32 v90, v96, v96
	v_max_f32_e32 v92, 0, v91
	v_max_f32_e32 v91, v97, v97
	v_max_f32_e32 v94, 0, v94
	v_max_f32_e32 v95, 0, v95
	v_max_f32_e32 v90, 0, v90
	v_max_f32_e32 v91, 0, v91
	v_max_f32_e32 v93, 0, v93
	v_pk_mul_f32 v[94:95], v[94:95], v[94:95]
	v_pk_mul_f32 v[96:97], v[90:91], v[90:91]
	v_pk_mul_f32 v[102:103], v[92:93], v[92:93]
	v_lshl_add_u64 v[98:99], v[142:143], 1, s[18:19]
	v_cvt_pk_bf16_f32 v90, v94, v95
	v_cvt_pk_bf16_f32 v91, v96, v97
	v_cvt_pk_bf16_f32 v92, v100, v101
	v_cvt_pk_bf16_f32 v93, v102, v103
	v_max_f32_e32 v82, 0, v82
	v_max_f32_e32 v83, 0, v83
	global_store_dwordx4 v[98:99], v[90:93], off
	v_max_f32_e32 v86, v86, v86
	v_max_f32_e32 v87, v87, v87
	v_pk_mul_f32 v[90:91], v[82:83], v[82:83]
	v_max_f32_e32 v83, v84, v84
	v_max_f32_e32 v82, v88, v88
	v_max_f32_e32 v84, 0, v83
	v_max_f32_e32 v83, v89, v89
	v_max_f32_e32 v86, 0, v86
	v_max_f32_e32 v87, 0, v87
	v_max_f32_e32 v82, 0, v82
	v_max_f32_e32 v83, 0, v83
	v_max_f32_e32 v85, 0, v85
	v_pk_mul_f32 v[86:87], v[86:87], v[86:87]
	v_pk_mul_f32 v[88:89], v[82:83], v[82:83]
	v_pk_mul_f32 v[92:93], v[84:85], v[84:85]
	v_cvt_pk_bf16_f32 v82, v86, v87
	v_cvt_pk_bf16_f32 v83, v88, v89
	v_cvt_pk_bf16_f32 v84, v90, v91
	v_cvt_pk_bf16_f32 v85, v92, v93
	v_max_f32_e32 v74, 0, v74
	v_max_f32_e32 v75, 0, v75
	global_store_dwordx4 v[98:99], v[82:85], off offset:256
	v_max_f32_e32 v78, v78, v78
	v_max_f32_e32 v79, v79, v79
	v_pk_mul_f32 v[84:85], v[74:75], v[74:75]
	v_max_f32_e32 v75, v76, v76
	v_max_f32_e32 v74, v80, v80
	v_max_f32_e32 v76, 0, v75
	v_max_f32_e32 v75, v81, v81
	v_max_f32_e32 v78, 0, v78
	v_max_f32_e32 v79, 0, v79
	v_max_f32_e32 v74, 0, v74
	v_max_f32_e32 v75, 0, v75
	v_max_f32_e32 v77, 0, v77
	v_pk_mul_f32 v[78:79], v[78:79], v[78:79]
	v_pk_mul_f32 v[80:81], v[74:75], v[74:75]
	v_pk_mul_f32 v[86:87], v[76:77], v[76:77]
	v_lshl_add_u64 v[82:83], v[144:145], 1, s[18:19]
	v_cvt_pk_bf16_f32 v74, v78, v79
	v_cvt_pk_bf16_f32 v75, v80, v81
	v_cvt_pk_bf16_f32 v76, v84, v85
	v_cvt_pk_bf16_f32 v77, v86, v87
	v_max_f32_e32 v66, 0, v66
	v_max_f32_e32 v67, 0, v67
	global_store_dwordx4 v[82:83], v[74:77], off
	v_max_f32_e32 v70, v70, v70
	v_max_f32_e32 v71, v71, v71
	v_pk_mul_f32 v[74:75], v[66:67], v[66:67]
	v_max_f32_e32 v67, v68, v68
	v_max_f32_e32 v66, v72, v72
	v_max_f32_e32 v68, 0, v67
	v_max_f32_e32 v67, v73, v73
	v_max_f32_e32 v70, 0, v70
	v_max_f32_e32 v71, 0, v71
	v_max_f32_e32 v66, 0, v66
	v_max_f32_e32 v67, 0, v67
	v_max_f32_e32 v69, 0, v69
	v_pk_mul_f32 v[70:71], v[70:71], v[70:71]
	v_pk_mul_f32 v[72:73], v[66:67], v[66:67]
	v_pk_mul_f32 v[76:77], v[68:69], v[68:69]
	v_cvt_pk_bf16_f32 v66, v70, v71
	v_cvt_pk_bf16_f32 v67, v72, v73
	v_cvt_pk_bf16_f32 v68, v74, v75
	v_cvt_pk_bf16_f32 v69, v76, v77
	v_max_f32_e32 v58, 0, v58
	v_max_f32_e32 v59, 0, v59
	global_store_dwordx4 v[82:83], v[66:69], off offset:256
	v_max_f32_e32 v62, v62, v62
	v_max_f32_e32 v63, v63, v63
	v_pk_mul_f32 v[68:69], v[58:59], v[58:59]
	v_max_f32_e32 v59, v60, v60
	v_max_f32_e32 v58, v64, v64
	v_max_f32_e32 v60, 0, v59
	v_max_f32_e32 v59, v65, v65
	v_max_f32_e32 v62, 0, v62
	v_max_f32_e32 v63, 0, v63
	v_max_f32_e32 v58, 0, v58
	v_max_f32_e32 v59, 0, v59
	v_max_f32_e32 v61, 0, v61
	v_pk_mul_f32 v[62:63], v[62:63], v[62:63]
	v_pk_mul_f32 v[64:65], v[58:59], v[58:59]
	v_pk_mul_f32 v[70:71], v[60:61], v[60:61]
	v_lshl_add_u64 v[66:67], v[146:147], 1, s[18:19]
	v_cvt_pk_bf16_f32 v58, v62, v63
	v_cvt_pk_bf16_f32 v59, v64, v65
	v_cvt_pk_bf16_f32 v60, v68, v69
	v_cvt_pk_bf16_f32 v61, v70, v71
	v_max_f32_e32 v50, 0, v50
	v_max_f32_e32 v51, 0, v51
	global_store_dwordx4 v[66:67], v[58:61], off
	v_max_f32_e32 v54, v54, v54
	v_max_f32_e32 v55, v55, v55
	v_pk_mul_f32 v[58:59], v[50:51], v[50:51]
	v_max_f32_e32 v51, v52, v52
	v_max_f32_e32 v50, v56, v56
	v_max_f32_e32 v52, 0, v51
	v_max_f32_e32 v51, v57, v57
	v_max_f32_e32 v54, 0, v54
	v_max_f32_e32 v55, 0, v55
	v_max_f32_e32 v50, 0, v50
	v_max_f32_e32 v51, 0, v51
	v_max_f32_e32 v53, 0, v53
	v_pk_mul_f32 v[54:55], v[54:55], v[54:55]
	v_pk_mul_f32 v[56:57], v[50:51], v[50:51]
	v_pk_mul_f32 v[60:61], v[52:53], v[52:53]
	v_cvt_pk_bf16_f32 v50, v54, v55
	v_cvt_pk_bf16_f32 v51, v56, v57
	v_cvt_pk_bf16_f32 v52, v58, v59
	v_cvt_pk_bf16_f32 v53, v60, v61
	v_max_f32_e32 v42, 0, v42
	v_max_f32_e32 v43, 0, v43
	global_store_dwordx4 v[66:67], v[50:53], off offset:256
	v_max_f32_e32 v46, v46, v46
	v_max_f32_e32 v47, v47, v47
	v_pk_mul_f32 v[52:53], v[42:43], v[42:43]
	v_max_f32_e32 v43, v44, v44
	v_max_f32_e32 v42, v48, v48
	v_max_f32_e32 v44, 0, v43
	v_max_f32_e32 v43, v49, v49
	v_max_f32_e32 v46, 0, v46
	v_max_f32_e32 v47, 0, v47
	v_max_f32_e32 v42, 0, v42
	v_max_f32_e32 v43, 0, v43
	v_max_f32_e32 v45, 0, v45
	v_pk_mul_f32 v[46:47], v[46:47], v[46:47]
	v_pk_mul_f32 v[48:49], v[42:43], v[42:43]
	v_pk_mul_f32 v[54:55], v[44:45], v[44:45]
	v_lshl_add_u64 v[50:51], v[148:149], 1, s[18:19]
	v_cvt_pk_bf16_f32 v42, v46, v47
	v_cvt_pk_bf16_f32 v43, v48, v49
	v_cvt_pk_bf16_f32 v44, v52, v53
	v_cvt_pk_bf16_f32 v45, v54, v55
	v_max_f32_e32 v34, 0, v34
	v_max_f32_e32 v35, 0, v35
	global_store_dwordx4 v[50:51], v[42:45], off
	v_max_f32_e32 v38, v38, v38
	v_max_f32_e32 v39, v39, v39
	v_pk_mul_f32 v[42:43], v[34:35], v[34:35]
	v_max_f32_e32 v35, v36, v36
	v_max_f32_e32 v34, v40, v40
	v_max_f32_e32 v36, 0, v35
	v_max_f32_e32 v35, v41, v41
	v_max_f32_e32 v38, 0, v38
	v_max_f32_e32 v39, 0, v39
	v_max_f32_e32 v34, 0, v34
	v_max_f32_e32 v35, 0, v35
	v_max_f32_e32 v37, 0, v37
	v_pk_mul_f32 v[38:39], v[38:39], v[38:39]
	v_pk_mul_f32 v[40:41], v[34:35], v[34:35]
	v_pk_mul_f32 v[44:45], v[36:37], v[36:37]
	v_cvt_pk_bf16_f32 v34, v38, v39
	v_cvt_pk_bf16_f32 v35, v40, v41
	v_cvt_pk_bf16_f32 v36, v42, v43
	v_cvt_pk_bf16_f32 v37, v44, v45
	v_max_f32_e32 v26, 0, v26
	v_max_f32_e32 v27, 0, v27
	global_store_dwordx4 v[50:51], v[34:37], off offset:256
	v_max_f32_e32 v30, v30, v30
	v_max_f32_e32 v31, v31, v31
	v_pk_mul_f32 v[36:37], v[26:27], v[26:27]
	v_max_f32_e32 v27, v28, v28
	v_max_f32_e32 v26, v32, v32
	v_max_f32_e32 v28, 0, v27
	v_max_f32_e32 v27, v33, v33
	v_max_f32_e32 v30, 0, v30
	v_max_f32_e32 v31, 0, v31
	v_max_f32_e32 v26, 0, v26
	v_max_f32_e32 v27, 0, v27
	v_max_f32_e32 v29, 0, v29
	v_pk_mul_f32 v[30:31], v[30:31], v[30:31]
	v_pk_mul_f32 v[32:33], v[26:27], v[26:27]
	v_pk_mul_f32 v[38:39], v[28:29], v[28:29]
	v_lshl_add_u64 v[34:35], v[150:151], 1, s[18:19]
	v_cvt_pk_bf16_f32 v26, v30, v31
	v_cvt_pk_bf16_f32 v27, v32, v33
	v_cvt_pk_bf16_f32 v28, v36, v37
	v_cvt_pk_bf16_f32 v29, v38, v39
	v_max_f32_e32 v18, 0, v18
	v_max_f32_e32 v19, 0, v19
	global_store_dwordx4 v[34:35], v[26:29], off
	v_max_f32_e32 v22, v22, v22
	v_max_f32_e32 v23, v23, v23
	v_pk_mul_f32 v[26:27], v[18:19], v[18:19]
	v_max_f32_e32 v19, v20, v20
	v_max_f32_e32 v18, v24, v24
	v_max_f32_e32 v20, 0, v19
	v_max_f32_e32 v19, v25, v25
	v_max_f32_e32 v22, 0, v22
	v_max_f32_e32 v23, 0, v23
	v_max_f32_e32 v18, 0, v18
	v_max_f32_e32 v19, 0, v19
	v_max_f32_e32 v21, 0, v21
	v_pk_mul_f32 v[22:23], v[22:23], v[22:23]
	v_pk_mul_f32 v[24:25], v[18:19], v[18:19]
	v_pk_mul_f32 v[28:29], v[20:21], v[20:21]
	v_cvt_pk_bf16_f32 v18, v22, v23
	v_cvt_pk_bf16_f32 v19, v24, v25
	v_cvt_pk_bf16_f32 v20, v26, v27
	v_cvt_pk_bf16_f32 v21, v28, v29
	v_max_f32_e32 v10, 0, v10
	v_max_f32_e32 v11, 0, v11
	global_store_dwordx4 v[34:35], v[18:21], off offset:256
	v_max_f32_e32 v14, v14, v14
	v_max_f32_e32 v15, v15, v15
	v_pk_mul_f32 v[20:21], v[10:11], v[10:11]
	v_max_f32_e32 v11, v12, v12
	v_max_f32_e32 v10, v16, v16
	v_max_f32_e32 v12, 0, v11
	v_max_f32_e32 v11, v17, v17
	v_max_f32_e32 v14, 0, v14
	v_max_f32_e32 v15, 0, v15
	v_max_f32_e32 v10, 0, v10
	v_max_f32_e32 v11, 0, v11
	v_max_f32_e32 v13, 0, v13
	v_pk_mul_f32 v[14:15], v[14:15], v[14:15]
	v_pk_mul_f32 v[16:17], v[10:11], v[10:11]
	v_pk_mul_f32 v[22:23], v[12:13], v[12:13]
	v_lshl_add_u64 v[18:19], v[152:153], 1, s[18:19]
	v_cvt_pk_bf16_f32 v10, v14, v15
	v_cvt_pk_bf16_f32 v11, v16, v17
	v_cvt_pk_bf16_f32 v12, v20, v21
	v_cvt_pk_bf16_f32 v13, v22, v23
	v_max_f32_e32 v2, 0, v2
	v_max_f32_e32 v3, 0, v3
	global_store_dwordx4 v[18:19], v[10:13], off
	v_max_f32_e32 v6, v6, v6
	v_max_f32_e32 v7, v7, v7
	v_pk_mul_f32 v[10:11], v[2:3], v[2:3]
	v_max_f32_e32 v3, v4, v4
	v_max_f32_e32 v2, v8, v8
	v_max_f32_e32 v4, 0, v3
	v_max_f32_e32 v3, v9, v9
	v_max_f32_e32 v6, 0, v6
	v_max_f32_e32 v7, 0, v7
	v_max_f32_e32 v2, 0, v2
	v_max_f32_e32 v3, 0, v3
	v_max_f32_e32 v5, 0, v5
	v_pk_mul_f32 v[6:7], v[6:7], v[6:7]
	v_pk_mul_f32 v[8:9], v[2:3], v[2:3]
	v_pk_mul_f32 v[12:13], v[4:5], v[4:5]
	v_cvt_pk_bf16_f32 v2, v6, v7
	v_cvt_pk_bf16_f32 v3, v8, v9
	v_cvt_pk_bf16_f32 v4, v10, v11
	v_cvt_pk_bf16_f32 v5, v12, v13
	s_and_b64 vcc, exec, s[0:1]
	s_mov_b32 s51, s30
	s_mov_b32 s52, s38
	s_mov_b64 s[20:21], s[80:81]
	s_mov_b64 s[18:19], s[42:43]
	global_store_dwordx4 v[18:19], v[2:5], off offset:256
	s_cbranch_vccz .LBB0_742
	s_waitcnt vmcnt(0)
	v_readlane_b32 s38, v255, 28
	s_cmpk_gt_u32 s26, 0xff
	v_readlane_b32 s39, v255, 29
	v_readlane_b32 s42, v255, 32
	s_cbranch_scc1 .LBB0_753
	s_barrier

.LBB0_814:
	s_add_i32 s22, s55, 0xffff0000
	s_and_b32 s22, s22, 0x3e0000
	s_and_b32 s23, s90, 0x100
	s_or_b32 s56, s23, s22
	s_and_b32 s22, s55, 0x7e0000
	s_add_u32 vcc_lo, s90, 0x100
	s_addc_u32 vcc_hi, s91, 0
	s_and_b32 s23, vcc_lo, 0x100
	s_or_b32 s22, s22, s23
	s_add_u32 s22, s84, s22
	s_addc_u32 s23, s85, 0
	s_add_u32 s57, s30, s90
	s_addc_u32 s58, s31, s91
	s_add_u32 s57, s57, 0x100
	s_addc_u32 s58, s58, 0
	s_add_i32 s59, 0, 0x10000
	s_cmpk_eq_i32 s54, 0x7c
	s_cselect_b32 s91, s43, s58
	s_cselect_b32 s90, s53, s57
	s_cselect_b32 s23, s51, s23
	s_cselect_b32 s22, s52, s22
	s_add_u32 s56, s84, s56
	s_addc_u32 s57, s85, 0
	s_add_u32 s56, s56, 0x10080
	s_addc_u32 s57, s57, 0
	v_lshl_add_u64 v[204:205], s[56:57], 0, v[136:137]
	s_add_i32 m0, s28, 0xc000
	ds_read_b128 v[158:161], v140
	ds_read_b128 v[162:165], v140 offset:1024
	ds_read_b128 v[168:171], v140 offset:2048
	ds_read_b128 v[172:175], v140 offset:3072
	ds_read_b128 v[176:179], v140 offset:4096
	ds_read_b128 v[192:195], v140 offset:5120
	ds_read_b128 v[196:199], v140 offset:6144
	ds_read_b128 v[200:203], v140 offset:7168
	global_load_lds_dwordx4 v[204:205], off
	v_lshl_add_u64 v[204:205], s[56:57], 0, v[132:133]
	s_add_i32 m0, s28, 0xe000
	s_nop 0
	global_load_lds_dwordx4 v[204:205], off
	s_waitcnt lgkmcnt(8)
	s_barrier
	s_waitcnt lgkmcnt(0)
	v_mfma_f32_16x16x32_bf16 v[86:89], v[142:145], v[158:161], v[86:89]
	v_mfma_f32_16x16x32_bf16 v[94:97], v[150:153], v[158:161], v[94:97]
	v_mfma_f32_16x16x32_bf16 v[98:101], v[142:145], v[168:171], v[98:101]
	v_mfma_f32_16x16x32_bf16 v[102:105], v[150:153], v[168:171], v[102:105]
	v_mfma_f32_16x16x32_bf16 v[114:117], v[142:145], v[176:179], v[114:117]
	v_mfma_f32_16x16x32_bf16 v[122:125], v[150:153], v[176:179], v[122:125]
	v_mfma_f32_16x16x32_bf16 v[126:129], v[142:145], v[196:199], v[126:129]
	v_mfma_f32_16x16x32_bf16 v[118:121], v[150:153], v[196:199], v[118:121]
	v_mfma_f32_16x16x32_bf16 v[86:89], v[146:149], v[162:165], v[86:89]
	v_mfma_f32_16x16x32_bf16 v[94:97], v[154:157], v[162:165], v[94:97]
	v_mfma_f32_16x16x32_bf16 v[98:101], v[146:149], v[172:175], v[98:101]
	v_mfma_f32_16x16x32_bf16 v[102:105], v[154:157], v[172:175], v[102:105]
	v_mfma_f32_16x16x32_bf16 v[114:117], v[146:149], v[192:195], v[114:117]
	v_mfma_f32_16x16x32_bf16 v[122:125], v[154:157], v[192:195], v[122:125]
	v_mfma_f32_16x16x32_bf16 v[126:129], v[146:149], v[200:203], v[126:129]
	v_mfma_f32_16x16x32_bf16 v[118:121], v[154:157], v[200:203], v[118:121]
	s_barrier
	s_add_i32 s58, 0, 0x14000
	s_add_i32 s56, s59, s81
	v_add_u32_e32 v141, s58, v139
	v_lshl_add_u64 v[212:213], s[90:91], 0, v[134:135]
	s_mov_b32 m0, s56
	ds_read_b128 v[204:207], v141
	ds_read_b128 v[208:211], v141 offset:1024
	ds_read_b128 v[224:227], v141 offset:2048
	ds_read_b128 v[228:231], v141 offset:3072
	global_load_lds_dwordx4 v[212:213], off
	v_lshl_add_u64 v[222:223], s[90:91], 0, v[130:131]
	s_add_i32 m0, s56, 0x2000
	s_nop 0
	global_load_lds_dwordx4 v[222:223], off
	s_barrier
	s_waitcnt lgkmcnt(0)
	v_mfma_f32_16x16x32_bf16 v[2:5], v[204:207], v[158:161], v[2:5]
	v_mfma_f32_16x16x32_bf16 v[6:9], v[224:227], v[158:161], v[6:9]
	v_mfma_f32_16x16x32_bf16 v[10:13], v[204:207], v[168:171], v[10:13]
	v_mfma_f32_16x16x32_bf16 v[14:17], v[224:227], v[168:171], v[14:17]
	v_mfma_f32_16x16x32_bf16 v[22:25], v[204:207], v[176:179], v[22:25]
	v_mfma_f32_16x16x32_bf16 v[18:21], v[224:227], v[176:179], v[18:21]
	v_mfma_f32_16x16x32_bf16 v[30:33], v[204:207], v[196:199], v[30:33]
	v_mfma_f32_16x16x32_bf16 v[26:29], v[224:227], v[196:199], v[26:29]
	v_mfma_f32_16x16x32_bf16 v[2:5], v[208:211], v[162:165], v[2:5]
	v_mfma_f32_16x16x32_bf16 v[6:9], v[228:231], v[162:165], v[6:9]
	v_mfma_f32_16x16x32_bf16 v[10:13], v[208:211], v[172:175], v[10:13]
	v_mfma_f32_16x16x32_bf16 v[14:17], v[228:231], v[172:175], v[14:17]
	v_mfma_f32_16x16x32_bf16 v[22:25], v[208:211], v[192:195], v[22:25]
	v_mfma_f32_16x16x32_bf16 v[18:21], v[228:231], v[192:195], v[18:21]
	v_mfma_f32_16x16x32_bf16 v[30:33], v[208:211], v[200:203], v[30:33]
	v_mfma_f32_16x16x32_bf16 v[26:29], v[228:231], v[200:203], v[26:29]
	s_mov_b32 m0, s28
	v_lshl_add_u64 v[232:233], s[22:23], 0, v[136:137]
	s_barrier
	ds_read_b128 v[158:161], v140 offset:16384
	ds_read_b128 v[162:165], v140 offset:17408
	ds_read_b128 v[168:171], v140 offset:18432
	ds_read_b128 v[172:175], v140 offset:19456
	ds_read_b128 v[176:179], v140 offset:20480
	ds_read_b128 v[192:195], v140 offset:21504
	ds_read_b128 v[196:199], v140 offset:22528
	ds_read_b128 v[200:203], v140 offset:23552
	global_load_lds_dwordx4 v[232:233], off
	v_lshl_add_u64 v[234:235], s[22:23], 0, v[132:133]
	s_mov_b32 m0, s29
	s_nop 0
	global_load_lds_dwordx4 v[234:235], off
	s_waitcnt vmcnt(10)
	s_barrier
	s_waitcnt lgkmcnt(0)
	v_mfma_f32_16x16x32_bf16 v[110:113], v[142:145], v[158:161], v[110:113]
	v_mfma_f32_16x16x32_bf16 v[106:109], v[150:153], v[158:161], v[106:109]
	v_mfma_f32_16x16x32_bf16 v[90:93], v[142:145], v[168:171], v[90:93]
	v_mfma_f32_16x16x32_bf16 v[82:85], v[150:153], v[168:171], v[82:85]
	v_mfma_f32_16x16x32_bf16 v[78:81], v[142:145], v[176:179], v[78:81]
	v_mfma_f32_16x16x32_bf16 v[74:77], v[150:153], v[176:179], v[74:77]
	v_mfma_f32_16x16x32_bf16 v[70:73], v[142:145], v[196:199], v[70:73]
	v_mfma_f32_16x16x32_bf16 v[66:69], v[150:153], v[196:199], v[66:69]
	v_mfma_f32_16x16x32_bf16 v[110:113], v[146:149], v[162:165], v[110:113]
	v_mfma_f32_16x16x32_bf16 v[106:109], v[154:157], v[162:165], v[106:109]
	v_mfma_f32_16x16x32_bf16 v[90:93], v[146:149], v[172:175], v[90:93]
	v_mfma_f32_16x16x32_bf16 v[82:85], v[154:157], v[172:175], v[82:85]
	v_mfma_f32_16x16x32_bf16 v[78:81], v[146:149], v[192:195], v[78:81]
	v_mfma_f32_16x16x32_bf16 v[74:77], v[154:157], v[192:195], v[74:77]
	v_mfma_f32_16x16x32_bf16 v[70:73], v[146:149], v[200:203], v[70:73]
	v_mfma_f32_16x16x32_bf16 v[66:69], v[154:157], v[200:203], v[66:69]
	s_barrier
	s_add_u32 s56, s90, 0x200000
	s_addc_u32 s57, s91, 0
	s_add_i32 s58, s58, s81
	v_lshl_add_u64 v[142:143], s[56:57], 0, v[134:135]
	s_mov_b32 m0, s58
	s_nop 0
	global_load_lds_dwordx4 v[142:143], off
	v_lshl_add_u64 v[142:143], s[56:57], 0, v[130:131]
	s_add_i32 m0, s58, 0x2000
	s_nop 0
	global_load_lds_dwordx4 v[142:143], off
	v_add_u32_e32 v141, 0x18000, v139
	ds_read_b128 v[142:145], v141
	ds_read_b128 v[146:149], v141 offset:1024
	ds_read_b128 v[150:153], v141 offset:2048
	ds_read_b128 v[154:157], v141 offset:3072
	s_waitcnt vmcnt(6)
	s_barrier
	v_mfma_f32_16x16x32_bf16 v[38:41], v[204:207], v[158:161], v[38:41]
	v_mfma_f32_16x16x32_bf16 v[34:37], v[224:227], v[158:161], v[34:37]
	v_mfma_f32_16x16x32_bf16 v[46:49], v[204:207], v[168:171], v[46:49]
	v_mfma_f32_16x16x32_bf16 v[42:45], v[224:227], v[168:171], v[42:45]
	v_mfma_f32_16x16x32_bf16 v[54:57], v[204:207], v[176:179], v[54:57]
	v_mfma_f32_16x16x32_bf16 v[50:53], v[224:227], v[176:179], v[50:53]
	v_mfma_f32_16x16x32_bf16 v[62:65], v[204:207], v[196:199], v[62:65]
	v_mfma_f32_16x16x32_bf16 v[58:61], v[224:227], v[196:199], v[58:61]
	v_mfma_f32_16x16x32_bf16 v[38:41], v[208:211], v[162:165], v[38:41]
	v_mfma_f32_16x16x32_bf16 v[34:37], v[228:231], v[162:165], v[34:37]
	v_mfma_f32_16x16x32_bf16 v[46:49], v[208:211], v[172:175], v[46:49]
	v_mfma_f32_16x16x32_bf16 v[42:45], v[228:231], v[172:175], v[42:45]
	v_mfma_f32_16x16x32_bf16 v[54:57], v[208:211], v[192:195], v[54:57]
	v_mfma_f32_16x16x32_bf16 v[50:53], v[228:231], v[192:195], v[50:53]
	v_mfma_f32_16x16x32_bf16 v[62:65], v[208:211], v[200:203], v[62:65]
	v_mfma_f32_16x16x32_bf16 v[58:61], v[228:231], v[200:203], v[58:61]
	s_add_i32 s56, 0, 0x18000
	s_barrier
	s_add_u32 s22, s22, 0x10000
	s_addc_u32 s23, s23, 0
	s_mov_b32 m0, s44
	v_lshl_add_u64 v[204:205], s[22:23], 0, v[136:137]
	ds_read_b128 v[158:161], v140 offset:32768
	ds_read_b128 v[162:165], v140 offset:33792
	ds_read_b128 v[168:171], v140 offset:34816
	ds_read_b128 v[172:175], v140 offset:35840
	ds_read_b128 v[176:179], v140 offset:36864
	ds_read_b128 v[192:195], v140 offset:37888
	ds_read_b128 v[196:199], v140 offset:38912
	ds_read_b128 v[200:203], v140 offset:39936
	global_load_lds_dwordx4 v[204:205], off
	v_lshl_add_u64 v[204:205], s[22:23], 0, v[132:133]
	s_mov_b32 m0, s45
	s_nop 0
	global_load_lds_dwordx4 v[204:205], off
	s_waitcnt lgkmcnt(8)
	s_barrier
	s_waitcnt lgkmcnt(0)
	v_mfma_f32_16x16x32_bf16 v[86:89], v[142:145], v[158:161], v[86:89]
	v_mfma_f32_16x16x32_bf16 v[94:97], v[150:153], v[158:161], v[94:97]
	v_mfma_f32_16x16x32_bf16 v[98:101], v[142:145], v[168:171], v[98:101]
	v_mfma_f32_16x16x32_bf16 v[102:105], v[150:153], v[168:171], v[102:105]
	v_mfma_f32_16x16x32_bf16 v[114:117], v[142:145], v[176:179], v[114:117]
	v_mfma_f32_16x16x32_bf16 v[122:125], v[150:153], v[176:179], v[122:125]
	v_mfma_f32_16x16x32_bf16 v[126:129], v[142:145], v[196:199], v[126:129]
	v_mfma_f32_16x16x32_bf16 v[118:121], v[150:153], v[196:199], v[118:121]
	v_mfma_f32_16x16x32_bf16 v[86:89], v[146:149], v[162:165], v[86:89]
	v_mfma_f32_16x16x32_bf16 v[94:97], v[154:157], v[162:165], v[94:97]
	v_mfma_f32_16x16x32_bf16 v[98:101], v[146:149], v[172:175], v[98:101]
	v_mfma_f32_16x16x32_bf16 v[102:105], v[154:157], v[172:175], v[102:105]
	v_mfma_f32_16x16x32_bf16 v[114:117], v[146:149], v[192:195], v[114:117]
	v_mfma_f32_16x16x32_bf16 v[122:125], v[154:157], v[192:195], v[122:125]
	v_mfma_f32_16x16x32_bf16 v[126:129], v[146:149], v[200:203], v[126:129]
	v_mfma_f32_16x16x32_bf16 v[118:121], v[154:157], v[200:203], v[118:121]
	s_barrier
	s_add_i32 s57, 0, 0x1c000
	s_add_i32 s22, s56, s81
	v_add_u32_e32 v141, s57, v139
	v_lshl_add_u64 v[212:213], v[212:213], 0, s[78:79]
	s_mov_b32 m0, s22
	ds_read_b128 v[204:207], v141
	ds_read_b128 v[208:211], v141 offset:1024
	ds_read_b128 v[224:227], v141 offset:2048
	ds_read_b128 v[228:231], v141 offset:3072
	global_load_lds_dwordx4 v[212:213], off
	v_lshl_add_u64 v[212:213], v[222:223], 0, s[78:79]
	s_add_i32 m0, s22, 0x2000
	s_nop 0
	global_load_lds_dwordx4 v[212:213], off
	s_barrier
	s_waitcnt lgkmcnt(0)
	v_mfma_f32_16x16x32_bf16 v[2:5], v[204:207], v[158:161], v[2:5]
	v_mfma_f32_16x16x32_bf16 v[6:9], v[224:227], v[158:161], v[6:9]
	v_mfma_f32_16x16x32_bf16 v[10:13], v[204:207], v[168:171], v[10:13]
	v_mfma_f32_16x16x32_bf16 v[14:17], v[224:227], v[168:171], v[14:17]
	v_mfma_f32_16x16x32_bf16 v[22:25], v[204:207], v[176:179], v[22:25]
	v_mfma_f32_16x16x32_bf16 v[18:21], v[224:227], v[176:179], v[18:21]
	v_mfma_f32_16x16x32_bf16 v[30:33], v[204:207], v[196:199], v[30:33]
	v_mfma_f32_16x16x32_bf16 v[26:29], v[224:227], v[196:199], v[26:29]
	v_mfma_f32_16x16x32_bf16 v[2:5], v[208:211], v[162:165], v[2:5]
	v_mfma_f32_16x16x32_bf16 v[6:9], v[228:231], v[162:165], v[6:9]
	v_mfma_f32_16x16x32_bf16 v[10:13], v[208:211], v[172:175], v[10:13]
	v_mfma_f32_16x16x32_bf16 v[14:17], v[228:231], v[172:175], v[14:17]
	v_mfma_f32_16x16x32_bf16 v[22:25], v[208:211], v[192:195], v[22:25]
	v_mfma_f32_16x16x32_bf16 v[18:21], v[228:231], v[192:195], v[18:21]
	v_mfma_f32_16x16x32_bf16 v[30:33], v[208:211], v[200:203], v[30:33]
	v_mfma_f32_16x16x32_bf16 v[26:29], v[228:231], v[200:203], v[26:29]
	s_mov_b32 m0, s47
	v_lshl_add_u64 v[212:213], v[232:233], 0, s[78:79]
	s_barrier
	ds_read_b128 v[158:161], v140 offset:49152
	ds_read_b128 v[162:165], v140 offset:50176
	ds_read_b128 v[168:171], v140 offset:51200
	ds_read_b128 v[172:175], v140 offset:52224
	ds_read_b128 v[176:179], v140 offset:53248
	ds_read_b128 v[192:195], v140 offset:54272
	ds_read_b128 v[196:199], v140 offset:55296
	ds_read_b128 v[200:203], v140 offset:56320
	global_load_lds_dwordx4 v[212:213], off
	v_lshl_add_u64 v[212:213], v[234:235], 0, s[78:79]
	s_mov_b32 m0, s48
	s_nop 0
	global_load_lds_dwordx4 v[212:213], off
	s_waitcnt vmcnt(10)
	s_barrier
	s_waitcnt lgkmcnt(0)
	v_mfma_f32_16x16x32_bf16 v[110:113], v[142:145], v[158:161], v[110:113]
	v_mfma_f32_16x16x32_bf16 v[106:109], v[150:153], v[158:161], v[106:109]
	v_mfma_f32_16x16x32_bf16 v[90:93], v[142:145], v[168:171], v[90:93]
	v_mfma_f32_16x16x32_bf16 v[82:85], v[150:153], v[168:171], v[82:85]
	v_mfma_f32_16x16x32_bf16 v[78:81], v[142:145], v[176:179], v[78:81]
	v_mfma_f32_16x16x32_bf16 v[74:77], v[150:153], v[176:179], v[74:77]
	v_mfma_f32_16x16x32_bf16 v[70:73], v[142:145], v[196:199], v[70:73]
	v_mfma_f32_16x16x32_bf16 v[66:69], v[150:153], v[196:199], v[66:69]
	v_mfma_f32_16x16x32_bf16 v[110:113], v[146:149], v[162:165], v[110:113]
	v_mfma_f32_16x16x32_bf16 v[106:109], v[154:157], v[162:165], v[106:109]
	v_mfma_f32_16x16x32_bf16 v[90:93], v[146:149], v[172:175], v[90:93]
	v_mfma_f32_16x16x32_bf16 v[82:85], v[154:157], v[172:175], v[82:85]
	v_mfma_f32_16x16x32_bf16 v[78:81], v[146:149], v[192:195], v[78:81]
	v_mfma_f32_16x16x32_bf16 v[74:77], v[154:157], v[192:195], v[74:77]
	v_mfma_f32_16x16x32_bf16 v[70:73], v[146:149], v[200:203], v[70:73]
	v_mfma_f32_16x16x32_bf16 v[66:69], v[154:157], v[200:203], v[66:69]
	s_barrier
	s_add_u32 s22, s90, 0x200080
	s_addc_u32 s23, s91, 0
	s_add_i32 s56, s57, s81
	v_lshl_add_u64 v[142:143], s[22:23], 0, v[134:135]
	s_mov_b32 m0, s56
	s_nop 0
	global_load_lds_dwordx4 v[142:143], off
	v_lshl_add_u64 v[142:143], s[22:23], 0, v[130:131]
	s_add_i32 m0, s56, 0x2000
	s_nop 0
	global_load_lds_dwordx4 v[142:143], off
	v_add_u32_e32 v141, 0x10000, v139
	ds_read_b128 v[142:145], v141
	ds_read_b128 v[146:149], v141 offset:1024
	ds_read_b128 v[150:153], v141 offset:2048
	ds_read_b128 v[154:157], v141 offset:3072
	s_waitcnt vmcnt(6)
	s_barrier
	v_mfma_f32_16x16x32_bf16 v[38:41], v[204:207], v[158:161], v[38:41]
	v_mfma_f32_16x16x32_bf16 v[34:37], v[224:227], v[158:161], v[34:37]
	v_mfma_f32_16x16x32_bf16 v[46:49], v[204:207], v[168:171], v[46:49]
	v_mfma_f32_16x16x32_bf16 v[42:45], v[224:227], v[168:171], v[42:45]
	v_mfma_f32_16x16x32_bf16 v[54:57], v[204:207], v[176:179], v[54:57]
	v_mfma_f32_16x16x32_bf16 v[50:53], v[224:227], v[176:179], v[50:53]
	v_mfma_f32_16x16x32_bf16 v[62:65], v[204:207], v[196:199], v[62:65]
	v_mfma_f32_16x16x32_bf16 v[58:61], v[224:227], v[196:199], v[58:61]
	v_mfma_f32_16x16x32_bf16 v[38:41], v[208:211], v[162:165], v[38:41]
	v_mfma_f32_16x16x32_bf16 v[34:37], v[228:231], v[162:165], v[34:37]
	v_mfma_f32_16x16x32_bf16 v[46:49], v[208:211], v[172:175], v[46:49]
	v_mfma_f32_16x16x32_bf16 v[42:45], v[228:231], v[172:175], v[42:45]
	v_mfma_f32_16x16x32_bf16 v[54:57], v[208:211], v[192:195], v[54:57]
	v_mfma_f32_16x16x32_bf16 v[50:53], v[228:231], v[192:195], v[50:53]
	v_mfma_f32_16x16x32_bf16 v[62:65], v[208:211], v[200:203], v[62:65]
	v_mfma_f32_16x16x32_bf16 v[58:61], v[228:231], v[200:203], v[58:61]
	s_add_i32 s54, s54, 2
	s_add_i32 s55, s55, 0x10000
	s_cmpk_gt_u32 s54, 0x7d
	s_mov_b64 s[90:91], vcc
	s_barrier
	s_cbranch_scc0 .LBB0_814
	s_waitcnt lgkmcnt(0)
	s_andn2_b64 vcc, exec, s[38:39]
	s_cbranch_vccnz .LBB0_806
	v_mov_b32_e32 v58, 0
	s_mov_b32 s80, s42
	s_mov_b32 s25, s82
	s_mov_b64 s[30:31], s[20:21]
	s_mov_b64 s[84:85], s[18:19]
	s_mov_b32 s49, s50
	v_mov_b32_e32 v59, v58
	v_mov_b32_e32 v60, v58
	v_mov_b32_e32 v61, v58
	v_mov_b32_e32 v62, v58
	v_mov_b32_e32 v63, v58
	v_mov_b32_e32 v64, v58
	v_mov_b32_e32 v65, v58
	v_mov_b32_e32 v50, v58
	v_mov_b32_e32 v51, v58
	v_mov_b32_e32 v52, v58
	v_mov_b32_e32 v53, v58
	v_mov_b32_e32 v54, v58
	v_mov_b32_e32 v55, v58
	v_mov_b32_e32 v56, v58
	v_mov_b32_e32 v57, v58
	v_mov_b32_e32 v42, v58
	v_mov_b32_e32 v43, v58
	v_mov_b32_e32 v44, v58
	v_mov_b32_e32 v45, v58
	v_mov_b32_e32 v46, v58
	v_mov_b32_e32 v47, v58
	v_mov_b32_e32 v48, v58
	v_mov_b32_e32 v49, v58
	v_mov_b32_e32 v34, v58
	v_mov_b32_e32 v35, v58
	v_mov_b32_e32 v36, v58
	v_mov_b32_e32 v37, v58
	v_mov_b32_e32 v38, v58
	v_mov_b32_e32 v39, v58
	v_mov_b32_e32 v40, v58
	v_mov_b32_e32 v41, v58
	v_mov_b32_e32 v66, v58
	v_mov_b32_e32 v67, v58
	v_mov_b32_e32 v68, v58
	v_mov_b32_e32 v69, v58
	v_mov_b32_e32 v70, v58
	v_mov_b32_e32 v71, v58
	v_mov_b32_e32 v72, v58
	v_mov_b32_e32 v73, v58
	v_mov_b32_e32 v74, v58
	v_mov_b32_e32 v75, v58
	v_mov_b32_e32 v76, v58
	v_mov_b32_e32 v77, v58
	v_mov_b32_e32 v78, v58
	v_mov_b32_e32 v79, v58
	v_mov_b32_e32 v80, v58
	v_mov_b32_e32 v81, v58
	v_mov_b32_e32 v82, v58
	v_mov_b32_e32 v83, v58
	v_mov_b32_e32 v84, v58
	v_mov_b32_e32 v85, v58
	v_mov_b32_e32 v90, v58
	v_mov_b32_e32 v91, v58
	v_mov_b32_e32 v92, v58
	v_mov_b32_e32 v93, v58
	v_mov_b32_e32 v106, v58
	v_mov_b32_e32 v107, v58
	v_mov_b32_e32 v108, v58
	v_mov_b32_e32 v109, v58
	v_mov_b32_e32 v110, v58
	v_mov_b32_e32 v111, v58
	v_mov_b32_e32 v112, v58
	v_mov_b32_e32 v113, v58
	v_mov_b32_e32 v26, v58
	v_mov_b32_e32 v27, v58
	v_mov_b32_e32 v28, v58
	v_mov_b32_e32 v29, v58
	v_mov_b32_e32 v30, v58
	v_mov_b32_e32 v31, v58
	v_mov_b32_e32 v32, v58
	v_mov_b32_e32 v33, v58
	v_mov_b32_e32 v18, v58
	v_mov_b32_e32 v19, v58
	v_mov_b32_e32 v20, v58
	v_mov_b32_e32 v21, v58
	v_mov_b32_e32 v22, v58
	v_mov_b32_e32 v23, v58
	v_mov_b32_e32 v24, v58
	v_mov_b32_e32 v25, v58
	v_mov_b32_e32 v14, v58
	v_mov_b32_e32 v15, v58
	v_mov_b32_e32 v16, v58
	v_mov_b32_e32 v17, v58
	v_mov_b32_e32 v10, v58
	v_mov_b32_e32 v11, v58
	v_mov_b32_e32 v12, v58
	v_mov_b32_e32 v13, v58
	v_mov_b32_e32 v6, v58
	v_mov_b32_e32 v7, v58
	v_mov_b32_e32 v8, v58
	v_mov_b32_e32 v9, v58
	v_mov_b32_e32 v2, v58
	v_mov_b32_e32 v3, v58
	v_mov_b32_e32 v4, v58
	v_mov_b32_e32 v5, v58
	v_mov_b32_e32 v118, v58
	v_mov_b32_e32 v119, v58
	v_mov_b32_e32 v120, v58
	v_mov_b32_e32 v121, v58
	v_mov_b32_e32 v126, v58
	v_mov_b32_e32 v127, v58
	v_mov_b32_e32 v128, v58
	v_mov_b32_e32 v129, v58
	v_mov_b32_e32 v122, v58
	v_mov_b32_e32 v123, v58
	v_mov_b32_e32 v124, v58
	v_mov_b32_e32 v125, v58
	v_mov_b32_e32 v114, v58
	v_mov_b32_e32 v115, v58
	v_mov_b32_e32 v116, v58
	v_mov_b32_e32 v117, v58
	v_mov_b32_e32 v102, v58
	v_mov_b32_e32 v103, v58
	v_mov_b32_e32 v104, v58
	v_mov_b32_e32 v105, v58
	v_mov_b32_e32 v98, v58
	v_mov_b32_e32 v99, v58
	v_mov_b32_e32 v100, v58
	v_mov_b32_e32 v101, v58
	v_mov_b32_e32 v94, v58
	v_mov_b32_e32 v95, v58
	v_mov_b32_e32 v96, v58
	v_mov_b32_e32 v97, v58
	v_mov_b32_e32 v86, v58
	v_mov_b32_e32 v87, v58
	v_mov_b32_e32 v88, v58
	v_mov_b32_e32 v89, v58
	s_branch .LBB0_806
